# A/B: s_setprio 1 moved in front of the barrier that opens each GEMM MFMA segment (segment now starts with an MFMA); on top of v40
# baseline (speedup 1.0000x reference)
; #define PG8_STAGE(bufoff, gbase, voff) do { _Pragma("unroll") for (int _i = 0; _i < 2; ++_i) \
;         __builtin_amdgcn_global_load_lds((const unsigned*)((const char*)(gbase) + (voff)[_i]), (PG8_LAS unsigned*)(lds + (bufoff) + ldsw + _i * 8192), 16, 0, 0); } while (0)
; #define PG8_LDA(dst, b, h) do { _Pragma("unroll") for (int m = 0; m < 4; ++m) _Pragma("unroll") for (int k = 0; k < 2; ++k) dst[m][k] = *(const PG8_LAS bf16x8*)(lds + PG8_SA(b, h) + aoff + m * 2048 + k * 1024); } while (0)
; #define PG8_LDB(dst, b, h) do { _Pragma("unroll") for (int n = 0; n < 2; ++n) _Pragma("unroll") for (int k = 0; k < 2; ++k) dst[n][k] = *(const PG8_LAS bf16x8*)(lds + PG8_SB(b, h) + boff + n * 2048 + k * 1024); } while (0)
; #define PG8_MMA(ai, bj, At, Bt) do { __builtin_amdgcn_s_setprio(1); _Pragma("unroll") for (int m = 0; m < 4; ++m) _Pragma("unroll") for (int n = 0; n < 2; ++n) _Pragma("unroll") for (int k = 0; k < 2; ++k) \
;         acc[ai][bj][m][n] = __builtin_amdgcn_mfma_f32_16x16x32_bf16(Bt[n][k], At[m][k], acc[ai][bj][m][n], 0, 0, 0); __builtin_amdgcn_s_setprio(0); } while (0)
; #define PG8_WAIT_V(n) asm volatile("s_waitcnt vmcnt(" #n ")" ::: "memory")
; #define PG8_WAIT_L(n) asm volatile("s_waitcnt lgkmcnt(" #n ")" ::: "memory")
; #define PG8_BAR __builtin_amdgcn_s_barrier()
; #define PG8_SCHED __builtin_amdgcn_sched_barrier(0)
; template <class Epi, class Sched, bool ALIGN_EPI = false, bool SP2 = false>
; __device__ __forceinline__ void gemm_phase(PG8_LAS unsigned char* lds, const Gemm g, const Sched& S, const Epi& E) {
;     ...
;             PG8_LDB(B0, 0, 0); PG8_LDB(B1, 0, 1); PG8_SCHED; PG8_LDA(At, 0, 0); PG8_STAGE(PG8_SA(1, 1), a1 + hstepA, voffA);
;             PG8_WAIT_V(8); PG8_WAIT_L(0); PG8_BAR; PG8_MMA(0, 0, At, B0); PG8_MMA(0, 1, At, B1); PG8_BAR; PG8_SCHED;
;             PG8_LDA(At, 0, 1); PG8_STAGE(PG8_SB(0, 0), b2, voffB); PG8_STAGE(PG8_SB(0, 1), b2 + hstepB, voffB); PG8_STAGE(PG8_SA(0, 0), a2, voffA);
.LBB0_254:
	s_add_u32 s28, s26, 0xfffc0080
	s_addc_u32 s29, s27, -1
	s_add_i32 s53, 0, 0x10000
	s_cmp_eq_u32 s52, 12
	s_cselect_b32 s31, s7, s29
	s_cselect_b32 s30, s9, s28
	v_add_u32_e32 v150, s53, v153
	s_cselect_b32 s29, s19, s51
	s_cselect_b32 s28, s21, s50
	s_add_i32 s56, 0, 0x14000
	ds_read_b128 v[142:145], v150
	ds_read_b128 v[146:149], v150 offset:1024
	ds_read_b128 v[158:161], v150 offset:2048
	ds_read_b128 v[162:165], v150 offset:3072
	v_add_u32_e32 v150, s56, v153
	ds_read_b128 v[166:169], v150
	ds_read_b128 v[170:173], v150 offset:1024
	ds_read_b128 v[174:177], v150 offset:2048
	ds_read_b128 v[178:181], v150 offset:3072
	s_add_i32 m0, s40, 0xc000
	ds_read_b128 v[182:185], v156
	ds_read_b128 v[202:205], v156 offset:1024
	ds_read_b128 v[206:209], v156 offset:2048
	ds_read_b128 v[210:213], v156 offset:3072
	ds_read_b128 v[232:235], v156 offset:4096
	ds_read_b128 v[236:239], v156 offset:5120
	ds_read_b128 v[240:243], v156 offset:6144
	ds_read_b128 v[244:247], v156 offset:7168
	global_load_lds_dwordx4 v138, s[26:27]
	s_add_i32 m0, s40, 0xe000
	s_nop 0
	global_load_lds_dwordx4 v140, s[26:27]
	s_waitcnt vmcnt(8)
	s_waitcnt lgkmcnt(0)
	s_setprio 1
	s_barrier
	v_mfma_f32_16x16x32_bf16 v[126:129], v[142:145], v[182:185], v[126:129]
	v_mfma_f32_16x16x32_bf16 v[122:125], v[158:161], v[182:185], v[122:125]
	v_mfma_f32_16x16x32_bf16 v[110:113], v[142:145], v[206:209], v[110:113]
	v_mfma_f32_16x16x32_bf16 v[106:109], v[158:161], v[206:209], v[106:109]
	v_mfma_f32_16x16x32_bf16 v[94:97], v[142:145], v[232:235], v[94:97]
	v_mfma_f32_16x16x32_bf16 v[90:93], v[158:161], v[232:235], v[90:93]
	v_mfma_f32_16x16x32_bf16 v[78:81], v[142:145], v[240:243], v[78:81]
	v_mfma_f32_16x16x32_bf16 v[74:77], v[158:161], v[240:243], v[74:77]
	v_mfma_f32_16x16x32_bf16 v[126:129], v[146:149], v[202:205], v[126:129]
	v_mfma_f32_16x16x32_bf16 v[122:125], v[162:165], v[202:205], v[122:125]
	v_mfma_f32_16x16x32_bf16 v[110:113], v[146:149], v[210:213], v[110:113]
	v_mfma_f32_16x16x32_bf16 v[106:109], v[162:165], v[210:213], v[106:109]
	v_mfma_f32_16x16x32_bf16 v[94:97], v[146:149], v[236:239], v[94:97]
	v_mfma_f32_16x16x32_bf16 v[90:93], v[162:165], v[236:239], v[90:93]
	v_mfma_f32_16x16x32_bf16 v[78:81], v[146:149], v[244:247], v[78:81]
	v_mfma_f32_16x16x32_bf16 v[74:77], v[162:165], v[244:247], v[74:77]
	s_setprio 0
	s_setprio 1
	v_mfma_f32_16x16x32_bf16 v[118:121], v[166:169], v[182:185], v[118:121]
	v_mfma_f32_16x16x32_bf16 v[114:117], v[174:177], v[182:185], v[114:117]
	v_mfma_f32_16x16x32_bf16 v[102:105], v[166:169], v[206:209], v[102:105]
	v_mfma_f32_16x16x32_bf16 v[98:101], v[174:177], v[206:209], v[98:101]
	v_mfma_f32_16x16x32_bf16 v[86:89], v[166:169], v[232:235], v[86:89]
	v_mfma_f32_16x16x32_bf16 v[82:85], v[174:177], v[232:235], v[82:85]
	v_mfma_f32_16x16x32_bf16 v[70:73], v[166:169], v[240:243], v[70:73]
	v_mfma_f32_16x16x32_bf16 v[66:69], v[174:177], v[240:243], v[66:69]
	v_mfma_f32_16x16x32_bf16 v[118:121], v[170:173], v[202:205], v[118:121]
	v_mfma_f32_16x16x32_bf16 v[114:117], v[178:181], v[202:205], v[114:117]
	v_mfma_f32_16x16x32_bf16 v[102:105], v[170:173], v[210:213], v[102:105]
	v_mfma_f32_16x16x32_bf16 v[98:101], v[178:181], v[210:213], v[98:101]
	v_mfma_f32_16x16x32_bf16 v[86:89], v[170:173], v[236:239], v[86:89]
	v_mfma_f32_16x16x32_bf16 v[82:85], v[178:181], v[236:239], v[82:85]
	v_mfma_f32_16x16x32_bf16 v[70:73], v[170:173], v[244:247], v[70:73]
	v_mfma_f32_16x16x32_bf16 v[66:69], v[178:181], v[244:247], v[66:69]
	s_setprio 0
	s_barrier
	s_add_i32 s53, s53, s39
	s_mov_b32 m0, s53
	ds_read_b128 v[182:185], v156 offset:16384
	ds_read_b128 v[202:205], v156 offset:17408
	ds_read_b128 v[206:209], v156 offset:18432
	ds_read_b128 v[210:213], v156 offset:19456
	ds_read_b128 v[232:235], v156 offset:20480
	ds_read_b128 v[236:239], v156 offset:21504
	ds_read_b128 v[240:243], v156 offset:22528
	ds_read_b128 v[244:247], v156 offset:23552
	s_add_u32 s60, s28, 0x80
	s_addc_u32 s61, s29, 0
	s_add_u32 s62, s30, 0x80
	s_addc_u32 s63, s31, 0
	global_load_lds_dwordx4 v132, s[28:29]
	s_add_i32 m0, s53, 0x2000
	s_add_u32 s54, s28, 0x40000
	s_addc_u32 s55, s29, 0
	s_add_i32 s53, s56, s39
	global_load_lds_dwordx4 v136, s[28:29]
	s_mov_b32 m0, s53
	s_nop 0
	global_load_lds_dwordx4 v132, s[54:55]
	s_add_i32 m0, s53, 0x2000
	s_nop 0
	global_load_lds_dwordx4 v136, s[54:55]
	s_mov_b32 m0, s40
	s_nop 0
	global_load_lds_dwordx4 v130, s[30:31]
	s_mov_b32 m0, s41
	s_nop 0
	global_load_lds_dwordx4 v134, s[30:31]
	s_waitcnt vmcnt(8)
	s_waitcnt lgkmcnt(0)
	s_setprio 1
	s_barrier
; #define PG8_STAGE(bufoff, gbase, voff) do { _Pragma("unroll") for (int _i = 0; _i < 2; ++_i) \
;         __builtin_amdgcn_global_load_lds((const unsigned*)((const char*)(gbase) + (voff)[_i]), (PG8_LAS unsigned*)(lds + (bufoff) + ldsw + _i * 8192), 16, 0, 0); } while (0)
; #define PG8_LDA(dst, b, h) do { _Pragma("unroll") for (int m = 0; m < 4; ++m) _Pragma("unroll") for (int k = 0; k < 2; ++k) dst[m][k] = *(const PG8_LAS bf16x8*)(lds + PG8_SA(b, h) + aoff + m * 2048 + k * 1024); } while (0)
; #define PG8_LDB(dst, b, h) do { _Pragma("unroll") for (int n = 0; n < 2; ++n) _Pragma("unroll") for (int k = 0; k < 2; ++k) dst[n][k] = *(const PG8_LAS bf16x8*)(lds + PG8_SB(b, h) + boff + n * 2048 + k * 1024); } while (0)
; #define PG8_MMA(ai, bj, At, Bt) do { __builtin_amdgcn_s_setprio(1); _Pragma("unroll") for (int m = 0; m < 4; ++m) _Pragma("unroll") for (int n = 0; n < 2; ++n) _Pragma("unroll") for (int k = 0; k < 2; ++k) \
;         acc[ai][bj][m][n] = __builtin_amdgcn_mfma_f32_16x16x32_bf16(Bt[n][k], At[m][k], acc[ai][bj][m][n], 0, 0, 0); __builtin_amdgcn_s_setprio(0); } while (0)
; #define PG8_WAIT_V(n) asm volatile("s_waitcnt vmcnt(" #n ")" ::: "memory")
; #define PG8_WAIT_L(n) asm volatile("s_waitcnt lgkmcnt(" #n ")" ::: "memory")
; #define PG8_BAR __builtin_amdgcn_s_barrier()
; #define PG8_SCHED __builtin_amdgcn_sched_barrier(0)
; template <class Epi, class Sched, bool ALIGN_EPI = false, bool SP2 = false>
; __device__ __forceinline__ void gemm_phase(PG8_LAS unsigned char* lds, const Gemm g, const Sched& S, const Epi& E) {
;     ...
;             PG8_WAIT_V(8); PG8_WAIT_L(0); PG8_BAR; PG8_MMA(1, 0, At, B0); PG8_MMA(1, 1, At, B1); PG8_BAR; PG8_SCHED;
;             PG8_LDB(B0, 1, 0); PG8_LDB(B1, 1, 1); PG8_SCHED; PG8_LDA(At, 1, 0); PG8_STAGE(PG8_SA(0, 1), a2 + hstepA, voffA);
;             PG8_WAIT_V(8); PG8_WAIT_L(0); PG8_BAR; PG8_MMA(0, 0, At, B0); PG8_MMA(0, 1, At, B1); PG8_BAR; PG8_SCHED;
	v_mfma_f32_16x16x32_bf16 v[62:65], v[142:145], v[182:185], v[62:65]
	v_mfma_f32_16x16x32_bf16 v[58:61], v[158:161], v[182:185], v[58:61]
	v_mfma_f32_16x16x32_bf16 v[46:49], v[142:145], v[206:209], v[46:49]
	v_mfma_f32_16x16x32_bf16 v[42:45], v[158:161], v[206:209], v[42:45]
	v_mfma_f32_16x16x32_bf16 v[30:33], v[142:145], v[232:235], v[30:33]
	v_mfma_f32_16x16x32_bf16 v[26:29], v[158:161], v[232:235], v[26:29]
	v_mfma_f32_16x16x32_bf16 v[14:17], v[142:145], v[240:243], v[14:17]
	v_mfma_f32_16x16x32_bf16 v[10:13], v[158:161], v[240:243], v[10:13]
	v_mfma_f32_16x16x32_bf16 v[62:65], v[146:149], v[202:205], v[62:65]
	v_mfma_f32_16x16x32_bf16 v[58:61], v[162:165], v[202:205], v[58:61]
	v_mfma_f32_16x16x32_bf16 v[46:49], v[146:149], v[210:213], v[46:49]
	v_mfma_f32_16x16x32_bf16 v[42:45], v[162:165], v[210:213], v[42:45]
	v_mfma_f32_16x16x32_bf16 v[30:33], v[146:149], v[236:239], v[30:33]
	v_mfma_f32_16x16x32_bf16 v[26:29], v[162:165], v[236:239], v[26:29]
	v_mfma_f32_16x16x32_bf16 v[14:17], v[146:149], v[244:247], v[14:17]
	v_mfma_f32_16x16x32_bf16 v[10:13], v[162:165], v[244:247], v[10:13]
	s_setprio 0
	s_setprio 1
	v_mfma_f32_16x16x32_bf16 v[54:57], v[166:169], v[182:185], v[54:57]
	v_mfma_f32_16x16x32_bf16 v[50:53], v[174:177], v[182:185], v[50:53]
	v_mfma_f32_16x16x32_bf16 v[38:41], v[166:169], v[206:209], v[38:41]
	v_mfma_f32_16x16x32_bf16 v[34:37], v[174:177], v[206:209], v[34:37]
	v_mfma_f32_16x16x32_bf16 v[22:25], v[166:169], v[232:235], v[22:25]
	v_mfma_f32_16x16x32_bf16 v[18:21], v[174:177], v[232:235], v[18:21]
	v_mfma_f32_16x16x32_bf16 v[6:9], v[166:169], v[240:243], v[6:9]
	v_mfma_f32_16x16x32_bf16 v[2:5], v[174:177], v[240:243], v[2:5]
	v_mfma_f32_16x16x32_bf16 v[54:57], v[170:173], v[202:205], v[54:57]
	v_mfma_f32_16x16x32_bf16 v[50:53], v[178:181], v[202:205], v[50:53]
	v_mfma_f32_16x16x32_bf16 v[38:41], v[170:173], v[210:213], v[38:41]
	v_mfma_f32_16x16x32_bf16 v[34:37], v[178:181], v[210:213], v[34:37]
	v_mfma_f32_16x16x32_bf16 v[22:25], v[170:173], v[236:239], v[22:25]
	v_mfma_f32_16x16x32_bf16 v[18:21], v[178:181], v[236:239], v[18:21]
	v_mfma_f32_16x16x32_bf16 v[6:9], v[170:173], v[244:247], v[6:9]
	v_mfma_f32_16x16x32_bf16 v[2:5], v[178:181], v[244:247], v[2:5]
	s_setprio 0
	s_barrier
	s_add_i32 s53, 0, 0x18000
	v_add_u32_e32 v157, s53, v153
	s_add_i32 s54, 0, 0x1c000
	ds_read_b128 v[142:145], v157
	ds_read_b128 v[146:149], v157 offset:1024
	ds_read_b128 v[158:161], v157 offset:2048
	ds_read_b128 v[162:165], v157 offset:3072
	v_add_u32_e32 v157, s54, v153
	ds_read_b128 v[166:169], v157
	ds_read_b128 v[170:173], v157 offset:1024
	ds_read_b128 v[174:177], v157 offset:2048
	ds_read_b128 v[178:181], v157 offset:3072
	s_add_u32 s30, s30, 0x40000
	s_addc_u32 s31, s31, 0
	s_mov_b32 m0, s42
	ds_read_b128 v[182:185], v156 offset:32768
	ds_read_b128 v[202:205], v156 offset:33792
	ds_read_b128 v[206:209], v156 offset:34816
	ds_read_b128 v[210:213], v156 offset:35840
	ds_read_b128 v[232:235], v156 offset:36864
	ds_read_b128 v[236:239], v156 offset:37888
	ds_read_b128 v[240:243], v156 offset:38912
	ds_read_b128 v[244:247], v156 offset:39936
	global_load_lds_dwordx4 v130, s[30:31]
	s_mov_b32 m0, s43
	s_nop 0
	global_load_lds_dwordx4 v134, s[30:31]
	s_waitcnt vmcnt(8)
	s_waitcnt lgkmcnt(0)
	s_setprio 1
	s_barrier
	v_mfma_f32_16x16x32_bf16 v[126:129], v[142:145], v[182:185], v[126:129]
	v_mfma_f32_16x16x32_bf16 v[122:125], v[158:161], v[182:185], v[122:125]
	v_mfma_f32_16x16x32_bf16 v[110:113], v[142:145], v[206:209], v[110:113]
	v_mfma_f32_16x16x32_bf16 v[106:109], v[158:161], v[206:209], v[106:109]
	v_mfma_f32_16x16x32_bf16 v[94:97], v[142:145], v[232:235], v[94:97]
	v_mfma_f32_16x16x32_bf16 v[90:93], v[158:161], v[232:235], v[90:93]
	v_mfma_f32_16x16x32_bf16 v[78:81], v[142:145], v[240:243], v[78:81]
	v_mfma_f32_16x16x32_bf16 v[74:77], v[158:161], v[240:243], v[74:77]
	v_mfma_f32_16x16x32_bf16 v[126:129], v[146:149], v[202:205], v[126:129]
	v_mfma_f32_16x16x32_bf16 v[122:125], v[162:165], v[202:205], v[122:125]
	v_mfma_f32_16x16x32_bf16 v[110:113], v[146:149], v[210:213], v[110:113]
	v_mfma_f32_16x16x32_bf16 v[106:109], v[162:165], v[210:213], v[106:109]
	v_mfma_f32_16x16x32_bf16 v[94:97], v[146:149], v[236:239], v[94:97]
	v_mfma_f32_16x16x32_bf16 v[90:93], v[162:165], v[236:239], v[90:93]
	v_mfma_f32_16x16x32_bf16 v[78:81], v[146:149], v[244:247], v[78:81]
	v_mfma_f32_16x16x32_bf16 v[74:77], v[162:165], v[244:247], v[74:77]
	s_setprio 0
	s_setprio 1
	v_mfma_f32_16x16x32_bf16 v[118:121], v[166:169], v[182:185], v[118:121]
	v_mfma_f32_16x16x32_bf16 v[114:117], v[174:177], v[182:185], v[114:117]
	v_mfma_f32_16x16x32_bf16 v[102:105], v[166:169], v[206:209], v[102:105]
	v_mfma_f32_16x16x32_bf16 v[98:101], v[174:177], v[206:209], v[98:101]
	v_mfma_f32_16x16x32_bf16 v[86:89], v[166:169], v[232:235], v[86:89]
	v_mfma_f32_16x16x32_bf16 v[82:85], v[174:177], v[232:235], v[82:85]
	v_mfma_f32_16x16x32_bf16 v[70:73], v[166:169], v[240:243], v[70:73]
	v_mfma_f32_16x16x32_bf16 v[66:69], v[174:177], v[240:243], v[66:69]
	v_mfma_f32_16x16x32_bf16 v[118:121], v[170:173], v[202:205], v[118:121]
	v_mfma_f32_16x16x32_bf16 v[114:117], v[178:181], v[202:205], v[114:117]
	v_mfma_f32_16x16x32_bf16 v[102:105], v[170:173], v[210:213], v[102:105]
	v_mfma_f32_16x16x32_bf16 v[98:101], v[178:181], v[210:213], v[98:101]
	v_mfma_f32_16x16x32_bf16 v[86:89], v[170:173], v[236:239], v[86:89]
	v_mfma_f32_16x16x32_bf16 v[82:85], v[178:181], v[236:239], v[82:85]
	v_mfma_f32_16x16x32_bf16 v[70:73], v[170:173], v[244:247], v[70:73]
	v_mfma_f32_16x16x32_bf16 v[66:69], v[178:181], v[244:247], v[66:69]
	s_setprio 0
	s_barrier
; #define PG8_STAGE(bufoff, gbase, voff) do { _Pragma("unroll") for (int _i = 0; _i < 2; ++_i) \
;         __builtin_amdgcn_global_load_lds((const unsigned*)((const char*)(gbase) + (voff)[_i]), (PG8_LAS unsigned*)(lds + (bufoff) + ldsw + _i * 8192), 16, 0, 0); } while (0)
; #define PG8_LDA(dst, b, h) do { _Pragma("unroll") for (int m = 0; m < 4; ++m) _Pragma("unroll") for (int k = 0; k < 2; ++k) dst[m][k] = *(const PG8_LAS bf16x8*)(lds + PG8_SA(b, h) + aoff + m * 2048 + k * 1024); } while (0)
; #define PG8_MMA(ai, bj, At, Bt) do { __builtin_amdgcn_s_setprio(1); _Pragma("unroll") for (int m = 0; m < 4; ++m) _Pragma("unroll") for (int n = 0; n < 2; ++n) _Pragma("unroll") for (int k = 0; k < 2; ++k) \
;         acc[ai][bj][m][n] = __builtin_amdgcn_mfma_f32_16x16x32_bf16(Bt[n][k], At[m][k], acc[ai][bj][m][n], 0, 0, 0); __builtin_amdgcn_s_setprio(0); } while (0)
; #define PG8_WAIT_V(n) asm volatile("s_waitcnt vmcnt(" #n ")" ::: "memory")
; #define PG8_WAIT_L(n) asm volatile("s_waitcnt lgkmcnt(" #n ")" ::: "memory")
; #define PG8_BAR __builtin_amdgcn_s_barrier()
; #define PG8_SCHED __builtin_amdgcn_sched_barrier(0)
; template <class Epi, class Sched, bool ALIGN_EPI = false, bool SP2 = false>
; __device__ __forceinline__ void gemm_phase(PG8_LAS unsigned char* lds, const Gemm g, const Sched& S, const Epi& E) {
;     ...
;         for (int t = 0; t < nt; t += 2) {
;             const bool last = (t == nt - 2);
;     ...
;             PG8_LDA(At, 1, 1); PG8_STAGE(PG8_SB(1, 0), b3, voffB); PG8_STAGE(PG8_SB(1, 1), b3 + hstepB, voffB); PG8_STAGE(PG8_SA(1, 0), a3, voffA);
;             PG8_WAIT_V(8); PG8_WAIT_L(0); PG8_BAR; PG8_MMA(1, 0, At, B0); PG8_MMA(1, 1, At, B1); PG8_BAR; PG8_SCHED;
	s_add_i32 s30, s53, s39
	s_mov_b32 m0, s30
	ds_read_b128 v[182:185], v156 offset:49152
	ds_read_b128 v[202:205], v156 offset:50176
	ds_read_b128 v[206:209], v156 offset:51200
	ds_read_b128 v[210:213], v156 offset:52224
	ds_read_b128 v[232:235], v156 offset:53248
	ds_read_b128 v[236:239], v156 offset:54272
	ds_read_b128 v[240:243], v156 offset:55296
	ds_read_b128 v[244:247], v156 offset:56320
	global_load_lds_dwordx4 v132, s[60:61]
	s_add_i32 m0, s30, 0x2000
	s_add_u32 s28, s28, 0x40080
	s_addc_u32 s29, s29, 0
	s_add_i32 s30, s54, s39
	global_load_lds_dwordx4 v136, s[60:61]
	s_mov_b32 m0, s30
	s_nop 0
	global_load_lds_dwordx4 v132, s[28:29]
	s_add_i32 m0, s30, 0x2000
	s_nop 0
	global_load_lds_dwordx4 v136, s[28:29]
	s_mov_b32 m0, s45
	s_nop 0
	global_load_lds_dwordx4 v130, s[62:63]
	s_mov_b32 m0, s46
	s_nop 0
	global_load_lds_dwordx4 v134, s[62:63]
	s_waitcnt vmcnt(8)
	s_waitcnt lgkmcnt(0)
	s_setprio 1
	s_barrier
	v_mfma_f32_16x16x32_bf16 v[62:65], v[142:145], v[182:185], v[62:65]
	v_mfma_f32_16x16x32_bf16 v[58:61], v[158:161], v[182:185], v[58:61]
	v_mfma_f32_16x16x32_bf16 v[46:49], v[142:145], v[206:209], v[46:49]
	v_mfma_f32_16x16x32_bf16 v[42:45], v[158:161], v[206:209], v[42:45]
	v_mfma_f32_16x16x32_bf16 v[30:33], v[142:145], v[232:235], v[30:33]
	v_mfma_f32_16x16x32_bf16 v[26:29], v[158:161], v[232:235], v[26:29]
	v_mfma_f32_16x16x32_bf16 v[14:17], v[142:145], v[240:243], v[14:17]
	v_mfma_f32_16x16x32_bf16 v[10:13], v[158:161], v[240:243], v[10:13]
	v_mfma_f32_16x16x32_bf16 v[62:65], v[146:149], v[202:205], v[62:65]
	v_mfma_f32_16x16x32_bf16 v[58:61], v[162:165], v[202:205], v[58:61]
	v_mfma_f32_16x16x32_bf16 v[46:49], v[146:149], v[210:213], v[46:49]
	v_mfma_f32_16x16x32_bf16 v[42:45], v[162:165], v[210:213], v[42:45]
	v_mfma_f32_16x16x32_bf16 v[30:33], v[146:149], v[236:239], v[30:33]
	v_mfma_f32_16x16x32_bf16 v[26:29], v[162:165], v[236:239], v[26:29]
	v_mfma_f32_16x16x32_bf16 v[14:17], v[146:149], v[244:247], v[14:17]
	v_mfma_f32_16x16x32_bf16 v[10:13], v[162:165], v[244:247], v[10:13]
	s_setprio 0
	s_setprio 1
	v_mfma_f32_16x16x32_bf16 v[54:57], v[166:169], v[182:185], v[54:57]
	v_mfma_f32_16x16x32_bf16 v[50:53], v[174:177], v[182:185], v[50:53]
	v_mfma_f32_16x16x32_bf16 v[38:41], v[166:169], v[206:209], v[38:41]
	v_mfma_f32_16x16x32_bf16 v[34:37], v[174:177], v[206:209], v[34:37]
	v_mfma_f32_16x16x32_bf16 v[22:25], v[166:169], v[232:235], v[22:25]
	v_mfma_f32_16x16x32_bf16 v[18:21], v[174:177], v[232:235], v[18:21]
	v_mfma_f32_16x16x32_bf16 v[6:9], v[166:169], v[240:243], v[6:9]
	v_mfma_f32_16x16x32_bf16 v[2:5], v[174:177], v[240:243], v[2:5]
	v_mfma_f32_16x16x32_bf16 v[54:57], v[170:173], v[202:205], v[54:57]
	v_mfma_f32_16x16x32_bf16 v[50:53], v[178:181], v[202:205], v[50:53]
	v_mfma_f32_16x16x32_bf16 v[38:41], v[170:173], v[210:213], v[38:41]
	v_mfma_f32_16x16x32_bf16 v[34:37], v[178:181], v[210:213], v[34:37]
	v_mfma_f32_16x16x32_bf16 v[22:25], v[170:173], v[236:239], v[22:25]
	v_mfma_f32_16x16x32_bf16 v[18:21], v[178:181], v[236:239], v[18:21]
	v_mfma_f32_16x16x32_bf16 v[6:9], v[170:173], v[244:247], v[6:9]
	v_mfma_f32_16x16x32_bf16 v[2:5], v[178:181], v[244:247], v[2:5]
	s_setprio 0
	s_barrier
	s_add_i32 s52, s52, 2
	s_add_u32 s26, s26, 0x100
	s_addc_u32 s27, s27, 0
	s_add_u32 s50, s50, 0x100
	s_addc_u32 s51, s51, 0
	s_cmp_gt_u32 s52, 13
	s_cbranch_scc0 .LBB0_254
	s_and_b64 vcc, exec, s[16:17]
	s_cbranch_vccz .LBB0_257
	s_barrier

; #define PG8_STAGE(bufoff, gbase, voff) do { _Pragma("unroll") for (int _i = 0; _i < 2; ++_i) \
;         __builtin_amdgcn_global_load_lds((const unsigned*)((const char*)(gbase) + (voff)[_i]), (PG8_LAS unsigned*)(lds + (bufoff) + ldsw + _i * 8192), 16, 0, 0); } while (0)
; #define PG8_LDA(dst, b, h) do { _Pragma("unroll") for (int m = 0; m < 4; ++m) _Pragma("unroll") for (int k = 0; k < 2; ++k) dst[m][k] = *(const PG8_LAS bf16x8*)(lds + PG8_SA(b, h) + aoff + m * 2048 + k * 1024); } while (0)
; #define PG8_LDB(dst, b, h) do { _Pragma("unroll") for (int n = 0; n < 2; ++n) _Pragma("unroll") for (int k = 0; k < 2; ++k) dst[n][k] = *(const PG8_LAS bf16x8*)(lds + PG8_SB(b, h) + boff + n * 2048 + k * 1024); } while (0)
; #define PG8_MMA(ai, bj, At, Bt) do { __builtin_amdgcn_s_setprio(1); _Pragma("unroll") for (int m = 0; m < 4; ++m) _Pragma("unroll") for (int n = 0; n < 2; ++n) _Pragma("unroll") for (int k = 0; k < 2; ++k) \
;         acc[ai][bj][m][n] = __builtin_amdgcn_mfma_f32_16x16x32_bf16(Bt[n][k], At[m][k], acc[ai][bj][m][n], 0, 0, 0); __builtin_amdgcn_s_setprio(0); } while (0)
; #define PG8_WAIT_V(n) asm volatile("s_waitcnt vmcnt(" #n ")" ::: "memory")
; #define PG8_WAIT_L(n) asm volatile("s_waitcnt lgkmcnt(" #n ")" ::: "memory")
; #define PG8_BAR __builtin_amdgcn_s_barrier()
; #define PG8_SCHED __builtin_amdgcn_sched_barrier(0)
; template <class Epi, class Sched, bool ALIGN_EPI = false, bool SP2 = false>
; __device__ __forceinline__ void gemm_phase(PG8_LAS unsigned char* lds, const Gemm g, const Sched& S, const Epi& E) {
;     ...
;             PG8_LDB(B0, 0, 0); PG8_LDB(B1, 0, 1); PG8_SCHED; PG8_LDA(At, 0, 0); PG8_STAGE(PG8_SA(1, 1), a1 + hstepA, voffA);
;             PG8_WAIT_V(8); PG8_WAIT_L(0); PG8_BAR; PG8_MMA(0, 0, At, B0); PG8_MMA(0, 1, At, B1); PG8_BAR; PG8_SCHED;
;             PG8_LDA(At, 0, 1); PG8_STAGE(PG8_SB(0, 0), b2, voffB); PG8_STAGE(PG8_SB(0, 1), b2 + hstepB, voffB); PG8_STAGE(PG8_SA(0, 0), a2, voffA);
;             PG8_WAIT_V(8); PG8_WAIT_L(0); PG8_BAR; PG8_MMA(1, 0, At, B0); PG8_MMA(1, 1, At, B1); PG8_BAR; PG8_SCHED;
.LBB0_448:
	s_add_u32 s16, s38, s14
	s_addc_u32 s17, s39, s15
	s_add_u32 s16, s16, 0x4e00100
	s_addc_u32 s17, s17, 0
	s_add_u32 s43, s40, s14
	s_addc_u32 s44, s41, s15
	s_add_i32 s45, 0, 0x10000
	v_add_u32_e32 v96, s45, v82
	ds_read_b128 v[84:87], v96
	ds_read_b128 v[88:91], v96 offset:1024
	ds_read_b128 v[92:95], v96 offset:2048
	ds_read_b128 v[96:99], v96 offset:3072
	s_cmpk_eq_i32 s14, 0x700
	s_cselect_b32 s19, s13, s17
	s_cselect_b32 s18, s12, s16
	s_cselect_b32 s17, s5, s44
	s_cselect_b32 s16, s4, s43
	v_lshl_add_u64 v[132:133], v[76:77], 0, s[14:15]
	s_add_i32 m0, s25, 0xc000
	ds_read_b128 v[100:103], v83
	ds_read_b128 v[104:107], v83 offset:1024
	ds_read_b128 v[108:111], v83 offset:2048
	ds_read_b128 v[112:115], v83 offset:3072
	ds_read_b128 v[116:119], v83 offset:4096
	ds_read_b128 v[120:123], v83 offset:5120
	ds_read_b128 v[124:127], v83 offset:6144
	ds_read_b128 v[128:131], v83 offset:7168
	global_load_lds_dwordx4 v[132:133], off
	v_lshl_add_u64 v[132:133], v[78:79], 0, s[14:15]
	s_add_i32 m0, s25, 0xe000
	s_nop 0
	global_load_lds_dwordx4 v[132:133], off
	s_waitcnt vmcnt(8)
	s_waitcnt lgkmcnt(0)
	s_setprio 1
	s_barrier
	v_mfma_f32_16x16x32_bf16 v[62:65], v[84:87], v[100:103], v[62:65]
	v_mfma_f32_16x16x32_bf16 v[58:61], v[92:95], v[100:103], v[58:61]
	v_mfma_f32_16x16x32_bf16 v[54:57], v[84:87], v[108:111], v[54:57]
	v_mfma_f32_16x16x32_bf16 v[50:53], v[92:95], v[108:111], v[50:53]
	v_mfma_f32_16x16x32_bf16 v[46:49], v[84:87], v[116:119], v[46:49]
	v_mfma_f32_16x16x32_bf16 v[42:45], v[92:95], v[116:119], v[42:45]
	v_mfma_f32_16x16x32_bf16 v[38:41], v[84:87], v[124:127], v[38:41]
	v_mfma_f32_16x16x32_bf16 v[34:37], v[92:95], v[124:127], v[34:37]
	v_mfma_f32_16x16x32_bf16 v[62:65], v[88:91], v[104:107], v[62:65]
	v_mfma_f32_16x16x32_bf16 v[58:61], v[96:99], v[104:107], v[58:61]
	v_mfma_f32_16x16x32_bf16 v[54:57], v[88:91], v[112:115], v[54:57]
	v_mfma_f32_16x16x32_bf16 v[50:53], v[96:99], v[112:115], v[50:53]
	v_mfma_f32_16x16x32_bf16 v[46:49], v[88:91], v[120:123], v[46:49]
	v_mfma_f32_16x16x32_bf16 v[42:45], v[96:99], v[120:123], v[42:45]
	v_mfma_f32_16x16x32_bf16 v[38:41], v[88:91], v[128:131], v[38:41]
	v_mfma_f32_16x16x32_bf16 v[34:37], v[96:99], v[128:131], v[34:37]
	s_setprio 0
	s_setprio 1
	s_setprio 0
	s_barrier
	s_add_i32 s43, s45, s24
	v_lshl_add_u64 v[132:133], s[16:17], 0, v[72:73]
	s_mov_b32 m0, s43
	ds_read_b128 v[100:103], v83 offset:16384
	ds_read_b128 v[104:107], v83 offset:17408
	ds_read_b128 v[108:111], v83 offset:18432
	ds_read_b128 v[112:115], v83 offset:19456
	ds_read_b128 v[116:119], v83 offset:20480
	ds_read_b128 v[120:123], v83 offset:21504
	ds_read_b128 v[124:127], v83 offset:22528
	ds_read_b128 v[128:131], v83 offset:23552
	global_load_lds_dwordx4 v[132:133], off
	s_add_i32 m0, s43, 0x2000
	s_add_u32 s44, s16, 0x40000
	v_lshl_add_u64 v[134:135], s[16:17], 0, v[68:69]
	s_addc_u32 s45, s17, 0
	global_load_lds_dwordx4 v[134:135], off
	v_lshl_add_u64 v[136:137], s[44:45], 0, v[72:73]
	s_mov_b32 m0, s26
	v_lshl_add_u64 v[138:139], s[18:19], 0, v[70:71]
	global_load_lds_dwordx4 v[136:137], off
	v_lshl_add_u64 v[136:137], s[44:45], 0, v[68:69]
	s_mov_b32 m0, s27
	s_nop 0
	global_load_lds_dwordx4 v[136:137], off
	v_lshl_add_u64 v[136:137], s[18:19], 0, v[74:75]
	s_mov_b32 m0, s25
	s_nop 0
	global_load_lds_dwordx4 v[136:137], off
	s_mov_b32 m0, s28
	s_nop 0
	global_load_lds_dwordx4 v[138:139], off
	s_waitcnt vmcnt(8)
	s_waitcnt lgkmcnt(0)
	s_setprio 1
	s_barrier
	v_mfma_f32_16x16x32_bf16 v[30:33], v[84:87], v[100:103], v[30:33]
	v_mfma_f32_16x16x32_bf16 v[26:29], v[92:95], v[100:103], v[26:29]
	v_mfma_f32_16x16x32_bf16 v[22:25], v[84:87], v[108:111], v[22:25]
	v_mfma_f32_16x16x32_bf16 v[18:21], v[92:95], v[108:111], v[18:21]
	v_mfma_f32_16x16x32_bf16 v[14:17], v[84:87], v[116:119], v[14:17]
	v_mfma_f32_16x16x32_bf16 v[10:13], v[92:95], v[116:119], v[10:13]
	v_mfma_f32_16x16x32_bf16 v[6:9], v[84:87], v[124:127], v[6:9]
	v_mfma_f32_16x16x32_bf16 v[2:5], v[92:95], v[124:127], v[2:5]
	v_mfma_f32_16x16x32_bf16 v[30:33], v[88:91], v[104:107], v[30:33]
	v_mfma_f32_16x16x32_bf16 v[26:29], v[96:99], v[104:107], v[26:29]
	v_mfma_f32_16x16x32_bf16 v[22:25], v[88:91], v[112:115], v[22:25]
	v_mfma_f32_16x16x32_bf16 v[18:21], v[96:99], v[112:115], v[18:21]
	v_mfma_f32_16x16x32_bf16 v[14:17], v[88:91], v[120:123], v[14:17]
	v_mfma_f32_16x16x32_bf16 v[10:13], v[96:99], v[120:123], v[10:13]
	v_mfma_f32_16x16x32_bf16 v[6:9], v[88:91], v[128:131], v[6:9]
	v_mfma_f32_16x16x32_bf16 v[2:5], v[96:99], v[128:131], v[2:5]
	s_setprio 0
	s_setprio 1
	s_setprio 0
	s_barrier
; #define PG8_STAGE(bufoff, gbase, voff) do { _Pragma("unroll") for (int _i = 0; _i < 2; ++_i) \
;         __builtin_amdgcn_global_load_lds((const unsigned*)((const char*)(gbase) + (voff)[_i]), (PG8_LAS unsigned*)(lds + (bufoff) + ldsw + _i * 8192), 16, 0, 0); } while (0)
; #define PG8_LDA(dst, b, h) do { _Pragma("unroll") for (int m = 0; m < 4; ++m) _Pragma("unroll") for (int k = 0; k < 2; ++k) dst[m][k] = *(const PG8_LAS bf16x8*)(lds + PG8_SA(b, h) + aoff + m * 2048 + k * 1024); } while (0)
; #define PG8_LDB(dst, b, h) do { _Pragma("unroll") for (int n = 0; n < 2; ++n) _Pragma("unroll") for (int k = 0; k < 2; ++k) dst[n][k] = *(const PG8_LAS bf16x8*)(lds + PG8_SB(b, h) + boff + n * 2048 + k * 1024); } while (0)
; #define PG8_MMA(ai, bj, At, Bt) do { __builtin_amdgcn_s_setprio(1); _Pragma("unroll") for (int m = 0; m < 4; ++m) _Pragma("unroll") for (int n = 0; n < 2; ++n) _Pragma("unroll") for (int k = 0; k < 2; ++k) \
;         acc[ai][bj][m][n] = __builtin_amdgcn_mfma_f32_16x16x32_bf16(Bt[n][k], At[m][k], acc[ai][bj][m][n], 0, 0, 0); __builtin_amdgcn_s_setprio(0); } while (0)
; #define PG8_WAIT_V(n) asm volatile("s_waitcnt vmcnt(" #n ")" ::: "memory")
; #define PG8_WAIT_L(n) asm volatile("s_waitcnt lgkmcnt(" #n ")" ::: "memory")
; #define PG8_BAR __builtin_amdgcn_s_barrier()
; #define PG8_SCHED __builtin_amdgcn_sched_barrier(0)
; template <class Epi, class Sched, bool ALIGN_EPI = false, bool SP2 = false>
; __device__ __forceinline__ void gemm_phase(PG8_LAS unsigned char* lds, const Gemm g, const Sched& S, const Epi& E) {
;     ...
;             PG8_LDB(B0, 1, 0); PG8_LDB(B1, 1, 1); PG8_SCHED; PG8_LDA(At, 1, 0); PG8_STAGE(PG8_SA(0, 1), a2 + hstepA, voffA);
;             PG8_WAIT_V(8); PG8_WAIT_L(0); PG8_BAR; PG8_MMA(0, 0, At, B0); PG8_MMA(0, 1, At, B1); PG8_BAR; PG8_SCHED;
;             PG8_LDA(At, 1, 1); PG8_STAGE(PG8_SB(1, 0), b3, voffB); PG8_STAGE(PG8_SB(1, 1), b3 + hstepB, voffB); PG8_STAGE(PG8_SA(1, 0), a3, voffA);
;             PG8_WAIT_V(8); PG8_WAIT_L(0); PG8_BAR; PG8_MMA(1, 0, At, B0); PG8_MMA(1, 1, At, B1); PG8_BAR; PG8_SCHED;
	s_add_i32 s43, 0, 0x18000
	v_add_u32_e32 v96, s43, v82
	ds_read_b128 v[84:87], v96
	ds_read_b128 v[88:91], v96 offset:1024
	ds_read_b128 v[92:95], v96 offset:2048
	ds_read_b128 v[96:99], v96 offset:3072
	s_add_u32 s18, s18, 0x40000
	s_addc_u32 s19, s19, 0
	s_mov_b32 m0, s29
	v_lshl_add_u64 v[140:141], s[18:19], 0, v[74:75]
	ds_read_b128 v[100:103], v83 offset:32768
	ds_read_b128 v[104:107], v83 offset:33792
	ds_read_b128 v[108:111], v83 offset:34816
	ds_read_b128 v[112:115], v83 offset:35840
	ds_read_b128 v[116:119], v83 offset:36864
	ds_read_b128 v[120:123], v83 offset:37888
	ds_read_b128 v[124:127], v83 offset:38912
	ds_read_b128 v[128:131], v83 offset:39936
	global_load_lds_dwordx4 v[140:141], off
	v_lshl_add_u64 v[140:141], s[18:19], 0, v[70:71]
	s_mov_b32 m0, s30
	s_nop 0
	global_load_lds_dwordx4 v[140:141], off
	s_waitcnt vmcnt(8)
	s_waitcnt lgkmcnt(0)
	s_setprio 1
	s_barrier
	v_mfma_f32_16x16x32_bf16 v[62:65], v[84:87], v[100:103], v[62:65]
	v_mfma_f32_16x16x32_bf16 v[58:61], v[92:95], v[100:103], v[58:61]
	v_mfma_f32_16x16x32_bf16 v[54:57], v[84:87], v[108:111], v[54:57]
	v_mfma_f32_16x16x32_bf16 v[50:53], v[92:95], v[108:111], v[50:53]
	v_mfma_f32_16x16x32_bf16 v[46:49], v[84:87], v[116:119], v[46:49]
	v_mfma_f32_16x16x32_bf16 v[42:45], v[92:95], v[116:119], v[42:45]
	v_mfma_f32_16x16x32_bf16 v[38:41], v[84:87], v[124:127], v[38:41]
	v_mfma_f32_16x16x32_bf16 v[34:37], v[92:95], v[124:127], v[34:37]
	v_mfma_f32_16x16x32_bf16 v[62:65], v[88:91], v[104:107], v[62:65]
	v_mfma_f32_16x16x32_bf16 v[58:61], v[96:99], v[104:107], v[58:61]
	v_mfma_f32_16x16x32_bf16 v[54:57], v[88:91], v[112:115], v[54:57]
	v_mfma_f32_16x16x32_bf16 v[50:53], v[96:99], v[112:115], v[50:53]
	v_mfma_f32_16x16x32_bf16 v[46:49], v[88:91], v[120:123], v[46:49]
	v_mfma_f32_16x16x32_bf16 v[42:45], v[96:99], v[120:123], v[42:45]
	v_mfma_f32_16x16x32_bf16 v[38:41], v[88:91], v[128:131], v[38:41]
	v_mfma_f32_16x16x32_bf16 v[34:37], v[96:99], v[128:131], v[34:37]
	s_setprio 0
	s_setprio 1
	s_setprio 0
	s_barrier
	s_add_i32 s18, s43, s24
	v_lshl_add_u64 v[132:133], v[132:133], 0, s[96:97]
	s_mov_b32 m0, s18
	ds_read_b128 v[100:103], v83 offset:49152
	ds_read_b128 v[104:107], v83 offset:50176
	ds_read_b128 v[108:111], v83 offset:51200
	ds_read_b128 v[112:115], v83 offset:52224
	ds_read_b128 v[116:119], v83 offset:53248
	ds_read_b128 v[120:123], v83 offset:54272
	ds_read_b128 v[124:127], v83 offset:55296
	ds_read_b128 v[128:131], v83 offset:56320
	global_load_lds_dwordx4 v[132:133], off
	s_add_i32 m0, s18, 0x2000
	s_add_u32 s16, s16, 0x40080
	v_lshl_add_u64 v[132:133], v[134:135], 0, s[96:97]
	s_addc_u32 s17, s17, 0
	global_load_lds_dwordx4 v[132:133], off
	v_lshl_add_u64 v[132:133], s[16:17], 0, v[72:73]
	s_mov_b32 m0, s36
	s_nop 0
	global_load_lds_dwordx4 v[132:133], off
	v_lshl_add_u64 v[132:133], s[16:17], 0, v[68:69]
	s_mov_b32 m0, s37
	s_nop 0
	global_load_lds_dwordx4 v[132:133], off
	v_lshl_add_u64 v[132:133], v[136:137], 0, s[96:97]
	s_mov_b32 m0, s34
	s_nop 0
	global_load_lds_dwordx4 v[132:133], off
	v_lshl_add_u64 v[132:133], v[138:139], 0, s[96:97]
	s_mov_b32 m0, s35
	s_nop 0
	global_load_lds_dwordx4 v[132:133], off
	s_waitcnt vmcnt(8)
	s_waitcnt lgkmcnt(0)
	s_setprio 1
	s_barrier
	v_mfma_f32_16x16x32_bf16 v[30:33], v[84:87], v[100:103], v[30:33]
	v_mfma_f32_16x16x32_bf16 v[26:29], v[92:95], v[100:103], v[26:29]
	v_mfma_f32_16x16x32_bf16 v[22:25], v[84:87], v[108:111], v[22:25]
	v_mfma_f32_16x16x32_bf16 v[18:21], v[92:95], v[108:111], v[18:21]
	v_mfma_f32_16x16x32_bf16 v[14:17], v[84:87], v[116:119], v[14:17]
	v_mfma_f32_16x16x32_bf16 v[10:13], v[92:95], v[116:119], v[10:13]
	v_mfma_f32_16x16x32_bf16 v[6:9], v[84:87], v[124:127], v[6:9]
	v_mfma_f32_16x16x32_bf16 v[2:5], v[92:95], v[124:127], v[2:5]
	v_mfma_f32_16x16x32_bf16 v[30:33], v[88:91], v[104:107], v[30:33]
	v_mfma_f32_16x16x32_bf16 v[26:29], v[96:99], v[104:107], v[26:29]
	v_mfma_f32_16x16x32_bf16 v[22:25], v[88:91], v[112:115], v[22:25]
	v_mfma_f32_16x16x32_bf16 v[18:21], v[96:99], v[112:115], v[18:21]
	v_mfma_f32_16x16x32_bf16 v[14:17], v[88:91], v[120:123], v[14:17]
	v_mfma_f32_16x16x32_bf16 v[10:13], v[96:99], v[120:123], v[10:13]
	v_mfma_f32_16x16x32_bf16 v[6:9], v[88:91], v[128:131], v[6:9]
	v_mfma_f32_16x16x32_bf16 v[2:5], v[96:99], v[128:131], v[2:5]
	s_setprio 0
	s_setprio 1
	s_setprio 0
	s_barrier
	s_add_i32 s42, s42, 2
	s_add_u32 s14, s14, 0x100
	s_addc_u32 s15, s15, 0
	s_cmp_gt_u32 s42, 13
	s_cbranch_scc0 .LBB0_448
	s_cmpk_lt_u32 s23, 0x100
	s_cbranch_scc0 .LBB0_451
	s_barrier

; #define PG8_STAGE(bufoff, gbase, voff) do { _Pragma("unroll") for (int _i = 0; _i < 2; ++_i) \
;         __builtin_amdgcn_global_load_lds((const unsigned*)((const char*)(gbase) + (voff)[_i]), (PG8_LAS unsigned*)(lds + (bufoff) + ldsw + _i * 8192), 16, 0, 0); } while (0)
; #define PG8_LDA(dst, b, h) do { _Pragma("unroll") for (int m = 0; m < 4; ++m) _Pragma("unroll") for (int k = 0; k < 2; ++k) dst[m][k] = *(const PG8_LAS bf16x8*)(lds + PG8_SA(b, h) + aoff + m * 2048 + k * 1024); } while (0)
; #define PG8_LDB(dst, b, h) do { _Pragma("unroll") for (int n = 0; n < 2; ++n) _Pragma("unroll") for (int k = 0; k < 2; ++k) dst[n][k] = *(const PG8_LAS bf16x8*)(lds + PG8_SB(b, h) + boff + n * 2048 + k * 1024); } while (0)
; #define PG8_MMA(ai, bj, At, Bt) do { __builtin_amdgcn_s_setprio(1); _Pragma("unroll") for (int m = 0; m < 4; ++m) _Pragma("unroll") for (int n = 0; n < 2; ++n) _Pragma("unroll") for (int k = 0; k < 2; ++k) \
;         acc[ai][bj][m][n] = __builtin_amdgcn_mfma_f32_16x16x32_bf16(Bt[n][k], At[m][k], acc[ai][bj][m][n], 0, 0, 0); __builtin_amdgcn_s_setprio(0); } while (0)
; #define PG8_WAIT_V(n) asm volatile("s_waitcnt vmcnt(" #n ")" ::: "memory")
; #define PG8_WAIT_L(n) asm volatile("s_waitcnt lgkmcnt(" #n ")" ::: "memory")
; #define PG8_BAR __builtin_amdgcn_s_barrier()
; #define PG8_SCHED __builtin_amdgcn_sched_barrier(0)
; template <class Epi, class Sched, bool ALIGN_EPI = false, bool SP2 = false>
; __device__ __forceinline__ void gemm_phase(PG8_LAS unsigned char* lds, const Gemm g, const Sched& S, const Epi& E) {
;     ...
;             PG8_LDB(B0, 0, 0); PG8_LDB(B1, 0, 1); PG8_SCHED; PG8_LDA(At, 0, 0); PG8_STAGE(PG8_SA(1, 1), a1 + hstepA, voffA);
;             PG8_WAIT_V(8); PG8_WAIT_L(0); PG8_BAR; PG8_MMA(0, 0, At, B0); PG8_MMA(0, 1, At, B1); PG8_BAR; PG8_SCHED;
;             PG8_LDA(At, 0, 1); PG8_STAGE(PG8_SB(0, 0), b2, voffB); PG8_STAGE(PG8_SB(0, 1), b2 + hstepB, voffB); PG8_STAGE(PG8_SA(0, 0), a2, voffA);
.LBB0_530:
	s_add_u32 s12, s1, s8
	s_addc_u32 s13, s28, s9
	s_add_u32 s12, s12, 0xfe00100
	s_addc_u32 s13, s13, 0
	s_add_u32 s34, s29, s8
	s_addc_u32 s35, s30, s9
	s_add_i32 s36, 0, 0x10000
	s_cmpk_eq_i32 s8, 0x700
	s_cselect_b32 s15, s7, s13
	s_cselect_b32 s14, s6, s12
	v_add_u32_e32 v145, s36, v143
	s_cselect_b32 s13, s5, s35
	s_cselect_b32 s12, s4, s34
	s_add_i32 s37, 0, 0x14000
	ds_read_b128 v[146:149], v145
	ds_read_b128 v[150:153], v145 offset:1024
	ds_read_b128 v[154:157], v145 offset:2048
	ds_read_b128 v[158:161], v145 offset:3072
	v_add_u32_e32 v145, s37, v143
	ds_read_b128 v[162:165], v145
	ds_read_b128 v[166:169], v145 offset:1024
	ds_read_b128 v[170:173], v145 offset:2048
	ds_read_b128 v[174:177], v145 offset:3072
	v_lshl_add_u64 v[186:187], v[138:139], 0, s[8:9]
	s_add_i32 m0, s21, 0xc000
	ds_read_b128 v[178:181], v144
	ds_read_b128 v[182:185], v144 offset:1024
	ds_read_b128 v[202:205], v144 offset:2048
	ds_read_b128 v[206:209], v144 offset:3072
	ds_read_b128 v[210:213], v144 offset:4096
	ds_read_b128 v[232:235], v144 offset:5120
	ds_read_b128 v[236:239], v144 offset:6144
	ds_read_b128 v[240:243], v144 offset:7168
	global_load_lds_dwordx4 v[186:187], off
	v_lshl_add_u64 v[186:187], v[140:141], 0, s[8:9]
	s_add_i32 m0, s21, 0xe000
	s_nop 0
	global_load_lds_dwordx4 v[186:187], off
	s_waitcnt vmcnt(8)
	s_waitcnt lgkmcnt(0)
	s_setprio 1
	s_barrier
	v_mfma_f32_16x16x32_bf16 v[126:129], v[146:149], v[178:181], v[126:129]
	v_mfma_f32_16x16x32_bf16 v[122:125], v[154:157], v[178:181], v[122:125]
	v_mfma_f32_16x16x32_bf16 v[118:121], v[146:149], v[202:205], v[118:121]
	v_mfma_f32_16x16x32_bf16 v[114:117], v[154:157], v[202:205], v[114:117]
	v_mfma_f32_16x16x32_bf16 v[110:113], v[146:149], v[210:213], v[110:113]
	v_mfma_f32_16x16x32_bf16 v[106:109], v[154:157], v[210:213], v[106:109]
	v_mfma_f32_16x16x32_bf16 v[102:105], v[146:149], v[236:239], v[102:105]
	v_mfma_f32_16x16x32_bf16 v[98:101], v[154:157], v[236:239], v[98:101]
	v_mfma_f32_16x16x32_bf16 v[126:129], v[150:153], v[182:185], v[126:129]
	v_mfma_f32_16x16x32_bf16 v[122:125], v[158:161], v[182:185], v[122:125]
	v_mfma_f32_16x16x32_bf16 v[118:121], v[150:153], v[206:209], v[118:121]
	v_mfma_f32_16x16x32_bf16 v[114:117], v[158:161], v[206:209], v[114:117]
	v_mfma_f32_16x16x32_bf16 v[110:113], v[150:153], v[232:235], v[110:113]
	v_mfma_f32_16x16x32_bf16 v[106:109], v[158:161], v[232:235], v[106:109]
	v_mfma_f32_16x16x32_bf16 v[102:105], v[150:153], v[240:243], v[102:105]
	v_mfma_f32_16x16x32_bf16 v[98:101], v[158:161], v[240:243], v[98:101]
	s_setprio 0
	s_setprio 1
	v_mfma_f32_16x16x32_bf16 v[94:97], v[162:165], v[178:181], v[94:97]
	v_mfma_f32_16x16x32_bf16 v[86:89], v[170:173], v[178:181], v[86:89]
	v_mfma_f32_16x16x32_bf16 v[78:81], v[162:165], v[202:205], v[78:81]
	v_mfma_f32_16x16x32_bf16 v[74:77], v[170:173], v[202:205], v[74:77]
	v_mfma_f32_16x16x32_bf16 v[70:73], v[162:165], v[210:213], v[70:73]
	v_mfma_f32_16x16x32_bf16 v[62:65], v[170:173], v[210:213], v[62:65]
	v_mfma_f32_16x16x32_bf16 v[54:57], v[162:165], v[236:239], v[54:57]
	v_mfma_f32_16x16x32_bf16 v[50:53], v[170:173], v[236:239], v[50:53]
	v_mfma_f32_16x16x32_bf16 v[94:97], v[166:169], v[182:185], v[94:97]
	v_mfma_f32_16x16x32_bf16 v[86:89], v[174:177], v[182:185], v[86:89]
	v_mfma_f32_16x16x32_bf16 v[78:81], v[166:169], v[206:209], v[78:81]
	v_mfma_f32_16x16x32_bf16 v[74:77], v[174:177], v[206:209], v[74:77]
	v_mfma_f32_16x16x32_bf16 v[70:73], v[166:169], v[232:235], v[70:73]
	v_mfma_f32_16x16x32_bf16 v[62:65], v[174:177], v[232:235], v[62:65]
	v_mfma_f32_16x16x32_bf16 v[54:57], v[166:169], v[240:243], v[54:57]
	v_mfma_f32_16x16x32_bf16 v[50:53], v[174:177], v[240:243], v[50:53]
	s_setprio 0
	s_barrier
	s_add_i32 s34, s36, s20
	s_mov_b32 m0, s34
	ds_read_b128 v[178:181], v144 offset:16384
	ds_read_b128 v[182:185], v144 offset:17408
	ds_read_b128 v[202:205], v144 offset:18432
	ds_read_b128 v[206:209], v144 offset:19456
	ds_read_b128 v[210:213], v144 offset:20480
	ds_read_b128 v[232:235], v144 offset:21504
	ds_read_b128 v[236:239], v144 offset:22528
	ds_read_b128 v[240:243], v144 offset:23552
	s_add_u32 s60, s12, 0x80
	s_addc_u32 s61, s13, 0
	s_add_u32 s62, s14, 0x80
	s_addc_u32 s63, s15, 0
	global_load_lds_dwordx4 v134, s[12:13]
	s_add_i32 m0, s34, 0x2000
	s_add_u32 s34, s12, 0x80000
	s_addc_u32 s35, s13, 0
	s_add_i32 s36, s37, s20
	global_load_lds_dwordx4 v130, s[12:13]
	s_mov_b32 m0, s36
	s_nop 0
	global_load_lds_dwordx4 v134, s[34:35]
	s_add_i32 m0, s36, 0x2000
	s_nop 0
	global_load_lds_dwordx4 v130, s[34:35]
	s_mov_b32 m0, s21
	s_nop 0
	global_load_lds_dwordx4 v136, s[14:15]
	s_mov_b32 m0, s22
	s_nop 0
	global_load_lds_dwordx4 v132, s[14:15]
	s_waitcnt vmcnt(8)
	s_waitcnt lgkmcnt(0)
	s_setprio 1
	s_barrier
; #define PG8_STAGE(bufoff, gbase, voff) do { _Pragma("unroll") for (int _i = 0; _i < 2; ++_i) \
;         __builtin_amdgcn_global_load_lds((const unsigned*)((const char*)(gbase) + (voff)[_i]), (PG8_LAS unsigned*)(lds + (bufoff) + ldsw + _i * 8192), 16, 0, 0); } while (0)
; #define PG8_LDA(dst, b, h) do { _Pragma("unroll") for (int m = 0; m < 4; ++m) _Pragma("unroll") for (int k = 0; k < 2; ++k) dst[m][k] = *(const PG8_LAS bf16x8*)(lds + PG8_SA(b, h) + aoff + m * 2048 + k * 1024); } while (0)
; #define PG8_LDB(dst, b, h) do { _Pragma("unroll") for (int n = 0; n < 2; ++n) _Pragma("unroll") for (int k = 0; k < 2; ++k) dst[n][k] = *(const PG8_LAS bf16x8*)(lds + PG8_SB(b, h) + boff + n * 2048 + k * 1024); } while (0)
; #define PG8_MMA(ai, bj, At, Bt) do { __builtin_amdgcn_s_setprio(1); _Pragma("unroll") for (int m = 0; m < 4; ++m) _Pragma("unroll") for (int n = 0; n < 2; ++n) _Pragma("unroll") for (int k = 0; k < 2; ++k) \
;         acc[ai][bj][m][n] = __builtin_amdgcn_mfma_f32_16x16x32_bf16(Bt[n][k], At[m][k], acc[ai][bj][m][n], 0, 0, 0); __builtin_amdgcn_s_setprio(0); } while (0)
; #define PG8_WAIT_V(n) asm volatile("s_waitcnt vmcnt(" #n ")" ::: "memory")
; #define PG8_WAIT_L(n) asm volatile("s_waitcnt lgkmcnt(" #n ")" ::: "memory")
; #define PG8_BAR __builtin_amdgcn_s_barrier()
; #define PG8_SCHED __builtin_amdgcn_sched_barrier(0)
; template <class Epi, class Sched, bool ALIGN_EPI = false, bool SP2 = false>
; __device__ __forceinline__ void gemm_phase(PG8_LAS unsigned char* lds, const Gemm g, const Sched& S, const Epi& E) {
;     ...
;             PG8_WAIT_V(8); PG8_WAIT_L(0); PG8_BAR; PG8_MMA(1, 0, At, B0); PG8_MMA(1, 1, At, B1); PG8_BAR; PG8_SCHED;
;             PG8_LDB(B0, 1, 0); PG8_LDB(B1, 1, 1); PG8_SCHED; PG8_LDA(At, 1, 0); PG8_STAGE(PG8_SA(0, 1), a2 + hstepA, voffA);
;             PG8_WAIT_V(8); PG8_WAIT_L(0); PG8_BAR; PG8_MMA(0, 0, At, B0); PG8_MMA(0, 1, At, B1); PG8_BAR; PG8_SCHED;
	v_mfma_f32_16x16x32_bf16 v[90:93], v[146:149], v[178:181], v[90:93]
	v_mfma_f32_16x16x32_bf16 v[82:85], v[154:157], v[178:181], v[82:85]
	v_mfma_f32_16x16x32_bf16 v[66:69], v[146:149], v[202:205], v[66:69]
	v_mfma_f32_16x16x32_bf16 v[58:61], v[154:157], v[202:205], v[58:61]
	v_mfma_f32_16x16x32_bf16 v[46:49], v[146:149], v[210:213], v[46:49]
	v_mfma_f32_16x16x32_bf16 v[42:45], v[154:157], v[210:213], v[42:45]
	v_mfma_f32_16x16x32_bf16 v[38:41], v[146:149], v[236:239], v[38:41]
	v_mfma_f32_16x16x32_bf16 v[34:37], v[154:157], v[236:239], v[34:37]
	v_mfma_f32_16x16x32_bf16 v[90:93], v[150:153], v[182:185], v[90:93]
	v_mfma_f32_16x16x32_bf16 v[82:85], v[158:161], v[182:185], v[82:85]
	v_mfma_f32_16x16x32_bf16 v[66:69], v[150:153], v[206:209], v[66:69]
	v_mfma_f32_16x16x32_bf16 v[58:61], v[158:161], v[206:209], v[58:61]
	v_mfma_f32_16x16x32_bf16 v[46:49], v[150:153], v[232:235], v[46:49]
	v_mfma_f32_16x16x32_bf16 v[42:45], v[158:161], v[232:235], v[42:45]
	v_mfma_f32_16x16x32_bf16 v[38:41], v[150:153], v[240:243], v[38:41]
	v_mfma_f32_16x16x32_bf16 v[34:37], v[158:161], v[240:243], v[34:37]
	s_setprio 0
	s_setprio 1
	v_mfma_f32_16x16x32_bf16 v[30:33], v[162:165], v[178:181], v[30:33]
	v_mfma_f32_16x16x32_bf16 v[26:29], v[170:173], v[178:181], v[26:29]
	v_mfma_f32_16x16x32_bf16 v[22:25], v[162:165], v[202:205], v[22:25]
	v_mfma_f32_16x16x32_bf16 v[18:21], v[170:173], v[202:205], v[18:21]
	v_mfma_f32_16x16x32_bf16 v[14:17], v[162:165], v[210:213], v[14:17]
	v_mfma_f32_16x16x32_bf16 v[10:13], v[170:173], v[210:213], v[10:13]
	v_mfma_f32_16x16x32_bf16 v[6:9], v[162:165], v[236:239], v[6:9]
	v_mfma_f32_16x16x32_bf16 v[2:5], v[170:173], v[236:239], v[2:5]
	v_mfma_f32_16x16x32_bf16 v[30:33], v[166:169], v[182:185], v[30:33]
	v_mfma_f32_16x16x32_bf16 v[26:29], v[174:177], v[182:185], v[26:29]
	v_mfma_f32_16x16x32_bf16 v[22:25], v[166:169], v[206:209], v[22:25]
	v_mfma_f32_16x16x32_bf16 v[18:21], v[174:177], v[206:209], v[18:21]
	v_mfma_f32_16x16x32_bf16 v[14:17], v[166:169], v[232:235], v[14:17]
	v_mfma_f32_16x16x32_bf16 v[10:13], v[174:177], v[232:235], v[10:13]
	v_mfma_f32_16x16x32_bf16 v[6:9], v[166:169], v[240:243], v[6:9]
	v_mfma_f32_16x16x32_bf16 v[2:5], v[174:177], v[240:243], v[2:5]
	s_setprio 0
	s_barrier
	s_add_i32 s34, 0, 0x18000
	v_add_u32_e32 v145, s34, v143
	s_add_i32 s35, 0, 0x1c000
	ds_read_b128 v[146:149], v145
	ds_read_b128 v[150:153], v145 offset:1024
	ds_read_b128 v[154:157], v145 offset:2048
	ds_read_b128 v[158:161], v145 offset:3072
	v_add_u32_e32 v145, s35, v143
	ds_read_b128 v[162:165], v145
	ds_read_b128 v[166:169], v145 offset:1024
	ds_read_b128 v[170:173], v145 offset:2048
	ds_read_b128 v[174:177], v145 offset:3072
	s_add_u32 s14, s14, 0x40000
	s_addc_u32 s15, s15, 0
	s_mov_b32 m0, s23
	ds_read_b128 v[178:181], v144 offset:32768
	ds_read_b128 v[182:185], v144 offset:33792
	ds_read_b128 v[202:205], v144 offset:34816
	ds_read_b128 v[206:209], v144 offset:35840
	ds_read_b128 v[210:213], v144 offset:36864
	ds_read_b128 v[232:235], v144 offset:37888
	ds_read_b128 v[236:239], v144 offset:38912
	ds_read_b128 v[240:243], v144 offset:39936
	global_load_lds_dwordx4 v136, s[14:15]
	s_mov_b32 m0, s24
	s_nop 0
	global_load_lds_dwordx4 v132, s[14:15]
	s_waitcnt vmcnt(8)
	s_waitcnt lgkmcnt(0)
	s_setprio 1
	s_barrier
	v_mfma_f32_16x16x32_bf16 v[126:129], v[146:149], v[178:181], v[126:129]
	v_mfma_f32_16x16x32_bf16 v[122:125], v[154:157], v[178:181], v[122:125]
	v_mfma_f32_16x16x32_bf16 v[118:121], v[146:149], v[202:205], v[118:121]
	v_mfma_f32_16x16x32_bf16 v[114:117], v[154:157], v[202:205], v[114:117]
	v_mfma_f32_16x16x32_bf16 v[110:113], v[146:149], v[210:213], v[110:113]
	v_mfma_f32_16x16x32_bf16 v[106:109], v[154:157], v[210:213], v[106:109]
	v_mfma_f32_16x16x32_bf16 v[102:105], v[146:149], v[236:239], v[102:105]
	v_mfma_f32_16x16x32_bf16 v[98:101], v[154:157], v[236:239], v[98:101]
	v_mfma_f32_16x16x32_bf16 v[126:129], v[150:153], v[182:185], v[126:129]
	v_mfma_f32_16x16x32_bf16 v[122:125], v[158:161], v[182:185], v[122:125]
	v_mfma_f32_16x16x32_bf16 v[118:121], v[150:153], v[206:209], v[118:121]
	v_mfma_f32_16x16x32_bf16 v[114:117], v[158:161], v[206:209], v[114:117]
	v_mfma_f32_16x16x32_bf16 v[110:113], v[150:153], v[232:235], v[110:113]
	v_mfma_f32_16x16x32_bf16 v[106:109], v[158:161], v[232:235], v[106:109]
	v_mfma_f32_16x16x32_bf16 v[102:105], v[150:153], v[240:243], v[102:105]
	v_mfma_f32_16x16x32_bf16 v[98:101], v[158:161], v[240:243], v[98:101]
	s_setprio 0
	s_setprio 1
	v_mfma_f32_16x16x32_bf16 v[94:97], v[162:165], v[178:181], v[94:97]
	v_mfma_f32_16x16x32_bf16 v[86:89], v[170:173], v[178:181], v[86:89]
	v_mfma_f32_16x16x32_bf16 v[78:81], v[162:165], v[202:205], v[78:81]
	v_mfma_f32_16x16x32_bf16 v[74:77], v[170:173], v[202:205], v[74:77]
	v_mfma_f32_16x16x32_bf16 v[70:73], v[162:165], v[210:213], v[70:73]
	v_mfma_f32_16x16x32_bf16 v[62:65], v[170:173], v[210:213], v[62:65]
	v_mfma_f32_16x16x32_bf16 v[54:57], v[162:165], v[236:239], v[54:57]
	v_mfma_f32_16x16x32_bf16 v[50:53], v[170:173], v[236:239], v[50:53]
	v_mfma_f32_16x16x32_bf16 v[94:97], v[166:169], v[182:185], v[94:97]
	v_mfma_f32_16x16x32_bf16 v[86:89], v[174:177], v[182:185], v[86:89]
	v_mfma_f32_16x16x32_bf16 v[78:81], v[166:169], v[206:209], v[78:81]
	v_mfma_f32_16x16x32_bf16 v[74:77], v[174:177], v[206:209], v[74:77]
	v_mfma_f32_16x16x32_bf16 v[70:73], v[166:169], v[232:235], v[70:73]
	v_mfma_f32_16x16x32_bf16 v[62:65], v[174:177], v[232:235], v[62:65]
	v_mfma_f32_16x16x32_bf16 v[54:57], v[166:169], v[240:243], v[54:57]
	v_mfma_f32_16x16x32_bf16 v[50:53], v[174:177], v[240:243], v[50:53]
	s_setprio 0
	s_barrier
; #define PG8_STAGE(bufoff, gbase, voff) do { _Pragma("unroll") for (int _i = 0; _i < 2; ++_i) \
;         __builtin_amdgcn_global_load_lds((const unsigned*)((const char*)(gbase) + (voff)[_i]), (PG8_LAS unsigned*)(lds + (bufoff) + ldsw + _i * 8192), 16, 0, 0); } while (0)
; #define PG8_LDA(dst, b, h) do { _Pragma("unroll") for (int m = 0; m < 4; ++m) _Pragma("unroll") for (int k = 0; k < 2; ++k) dst[m][k] = *(const PG8_LAS bf16x8*)(lds + PG8_SA(b, h) + aoff + m * 2048 + k * 1024); } while (0)
; #define PG8_MMA(ai, bj, At, Bt) do { __builtin_amdgcn_s_setprio(1); _Pragma("unroll") for (int m = 0; m < 4; ++m) _Pragma("unroll") for (int n = 0; n < 2; ++n) _Pragma("unroll") for (int k = 0; k < 2; ++k) \
;         acc[ai][bj][m][n] = __builtin_amdgcn_mfma_f32_16x16x32_bf16(Bt[n][k], At[m][k], acc[ai][bj][m][n], 0, 0, 0); __builtin_amdgcn_s_setprio(0); } while (0)
; #define PG8_WAIT_V(n) asm volatile("s_waitcnt vmcnt(" #n ")" ::: "memory")
; #define PG8_WAIT_L(n) asm volatile("s_waitcnt lgkmcnt(" #n ")" ::: "memory")
; #define PG8_BAR __builtin_amdgcn_s_barrier()
; #define PG8_SCHED __builtin_amdgcn_sched_barrier(0)
; template <class Epi, class Sched, bool ALIGN_EPI = false, bool SP2 = false>
; __device__ __forceinline__ void gemm_phase(PG8_LAS unsigned char* lds, const Gemm g, const Sched& S, const Epi& E) {
;     ...
;             PG8_LDA(At, 1, 1); PG8_STAGE(PG8_SB(1, 0), b3, voffB); PG8_STAGE(PG8_SB(1, 1), b3 + hstepB, voffB); PG8_STAGE(PG8_SA(1, 0), a3, voffA);
;             PG8_WAIT_V(8); PG8_WAIT_L(0); PG8_BAR; PG8_MMA(1, 0, At, B0); PG8_MMA(1, 1, At, B1); PG8_BAR; PG8_SCHED;
	s_add_i32 s14, s34, s20
	s_mov_b32 m0, s14
	ds_read_b128 v[178:181], v144 offset:49152
	ds_read_b128 v[182:185], v144 offset:50176
	ds_read_b128 v[202:205], v144 offset:51200
	ds_read_b128 v[206:209], v144 offset:52224
	ds_read_b128 v[210:213], v144 offset:53248
	ds_read_b128 v[232:235], v144 offset:54272
	ds_read_b128 v[236:239], v144 offset:55296
	ds_read_b128 v[240:243], v144 offset:56320
	global_load_lds_dwordx4 v134, s[60:61]
	s_add_i32 m0, s14, 0x2000
	s_add_u32 s12, s12, 0x80080
	s_addc_u32 s13, s13, 0
	s_add_i32 s14, s35, s20
	global_load_lds_dwordx4 v130, s[60:61]
	s_mov_b32 m0, s14
	s_nop 0
	global_load_lds_dwordx4 v134, s[12:13]
	s_add_i32 m0, s14, 0x2000
	s_nop 0
	global_load_lds_dwordx4 v130, s[12:13]
	s_mov_b32 m0, s26
	s_nop 0
	global_load_lds_dwordx4 v136, s[62:63]
	s_mov_b32 m0, s27
	s_nop 0
	global_load_lds_dwordx4 v132, s[62:63]
	s_waitcnt vmcnt(8)
	s_waitcnt lgkmcnt(0)
	s_setprio 1
	s_barrier
	v_mfma_f32_16x16x32_bf16 v[90:93], v[146:149], v[178:181], v[90:93]
	v_mfma_f32_16x16x32_bf16 v[82:85], v[154:157], v[178:181], v[82:85]
	v_mfma_f32_16x16x32_bf16 v[66:69], v[146:149], v[202:205], v[66:69]
	v_mfma_f32_16x16x32_bf16 v[58:61], v[154:157], v[202:205], v[58:61]
	v_mfma_f32_16x16x32_bf16 v[46:49], v[146:149], v[210:213], v[46:49]
	v_mfma_f32_16x16x32_bf16 v[42:45], v[154:157], v[210:213], v[42:45]
	v_mfma_f32_16x16x32_bf16 v[38:41], v[146:149], v[236:239], v[38:41]
	v_mfma_f32_16x16x32_bf16 v[34:37], v[154:157], v[236:239], v[34:37]
	v_mfma_f32_16x16x32_bf16 v[90:93], v[150:153], v[182:185], v[90:93]
	v_mfma_f32_16x16x32_bf16 v[82:85], v[158:161], v[182:185], v[82:85]
	v_mfma_f32_16x16x32_bf16 v[66:69], v[150:153], v[206:209], v[66:69]
	v_mfma_f32_16x16x32_bf16 v[58:61], v[158:161], v[206:209], v[58:61]
	v_mfma_f32_16x16x32_bf16 v[46:49], v[150:153], v[232:235], v[46:49]
	v_mfma_f32_16x16x32_bf16 v[42:45], v[158:161], v[232:235], v[42:45]
	v_mfma_f32_16x16x32_bf16 v[38:41], v[150:153], v[240:243], v[38:41]
	v_mfma_f32_16x16x32_bf16 v[34:37], v[158:161], v[240:243], v[34:37]
	s_setprio 0
	s_setprio 1
	v_mfma_f32_16x16x32_bf16 v[30:33], v[162:165], v[178:181], v[30:33]
	v_mfma_f32_16x16x32_bf16 v[26:29], v[170:173], v[178:181], v[26:29]
	v_mfma_f32_16x16x32_bf16 v[22:25], v[162:165], v[202:205], v[22:25]
	v_mfma_f32_16x16x32_bf16 v[18:21], v[170:173], v[202:205], v[18:21]
	v_mfma_f32_16x16x32_bf16 v[14:17], v[162:165], v[210:213], v[14:17]
	v_mfma_f32_16x16x32_bf16 v[10:13], v[170:173], v[210:213], v[10:13]
	v_mfma_f32_16x16x32_bf16 v[6:9], v[162:165], v[236:239], v[6:9]
	v_mfma_f32_16x16x32_bf16 v[2:5], v[170:173], v[236:239], v[2:5]
	v_mfma_f32_16x16x32_bf16 v[30:33], v[166:169], v[182:185], v[30:33]
	v_mfma_f32_16x16x32_bf16 v[26:29], v[174:177], v[182:185], v[26:29]
	v_mfma_f32_16x16x32_bf16 v[22:25], v[166:169], v[206:209], v[22:25]
	v_mfma_f32_16x16x32_bf16 v[18:21], v[174:177], v[206:209], v[18:21]
	v_mfma_f32_16x16x32_bf16 v[14:17], v[166:169], v[232:235], v[14:17]
	v_mfma_f32_16x16x32_bf16 v[10:13], v[174:177], v[232:235], v[10:13]
	v_mfma_f32_16x16x32_bf16 v[6:9], v[166:169], v[240:243], v[6:9]
	v_mfma_f32_16x16x32_bf16 v[2:5], v[174:177], v[240:243], v[2:5]
	s_setprio 0
	s_barrier
	s_add_i32 s31, s31, 2
	s_add_u32 s8, s8, 0x100
	s_addc_u32 s9, s9, 0
	s_cmp_gt_u32 s31, 13
	s_cbranch_scc0 .LBB0_530
	s_cmpk_lt_u32 s19, 0x100
	s_cbranch_scc0 .LBB0_533
	s_barrier

; #define PG8_STAGE(bufoff, gbase, voff) do { _Pragma("unroll") for (int _i = 0; _i < 2; ++_i) \
;         __builtin_amdgcn_global_load_lds((const unsigned*)((const char*)(gbase) + (voff)[_i]), (PG8_LAS unsigned*)(lds + (bufoff) + ldsw + _i * 8192), 16, 0, 0); } while (0)
; #define PG8_LDA(dst, b, h) do { _Pragma("unroll") for (int m = 0; m < 4; ++m) _Pragma("unroll") for (int k = 0; k < 2; ++k) dst[m][k] = *(const PG8_LAS bf16x8*)(lds + PG8_SA(b, h) + aoff + m * 2048 + k * 1024); } while (0)
; #define PG8_LDB(dst, b, h) do { _Pragma("unroll") for (int n = 0; n < 2; ++n) _Pragma("unroll") for (int k = 0; k < 2; ++k) dst[n][k] = *(const PG8_LAS bf16x8*)(lds + PG8_SB(b, h) + boff + n * 2048 + k * 1024); } while (0)
; #define PG8_MMA(ai, bj, At, Bt) do { __builtin_amdgcn_s_setprio(1); _Pragma("unroll") for (int m = 0; m < 4; ++m) _Pragma("unroll") for (int n = 0; n < 2; ++n) _Pragma("unroll") for (int k = 0; k < 2; ++k) \
;         acc[ai][bj][m][n] = __builtin_amdgcn_mfma_f32_16x16x32_bf16(Bt[n][k], At[m][k], acc[ai][bj][m][n], 0, 0, 0); __builtin_amdgcn_s_setprio(0); } while (0)
; #define PG8_WAIT_V(n) asm volatile("s_waitcnt vmcnt(" #n ")" ::: "memory")
; #define PG8_WAIT_L(n) asm volatile("s_waitcnt lgkmcnt(" #n ")" ::: "memory")
; #define PG8_BAR __builtin_amdgcn_s_barrier()
; #define PG8_SCHED __builtin_amdgcn_sched_barrier(0)
; template <class Epi, class Sched, bool ALIGN_EPI = false, bool SP2 = false>
; __device__ __forceinline__ void gemm_phase(PG8_LAS unsigned char* lds, const Gemm g, const Sched& S, const Epi& E) {
;     ...
;         PG8_WAIT_V(2); PG8_BAR;
;         PG8_STAGE(PG8_SB(1, 0), cB + kstep, voffB); PG8_STAGE(PG8_SA(1, 0), cA + kstep, voffA); PG8_STAGE(PG8_SB(1, 1), cB + hstepB + kstep, voffB);
;         PG8_WAIT_V(6); PG8_BAR;
;     ...
;             PG8_LDB(B0, 0, 0); PG8_LDB(B1, 0, 1); PG8_SCHED; PG8_LDA(At, 0, 0); PG8_STAGE(PG8_SA(1, 1), a1 + hstepA, voffA);
;             PG8_WAIT_V(8); PG8_WAIT_L(0); PG8_BAR; PG8_MMA(0, 0, At, B0); PG8_MMA(0, 1, At, B1); PG8_BAR; PG8_SCHED;
;             PG8_LDA(At, 0, 1); PG8_STAGE(PG8_SB(0, 0), b2, voffB); PG8_STAGE(PG8_SB(0, 1), b2 + hstepB, voffB); PG8_STAGE(PG8_SA(0, 0), a2, voffA);
;             PG8_WAIT_V(8); PG8_WAIT_L(0); PG8_BAR; PG8_MMA(1, 0, At, B0); PG8_MMA(1, 1, At, B1); PG8_BAR; PG8_SCHED;
.LBB0_592:
	s_add_i32 s44, 0, 0x18000
	s_add_i32 s36, s44, s14
	s_and_b32 s28, s15, 3
	v_lshl_add_u64 v[26:27], v[4:5], 0, s[96:97]
	s_mov_b32 m0, s36
	s_add_i32 s38, s36, 0x2000
	s_lshl_b32 s15, s26, 13
	s_lshl_b32 s43, s28, 12
	s_waitcnt vmcnt(2)
	s_barrier
	global_load_lds_dwordx4 v[26:27], off
	v_lshl_add_u64 v[28:29], v[6:7], 0, s[96:97]
	s_mov_b32 m0, s38
	s_add_i32 s37, s27, 0x8000
	s_add_i32 s39, s27, 0xa000
	global_load_lds_dwordx4 v[28:29], off
	v_lshl_add_u64 v[24:25], v[18:19], 0, s[96:97]
	s_mov_b32 m0, s37
	s_add_u32 s16, s8, 0x10080
	global_load_lds_dwordx4 v[24:25], off
	v_lshl_add_u64 v[30:31], v[22:23], 0, s[96:97]
	s_mov_b32 m0, s39
	s_addc_u32 s17, s9, 0
	s_add_i32 s40, s27, 0x1c000
	global_load_lds_dwordx4 v[30:31], off
	v_lshl_add_u64 v[68:69], s[16:17], 0, v[32:33]
	s_mov_b32 m0, s40
	s_add_i32 s41, s27, 0x1e000
	global_load_lds_dwordx4 v[68:69], off
	v_lshl_add_u64 v[70:71], s[16:17], 0, v[20:21]
	s_mov_b32 m0, s41
	v_lshrrev_b32_e32 v35, 1, v34
	global_load_lds_dwordx4 v[70:71], off
	v_and_b32_e32 v72, 24, v35
	v_and_b32_e32 v67, 15, v34
	v_lshlrev_b32_e32 v35, 1, v72
	v_lshlrev_b32_e32 v34, 2, v34
	v_lshl_or_b32 v35, v67, 6, v35
	v_and_b32_e32 v34, 32, v34
	v_bitop3_b32 v36, v35, s15, v34 bitop3:0xde
	s_add_i32 s15, 0, 0x10000
	v_bitop3_b32 v34, v35, s43, v34 bitop3:0xde
	s_add_u32 s48, s12, 0x10080
	v_add_u32_e32 v157, s44, v34
	s_addc_u32 s49, s13, 0
	s_add_i32 s44, s15, s14
	s_add_i32 s46, s27, 0xc000
	s_add_i32 s45, s27, 0xe000
	s_add_i32 s43, s44, 0x2000
	v_add_u32_e32 v73, s15, v34
	s_add_u32 s50, s8, 0x10100
	s_waitcnt vmcnt(6)
	s_barrier
	v_add_u32_e32 v156, 0, v36
	s_addc_u32 s51, s9, 0
	ds_read_b128 v[34:37], v73
	ds_read_b128 v[38:41], v73 offset:1024
	ds_read_b128 v[42:45], v73 offset:2048
	ds_read_b128 v[46:49], v73 offset:3072
	s_add_u32 s16, s12, 0x10100
	s_addc_u32 s17, s13, 0
	s_add_u32 s14, s8, 0x10180
	s_addc_u32 s15, s9, 0
	s_add_u32 s8, s12, 0x10180
	s_addc_u32 s9, s13, 0
	s_cmpk_gt_u32 s42, 0xff
	s_mov_b32 m0, s46
	v_lshl_add_u64 v[90:91], s[48:49], 0, v[14:15]
	ds_read_b128 v[50:53], v156
	ds_read_b128 v[54:57], v156 offset:1024
	ds_read_b128 v[58:61], v156 offset:2048
	ds_read_b128 v[62:65], v156 offset:3072
	ds_read_b128 v[74:77], v156 offset:4096
	ds_read_b128 v[78:81], v156 offset:5120
	ds_read_b128 v[82:85], v156 offset:6144
	ds_read_b128 v[86:89], v156 offset:7168
	global_load_lds_dwordx4 v[90:91], off
	v_lshl_add_u64 v[90:91], s[48:49], 0, v[2:3]
	s_mov_b32 m0, s45
	s_nop 0
	global_load_lds_dwordx4 v[90:91], off
	s_waitcnt vmcnt(8)
	s_waitcnt lgkmcnt(0)
	s_setprio 1
	s_barrier
	v_mfma_f32_16x16x32_bf16 v[90:93], v[34:37], v[50:53], 0
	v_mfma_f32_16x16x32_bf16 v[50:53], v[42:45], v[50:53], 0
	v_mfma_f32_16x16x32_bf16 v[90:93], v[38:41], v[54:57], v[90:93]
	v_mfma_f32_16x16x32_bf16 v[50:53], v[46:49], v[54:57], v[50:53]
	v_mfma_f32_16x16x32_bf16 v[54:57], v[34:37], v[58:61], 0
	v_mfma_f32_16x16x32_bf16 v[58:61], v[42:45], v[58:61], 0
	v_mfma_f32_16x16x32_bf16 v[54:57], v[38:41], v[62:65], v[54:57]
	v_mfma_f32_16x16x32_bf16 v[58:61], v[46:49], v[62:65], v[58:61]
	v_mfma_f32_16x16x32_bf16 v[62:65], v[34:37], v[74:77], 0
	v_mfma_f32_16x16x32_bf16 v[74:77], v[42:45], v[74:77], 0
	v_mfma_f32_16x16x32_bf16 v[62:65], v[38:41], v[78:81], v[62:65]
	v_mfma_f32_16x16x32_bf16 v[74:77], v[46:49], v[78:81], v[74:77]
	v_mfma_f32_16x16x32_bf16 v[78:81], v[34:37], v[82:85], 0
	v_mfma_f32_16x16x32_bf16 v[82:85], v[42:45], v[82:85], 0
	v_mfma_f32_16x16x32_bf16 v[78:81], v[38:41], v[86:89], v[78:81]
	v_mfma_f32_16x16x32_bf16 v[82:85], v[46:49], v[86:89], v[82:85]
	s_setprio 0
	s_setprio 1
	s_setprio 0
	s_barrier
	s_mov_b64 s[12:13], 0x100
	s_mov_b32 m0, s44
	v_lshl_add_u64 v[122:123], v[4:5], 0, s[12:13]
	ds_read_b128 v[86:89], v156 offset:16384
	ds_read_b128 v[94:97], v156 offset:17408
	ds_read_b128 v[98:101], v156 offset:18432
	ds_read_b128 v[102:105], v156 offset:19456
	ds_read_b128 v[106:109], v156 offset:20480
	ds_read_b128 v[110:113], v156 offset:21504
	ds_read_b128 v[114:117], v156 offset:22528
	ds_read_b128 v[118:121], v156 offset:23552
	global_load_lds_dwordx4 v[122:123], off
	v_lshl_add_u64 v[122:123], v[6:7], 0, s[12:13]
	s_mov_b32 m0, s43
	s_nop 0
	global_load_lds_dwordx4 v[122:123], off
	v_lshl_add_u64 v[122:123], s[50:51], 0, v[32:33]
	s_mov_b32 m0, s29
	s_nop 0
	global_load_lds_dwordx4 v[122:123], off
	v_lshl_add_u64 v[122:123], s[50:51], 0, v[20:21]
	s_mov_b32 m0, s31
	s_nop 0
	global_load_lds_dwordx4 v[122:123], off
	v_lshl_add_u64 v[122:123], v[18:19], 0, s[12:13]
	s_mov_b32 m0, s27
	s_nop 0
	global_load_lds_dwordx4 v[122:123], off
	v_lshl_add_u64 v[122:123], v[22:23], 0, s[12:13]
	s_mov_b32 m0, s35
	s_nop 0
	global_load_lds_dwordx4 v[122:123], off
	s_waitcnt vmcnt(8)
	s_waitcnt lgkmcnt(0)
	s_setprio 1
	s_barrier
	v_mfma_f32_16x16x32_bf16 v[122:125], v[34:37], v[86:89], 0
	v_mfma_f32_16x16x32_bf16 v[86:89], v[42:45], v[86:89], 0
	v_mfma_f32_16x16x32_bf16 v[122:125], v[38:41], v[94:97], v[122:125]
	v_mfma_f32_16x16x32_bf16 v[86:89], v[46:49], v[94:97], v[86:89]
	v_mfma_f32_16x16x32_bf16 v[94:97], v[34:37], v[98:101], 0
	v_mfma_f32_16x16x32_bf16 v[98:101], v[42:45], v[98:101], 0
	v_mfma_f32_16x16x32_bf16 v[94:97], v[38:41], v[102:105], v[94:97]
	v_mfma_f32_16x16x32_bf16 v[98:101], v[46:49], v[102:105], v[98:101]
	v_mfma_f32_16x16x32_bf16 v[102:105], v[34:37], v[106:109], 0
	v_mfma_f32_16x16x32_bf16 v[34:37], v[34:37], v[114:117], 0
	v_mfma_f32_16x16x32_bf16 v[102:105], v[38:41], v[110:113], v[102:105]
	v_mfma_f32_16x16x32_bf16 v[34:37], v[38:41], v[118:121], v[34:37]
	v_mfma_f32_16x16x32_bf16 v[38:41], v[42:45], v[114:117], 0
	v_mfma_f32_16x16x32_bf16 v[106:109], v[42:45], v[106:109], 0
	v_mfma_f32_16x16x32_bf16 v[38:41], v[46:49], v[118:121], v[38:41]
	v_mfma_f32_16x16x32_bf16 v[106:109], v[46:49], v[110:113], v[106:109]
	s_setprio 0
	s_setprio 1
	s_setprio 0
	s_barrier
; #define PG8_STAGE(bufoff, gbase, voff) do { _Pragma("unroll") for (int _i = 0; _i < 2; ++_i) \
;         __builtin_amdgcn_global_load_lds((const unsigned*)((const char*)(gbase) + (voff)[_i]), (PG8_LAS unsigned*)(lds + (bufoff) + ldsw + _i * 8192), 16, 0, 0); } while (0)
; #define PG8_LDA(dst, b, h) do { _Pragma("unroll") for (int m = 0; m < 4; ++m) _Pragma("unroll") for (int k = 0; k < 2; ++k) dst[m][k] = *(const PG8_LAS bf16x8*)(lds + PG8_SA(b, h) + aoff + m * 2048 + k * 1024); } while (0)
; #define PG8_LDB(dst, b, h) do { _Pragma("unroll") for (int n = 0; n < 2; ++n) _Pragma("unroll") for (int k = 0; k < 2; ++k) dst[n][k] = *(const PG8_LAS bf16x8*)(lds + PG8_SB(b, h) + boff + n * 2048 + k * 1024); } while (0)
; #define PG8_MMA(ai, bj, At, Bt) do { __builtin_amdgcn_s_setprio(1); _Pragma("unroll") for (int m = 0; m < 4; ++m) _Pragma("unroll") for (int n = 0; n < 2; ++n) _Pragma("unroll") for (int k = 0; k < 2; ++k) \
;         acc[ai][bj][m][n] = __builtin_amdgcn_mfma_f32_16x16x32_bf16(Bt[n][k], At[m][k], acc[ai][bj][m][n], 0, 0, 0); __builtin_amdgcn_s_setprio(0); } while (0)
; #define PG8_WAIT_V(n) asm volatile("s_waitcnt vmcnt(" #n ")" ::: "memory")
; #define PG8_WAIT_L(n) asm volatile("s_waitcnt lgkmcnt(" #n ")" ::: "memory")
; #define PG8_BAR __builtin_amdgcn_s_barrier()
; #define PG8_SCHED __builtin_amdgcn_sched_barrier(0)
; template <class Epi, class Sched, bool ALIGN_EPI = false, bool SP2 = false>
; __device__ __forceinline__ void gemm_phase(PG8_LAS unsigned char* lds, const Gemm g, const Sched& S, const Epi& E) {
;     ...
;             PG8_LDB(B0, 0, 0); PG8_LDB(B1, 0, 1); PG8_SCHED; PG8_LDA(At, 0, 0); PG8_STAGE(PG8_SA(1, 1), a1 + hstepA, voffA);
;             PG8_WAIT_V(8); PG8_WAIT_L(0); PG8_BAR; PG8_MMA(0, 0, At, B0); PG8_MMA(0, 1, At, B1); PG8_BAR; PG8_SCHED;
;     ...
;             PG8_LDB(B0, 1, 0); PG8_LDB(B1, 1, 1); PG8_SCHED; PG8_LDA(At, 1, 0); PG8_STAGE(PG8_SA(0, 1), a2 + hstepA, voffA);
;             PG8_WAIT_V(8); PG8_WAIT_L(0); PG8_BAR; PG8_MMA(0, 0, At, B0); PG8_MMA(0, 1, At, B1); PG8_BAR; PG8_SCHED;
;             PG8_LDA(At, 1, 1); PG8_STAGE(PG8_SB(1, 0), b3, voffB); PG8_STAGE(PG8_SB(1, 1), b3 + hstepB, voffB); PG8_STAGE(PG8_SA(1, 0), a3, voffA);
;             PG8_WAIT_V(8); PG8_WAIT_L(0); PG8_BAR; PG8_MMA(1, 0, At, B0); PG8_MMA(1, 1, At, B1); PG8_BAR; PG8_SCHED;
	ds_read_b128 v[42:45], v157
	ds_read_b128 v[46:49], v157 offset:1024
	ds_read_b128 v[110:113], v157 offset:2048
	ds_read_b128 v[114:117], v157 offset:3072
	s_mov_b32 m0, s30
	v_lshl_add_u64 v[154:155], s[16:17], 0, v[14:15]
	ds_read_b128 v[118:121], v156 offset:32768
	ds_read_b128 v[126:129], v156 offset:33792
	ds_read_b128 v[130:133], v156 offset:34816
	ds_read_b128 v[134:137], v156 offset:35840
	ds_read_b128 v[138:141], v156 offset:36864
	ds_read_b128 v[142:145], v156 offset:37888
	ds_read_b128 v[146:149], v156 offset:38912
	ds_read_b128 v[150:153], v156 offset:39936
	global_load_lds_dwordx4 v[154:155], off
	v_lshl_add_u64 v[154:155], s[16:17], 0, v[2:3]
	s_mov_b32 m0, s34
	s_nop 0
	global_load_lds_dwordx4 v[154:155], off
	s_waitcnt vmcnt(8)
	s_waitcnt lgkmcnt(0)
	s_setprio 1
	s_barrier
	v_mfma_f32_16x16x32_bf16 v[50:53], v[110:113], v[118:121], v[50:53]
	v_mfma_f32_16x16x32_bf16 v[54:57], v[42:45], v[130:133], v[54:57]
	v_mfma_f32_16x16x32_bf16 v[58:61], v[110:113], v[130:133], v[58:61]
	v_mfma_f32_16x16x32_bf16 v[62:65], v[42:45], v[138:141], v[62:65]
	v_mfma_f32_16x16x32_bf16 v[90:93], v[42:45], v[118:121], v[90:93]
	v_mfma_f32_16x16x32_bf16 v[50:53], v[114:117], v[126:129], v[50:53]
	v_mfma_f32_16x16x32_bf16 v[54:57], v[46:49], v[134:137], v[54:57]
	v_mfma_f32_16x16x32_bf16 v[58:61], v[114:117], v[134:137], v[58:61]
	v_mfma_f32_16x16x32_bf16 v[62:65], v[46:49], v[142:145], v[62:65]
	v_mfma_f32_16x16x32_bf16 v[74:77], v[110:113], v[138:141], v[74:77]
	v_mfma_f32_16x16x32_bf16 v[78:81], v[42:45], v[146:149], v[78:81]
	v_mfma_f32_16x16x32_bf16 v[82:85], v[110:113], v[146:149], v[82:85]
	v_mfma_f32_16x16x32_bf16 v[90:93], v[46:49], v[126:129], v[90:93]
	v_mfma_f32_16x16x32_bf16 v[74:77], v[114:117], v[142:145], v[74:77]
	v_mfma_f32_16x16x32_bf16 v[78:81], v[46:49], v[150:153], v[78:81]
	v_mfma_f32_16x16x32_bf16 v[82:85], v[114:117], v[150:153], v[82:85]
	s_setprio 0
	s_setprio 1
	s_setprio 0
	s_barrier
	s_mov_b64 s[12:13], 0x180
	s_mov_b32 m0, s36
	v_lshl_add_u64 v[154:155], v[4:5], 0, s[12:13]
	ds_read_b128 v[118:121], v156 offset:49152
	ds_read_b128 v[126:129], v156 offset:50176
	ds_read_b128 v[130:133], v156 offset:51200
	ds_read_b128 v[134:137], v156 offset:52224
	ds_read_b128 v[138:141], v156 offset:53248
	ds_read_b128 v[142:145], v156 offset:54272
	ds_read_b128 v[146:149], v156 offset:55296
	ds_read_b128 v[150:153], v156 offset:56320
	global_load_lds_dwordx4 v[154:155], off
	v_lshl_add_u64 v[154:155], v[6:7], 0, s[12:13]
	s_mov_b32 m0, s38
	v_lshl_add_u64 v[32:33], s[14:15], 0, v[32:33]
	global_load_lds_dwordx4 v[154:155], off
	s_mov_b32 m0, s40
	v_lshl_add_u64 v[20:21], s[14:15], 0, v[20:21]
	global_load_lds_dwordx4 v[32:33], off
	s_mov_b32 m0, s41
	s_nop 0
	global_load_lds_dwordx4 v[20:21], off
	v_lshl_add_u64 v[20:21], v[18:19], 0, s[12:13]
	s_mov_b32 m0, s37
	s_nop 0
	global_load_lds_dwordx4 v[20:21], off
	v_lshl_add_u64 v[20:21], v[22:23], 0, s[12:13]
	s_mov_b32 m0, s39
	s_nop 0
	global_load_lds_dwordx4 v[20:21], off
	s_waitcnt vmcnt(8)
	s_waitcnt lgkmcnt(0)
	s_setprio 1
	s_barrier
	v_mfma_f32_16x16x32_bf16 v[32:35], v[42:45], v[146:149], v[34:37]
	v_mfma_f32_16x16x32_bf16 v[36:39], v[110:113], v[146:149], v[38:41]
	v_mfma_f32_16x16x32_bf16 v[122:125], v[42:45], v[118:121], v[122:125]
	v_mfma_f32_16x16x32_bf16 v[86:89], v[110:113], v[118:121], v[86:89]
	v_mfma_f32_16x16x32_bf16 v[94:97], v[42:45], v[130:133], v[94:97]
	v_mfma_f32_16x16x32_bf16 v[98:101], v[110:113], v[130:133], v[98:101]
	v_mfma_f32_16x16x32_bf16 v[102:105], v[42:45], v[138:141], v[102:105]
	v_mfma_f32_16x16x32_bf16 v[106:109], v[110:113], v[138:141], v[106:109]
	v_mfma_f32_16x16x32_bf16 v[32:35], v[46:49], v[150:153], v[32:35]
	v_mfma_f32_16x16x32_bf16 v[36:39], v[114:117], v[150:153], v[36:39]
	v_mfma_f32_16x16x32_bf16 v[122:125], v[46:49], v[126:129], v[122:125]
	v_mfma_f32_16x16x32_bf16 v[86:89], v[114:117], v[126:129], v[86:89]
	v_mfma_f32_16x16x32_bf16 v[94:97], v[46:49], v[134:137], v[94:97]
	v_mfma_f32_16x16x32_bf16 v[98:101], v[114:117], v[134:137], v[98:101]
	v_mfma_f32_16x16x32_bf16 v[102:105], v[46:49], v[142:145], v[102:105]
	v_mfma_f32_16x16x32_bf16 v[106:109], v[114:117], v[142:145], v[106:109]
	s_setprio 0
	s_setprio 1
	s_setprio 0
	s_barrier
	ds_read_b128 v[40:43], v73
	ds_read_b128 v[44:47], v73 offset:1024
	ds_read_b128 v[110:113], v73 offset:2048
	ds_read_b128 v[114:117], v73 offset:3072
	s_mov_b32 m0, s46
	v_lshl_add_u64 v[14:15], s[8:9], 0, v[14:15]
	ds_read_b128 v[118:121], v156
	ds_read_b128 v[126:129], v156 offset:1024
	ds_read_b128 v[130:133], v156 offset:2048
	ds_read_b128 v[134:137], v156 offset:3072
	ds_read_b128 v[138:141], v156 offset:4096
	ds_read_b128 v[142:145], v156 offset:5120
	ds_read_b128 v[146:149], v156 offset:6144
	ds_read_b128 v[150:153], v156 offset:7168
	global_load_lds_dwordx4 v[14:15], off
	v_lshl_add_u64 v[2:3], s[8:9], 0, v[2:3]
	s_mov_b32 m0, s45
	s_nop 0
	global_load_lds_dwordx4 v[2:3], off
	s_waitcnt vmcnt(8)
	s_waitcnt lgkmcnt(0)
	s_setprio 1
	s_barrier
	v_mfma_f32_16x16x32_bf16 v[48:51], v[110:113], v[118:121], v[50:53]
	v_mfma_f32_16x16x32_bf16 v[52:55], v[40:43], v[130:133], v[54:57]
	v_mfma_f32_16x16x32_bf16 v[56:59], v[110:113], v[130:133], v[58:61]
	v_mfma_f32_16x16x32_bf16 v[90:93], v[40:43], v[118:121], v[90:93]
	v_mfma_f32_16x16x32_bf16 v[118:121], v[114:117], v[134:137], v[56:59]
	v_mfma_f32_16x16x32_bf16 v[56:59], v[40:43], v[138:141], v[62:65]
	v_mfma_f32_16x16x32_bf16 v[90:93], v[44:47], v[126:129], v[90:93]
	v_mfma_f32_16x16x32_bf16 v[48:51], v[114:117], v[126:129], v[48:51]
	v_mfma_f32_16x16x32_bf16 v[126:129], v[44:47], v[142:145], v[56:59]
	v_mfma_f32_16x16x32_bf16 v[56:59], v[110:113], v[138:141], v[74:77]
	v_mfma_f32_16x16x32_bf16 v[74:77], v[114:117], v[142:145], v[56:59]
	v_mfma_f32_16x16x32_bf16 v[56:59], v[40:43], v[146:149], v[78:81]
	v_mfma_f32_16x16x32_bf16 v[52:55], v[44:47], v[134:137], v[52:55]
	v_mfma_f32_16x16x32_bf16 v[78:81], v[44:47], v[150:153], v[56:59]
	v_mfma_f32_16x16x32_bf16 v[56:59], v[110:113], v[146:149], v[82:85]
	v_mfma_f32_16x16x32_bf16 v[82:85], v[114:117], v[150:153], v[56:59]
	s_setprio 0
	s_setprio 1
	s_setprio 0
	s_barrier
; #define PG8_STAGE(bufoff, gbase, voff) do { _Pragma("unroll") for (int _i = 0; _i < 2; ++_i) \
;         __builtin_amdgcn_global_load_lds((const unsigned*)((const char*)(gbase) + (voff)[_i]), (PG8_LAS unsigned*)(lds + (bufoff) + ldsw + _i * 8192), 16, 0, 0); } while (0)
; #define PG8_LDA(dst, b, h) do { _Pragma("unroll") for (int m = 0; m < 4; ++m) _Pragma("unroll") for (int k = 0; k < 2; ++k) dst[m][k] = *(const PG8_LAS bf16x8*)(lds + PG8_SA(b, h) + aoff + m * 2048 + k * 1024); } while (0)
; #define PG8_LDB(dst, b, h) do { _Pragma("unroll") for (int n = 0; n < 2; ++n) _Pragma("unroll") for (int k = 0; k < 2; ++k) dst[n][k] = *(const PG8_LAS bf16x8*)(lds + PG8_SB(b, h) + boff + n * 2048 + k * 1024); } while (0)
; #define PG8_MMA(ai, bj, At, Bt) do { __builtin_amdgcn_s_setprio(1); _Pragma("unroll") for (int m = 0; m < 4; ++m) _Pragma("unroll") for (int n = 0; n < 2; ++n) _Pragma("unroll") for (int k = 0; k < 2; ++k) \
;         acc[ai][bj][m][n] = __builtin_amdgcn_mfma_f32_16x16x32_bf16(Bt[n][k], At[m][k], acc[ai][bj][m][n], 0, 0, 0); __builtin_amdgcn_s_setprio(0); } while (0)
; #define PG8_WAIT_V(n) asm volatile("s_waitcnt vmcnt(" #n ")" ::: "memory")
; #define PG8_WAIT_L(n) asm volatile("s_waitcnt lgkmcnt(" #n ")" ::: "memory")
; #define PG8_BAR __builtin_amdgcn_s_barrier()
; #define PG8_SCHED __builtin_amdgcn_sched_barrier(0)
; template <class Epi, class Sched, bool ALIGN_EPI = false, bool SP2 = false>
; __device__ __forceinline__ void gemm_phase(PG8_LAS unsigned char* lds, const Gemm g, const Sched& S, const Epi& E) {
;     ...
;             PG8_LDA(At, 0, 1); PG8_STAGE(PG8_SB(0, 0), b2, voffB); PG8_STAGE(PG8_SB(0, 1), b2 + hstepB, voffB); PG8_STAGE(PG8_SA(0, 0), a2, voffA);
;             PG8_WAIT_V(8); PG8_WAIT_L(0); PG8_BAR; PG8_MMA(1, 0, At, B0); PG8_MMA(1, 1, At, B1); PG8_BAR; PG8_SCHED;
;             PG8_LDB(B0, 1, 0); PG8_LDB(B1, 1, 1); PG8_SCHED; PG8_LDA(At, 1, 0); PG8_STAGE(PG8_SA(0, 1), a2 + hstepA, voffA);
;             PG8_WAIT_V(8); PG8_WAIT_L(0); PG8_BAR; PG8_MMA(0, 0, At, B0); PG8_MMA(0, 1, At, B1); PG8_BAR; PG8_SCHED;
;             PG8_LDA(At, 1, 1); PG8_STAGE(PG8_SB(1, 0), b3, voffB); PG8_STAGE(PG8_SB(1, 1), b3 + hstepB, voffB); PG8_STAGE(PG8_SA(1, 0), a3, voffA);
;             PG8_WAIT_V(8); PG8_WAIT_L(0); PG8_BAR; PG8_MMA(1, 0, At, B0); PG8_MMA(1, 1, At, B1); PG8_BAR; PG8_SCHED;
;     ...
;         if constexpr (ALIGN_EPI) { if (wr == 0) PG8_BAR; }
	s_mov_b32 m0, s44
	s_nop 1
	ds_read_b128 v[56:59], v156 offset:16384
	ds_read_b128 v[60:63], v156 offset:17408
	ds_read_b128 v[130:133], v156 offset:18432
	ds_read_b128 v[134:137], v156 offset:19456
	ds_read_b128 v[138:141], v156 offset:20480
	ds_read_b128 v[142:145], v156 offset:21504
	ds_read_b128 v[146:149], v156 offset:22528
	ds_read_b128 v[150:153], v156 offset:23552
	global_load_lds_dwordx4 v[4:5], off
	s_mov_b32 m0, s43
	s_nop 0
	global_load_lds_dwordx4 v[6:7], off
	s_mov_b32 m0, s29
	s_nop 0
	global_load_lds_dwordx4 v[8:9], off
	s_mov_b32 m0, s31
	s_nop 0
	global_load_lds_dwordx4 v[10:11], off
	s_mov_b32 m0, s27
	s_nop 0
	global_load_lds_dwordx4 v[18:19], off
	s_mov_b32 m0, s35
	s_nop 0
	global_load_lds_dwordx4 v[22:23], off
	s_waitcnt vmcnt(8)
	s_waitcnt lgkmcnt(0)
	s_setprio 1
	s_barrier
	v_mfma_f32_16x16x32_bf16 v[2:5], v[40:43], v[56:59], v[122:125]
	v_mfma_f32_16x16x32_bf16 v[6:9], v[110:113], v[56:59], v[86:89]
	v_mfma_f32_16x16x32_bf16 v[56:59], v[110:113], v[130:133], v[98:101]
	v_mfma_f32_16x16x32_bf16 v[18:21], v[40:43], v[130:133], v[94:97]
	v_mfma_f32_16x16x32_bf16 v[86:89], v[114:117], v[134:137], v[56:59]
	v_mfma_f32_16x16x32_bf16 v[56:59], v[40:43], v[138:141], v[102:105]
	v_mfma_f32_16x16x32_bf16 v[32:35], v[40:43], v[146:149], v[32:35]
	v_mfma_f32_16x16x32_bf16 v[2:5], v[44:47], v[60:63], v[2:5]
	v_mfma_f32_16x16x32_bf16 v[6:9], v[114:117], v[60:63], v[6:9]
	v_mfma_f32_16x16x32_bf16 v[18:21], v[44:47], v[134:137], v[18:21]
	v_mfma_f32_16x16x32_bf16 v[94:97], v[44:47], v[142:145], v[56:59]
	v_mfma_f32_16x16x32_bf16 v[56:59], v[110:113], v[138:141], v[106:109]
	v_mfma_f32_16x16x32_bf16 v[102:105], v[44:47], v[150:153], v[32:35]
	v_mfma_f32_16x16x32_bf16 v[32:35], v[110:113], v[146:149], v[36:39]
	v_mfma_f32_16x16x32_bf16 v[98:101], v[114:117], v[142:145], v[56:59]
	v_mfma_f32_16x16x32_bf16 v[106:109], v[114:117], v[150:153], v[32:35]
	s_setprio 0
	s_setprio 1
	s_setprio 0
	s_barrier
	ds_read_b128 v[110:113], v157
	ds_read_b128 v[114:117], v157 offset:1024
	ds_read_b128 v[122:125], v157 offset:2048
	ds_read_b128 v[130:133], v157 offset:3072
	s_mov_b32 m0, s30
	ds_read_b128 v[32:35], v156 offset:32768
	ds_read_b128 v[36:39], v156 offset:33792
	ds_read_b128 v[40:43], v156 offset:34816
	ds_read_b128 v[44:47], v156 offset:35840
	ds_read_b128 v[134:137], v156 offset:36864
	ds_read_b128 v[138:141], v156 offset:37888
	ds_read_b128 v[142:145], v156 offset:38912
	ds_read_b128 v[146:149], v156 offset:39936
	global_load_lds_dwordx4 v[12:13], off
	s_mov_b32 m0, s34
	s_nop 0
	global_load_lds_dwordx4 v[16:17], off
	s_waitcnt vmcnt(8)
	s_waitcnt lgkmcnt(0)
	s_setprio 1
	s_barrier
	v_mfma_f32_16x16x32_bf16 v[10:13], v[110:113], v[32:35], v[90:93]
	v_mfma_f32_16x16x32_bf16 v[58:61], v[114:117], v[36:39], v[10:13]
	v_mfma_f32_16x16x32_bf16 v[10:13], v[122:125], v[32:35], v[48:51]
	v_mfma_f32_16x16x32_bf16 v[62:65], v[130:133], v[36:39], v[10:13]
	v_mfma_f32_16x16x32_bf16 v[10:13], v[110:113], v[40:43], v[52:55]
	v_mfma_f32_16x16x32_bf16 v[50:53], v[114:117], v[44:47], v[10:13]
	v_mfma_f32_16x16x32_bf16 v[10:13], v[122:125], v[40:43], v[118:121]
	v_mfma_f32_16x16x32_bf16 v[54:57], v[130:133], v[44:47], v[10:13]
	v_mfma_f32_16x16x32_bf16 v[10:13], v[110:113], v[134:137], v[126:129]
	v_mfma_f32_16x16x32_bf16 v[42:45], v[114:117], v[138:141], v[10:13]
	v_mfma_f32_16x16x32_bf16 v[10:13], v[122:125], v[134:137], v[74:77]
	v_mfma_f32_16x16x32_bf16 v[46:49], v[130:133], v[138:141], v[10:13]
	v_mfma_f32_16x16x32_bf16 v[10:13], v[110:113], v[142:145], v[78:81]
	v_mfma_f32_16x16x32_bf16 v[34:37], v[114:117], v[146:149], v[10:13]
	v_mfma_f32_16x16x32_bf16 v[10:13], v[122:125], v[142:145], v[82:85]
	v_mfma_f32_16x16x32_bf16 v[38:41], v[130:133], v[146:149], v[10:13]
	s_setprio 0
	s_setprio 1
	s_setprio 0
	s_barrier
	s_mov_b32 m0, s36
	s_nop 1
	ds_read_b128 v[10:13], v156 offset:49152
	ds_read_b128 v[14:17], v156 offset:50176
	ds_read_b128 v[74:77], v156 offset:51200
	ds_read_b128 v[78:81], v156 offset:52224
	ds_read_b128 v[82:85], v156 offset:53248
	ds_read_b128 v[90:93], v156 offset:54272
	ds_read_b128 v[118:121], v156 offset:55296
	ds_read_b128 v[126:129], v156 offset:56320
	global_load_lds_dwordx4 v[26:27], off
	s_mov_b32 m0, s38
	s_nop 0
	global_load_lds_dwordx4 v[28:29], off
	s_mov_b32 m0, s40
	s_nop 0
	global_load_lds_dwordx4 v[68:69], off
	s_mov_b32 m0, s41
	s_nop 0
	global_load_lds_dwordx4 v[70:71], off
	s_mov_b32 m0, s37
	s_nop 0
	global_load_lds_dwordx4 v[24:25], off
	s_mov_b32 m0, s39
	s_nop 0
	global_load_lds_dwordx4 v[30:31], off
	s_waitcnt vmcnt(8)
	s_waitcnt lgkmcnt(0)
	s_setprio 1
	s_barrier
	v_mfma_f32_16x16x32_bf16 v[2:5], v[110:113], v[10:13], v[2:5]
	v_mfma_f32_16x16x32_bf16 v[26:29], v[114:117], v[14:17], v[2:5]
	v_mfma_f32_16x16x32_bf16 v[2:5], v[122:125], v[10:13], v[6:9]
	v_mfma_f32_16x16x32_bf16 v[30:33], v[130:133], v[14:17], v[2:5]
	v_mfma_f32_16x16x32_bf16 v[2:5], v[110:113], v[74:77], v[18:21]
	v_mfma_f32_16x16x32_bf16 v[18:21], v[114:117], v[78:81], v[2:5]
	v_mfma_f32_16x16x32_bf16 v[2:5], v[122:125], v[74:77], v[86:89]
	v_mfma_f32_16x16x32_bf16 v[22:25], v[130:133], v[78:81], v[2:5]
	v_mfma_f32_16x16x32_bf16 v[2:5], v[110:113], v[82:85], v[94:97]
	v_mfma_f32_16x16x32_bf16 v[10:13], v[114:117], v[90:93], v[2:5]
	v_mfma_f32_16x16x32_bf16 v[2:5], v[122:125], v[82:85], v[98:101]
	v_mfma_f32_16x16x32_bf16 v[14:17], v[130:133], v[90:93], v[2:5]
	v_mfma_f32_16x16x32_bf16 v[2:5], v[110:113], v[118:121], v[102:105]
	v_mfma_f32_16x16x32_bf16 v[6:9], v[122:125], v[118:121], v[106:109]
	v_mfma_f32_16x16x32_bf16 v[2:5], v[114:117], v[126:129], v[2:5]
	v_mfma_f32_16x16x32_bf16 v[6:9], v[130:133], v[126:129], v[6:9]
	s_setprio 0
	s_setprio 1
	s_setprio 0
	s_barrier
	s_cbranch_scc1 .LBB0_594
	s_barrier

; #define PG8_STAGE(bufoff, gbase, voff) do { _Pragma("unroll") for (int _i = 0; _i < 2; ++_i) \
;         __builtin_amdgcn_global_load_lds((const unsigned*)((const char*)(gbase) + (voff)[_i]), (PG8_LAS unsigned*)(lds + (bufoff) + ldsw + _i * 8192), 16, 0, 0); } while (0)
; #define PG8_LDA(dst, b, h) do { _Pragma("unroll") for (int m = 0; m < 4; ++m) _Pragma("unroll") for (int k = 0; k < 2; ++k) dst[m][k] = *(const PG8_LAS bf16x8*)(lds + PG8_SA(b, h) + aoff + m * 2048 + k * 1024); } while (0)
; #define PG8_LDB(dst, b, h) do { _Pragma("unroll") for (int n = 0; n < 2; ++n) _Pragma("unroll") for (int k = 0; k < 2; ++k) dst[n][k] = *(const PG8_LAS bf16x8*)(lds + PG8_SB(b, h) + boff + n * 2048 + k * 1024); } while (0)
; #define PG8_MMA(ai, bj, At, Bt) do { __builtin_amdgcn_s_setprio(1); _Pragma("unroll") for (int m = 0; m < 4; ++m) _Pragma("unroll") for (int n = 0; n < 2; ++n) _Pragma("unroll") for (int k = 0; k < 2; ++k) \
;         acc[ai][bj][m][n] = __builtin_amdgcn_mfma_f32_16x16x32_bf16(Bt[n][k], At[m][k], acc[ai][bj][m][n], 0, 0, 0); __builtin_amdgcn_s_setprio(0); } while (0)
; #define PG8_WAIT_V(n) asm volatile("s_waitcnt vmcnt(" #n ")" ::: "memory")
; #define PG8_WAIT_L(n) asm volatile("s_waitcnt lgkmcnt(" #n ")" ::: "memory")
; #define PG8_BAR __builtin_amdgcn_s_barrier()
; #define PG8_SCHED __builtin_amdgcn_sched_barrier(0)
; template <class Epi, class Sched, bool ALIGN_EPI = false, bool SP2 = false>
; __device__ __forceinline__ void gemm_phase(PG8_LAS unsigned char* lds, const Gemm g, const Sched& S, const Epi& E) {
;     ...
;             PG8_LDB(B0, 0, 0); PG8_LDB(B1, 0, 1); PG8_SCHED; PG8_LDA(At, 0, 0); PG8_STAGE(PG8_SA(1, 1), a1 + hstepA, voffA);
;             PG8_WAIT_V(8); PG8_WAIT_L(0); PG8_BAR; PG8_MMA(0, 0, At, B0); PG8_MMA(0, 1, At, B1); PG8_BAR; PG8_SCHED;
;             PG8_LDA(At, 0, 1); PG8_STAGE(PG8_SB(0, 0), b2, voffB); PG8_STAGE(PG8_SB(0, 1), b2 + hstepB, voffB); PG8_STAGE(PG8_SA(0, 0), a2, voffA);
.LBB0_1160:
	s_add_u32 s24, s22, 0x100
	s_addc_u32 s25, s23, 0
	s_add_i32 s57, 0, 0x10000
	s_cmp_eq_u32 s56, 4
	s_cselect_b32 s29, s17, s25
	s_cselect_b32 s28, s16, s24
	v_add_u32_e32 v145, s57, v142
	s_cselect_b32 s27, s52, s55
	s_cselect_b32 s26, s53, s54
	s_add_i32 s58, 0, 0x14000
	ds_read_b128 v[146:149], v145
	ds_read_b128 v[150:153], v145 offset:1024
	ds_read_b128 v[154:157], v145 offset:2048
	ds_read_b128 v[158:161], v145 offset:3072
	v_add_u32_e32 v145, s58, v142
	ds_read_b128 v[162:165], v145
	ds_read_b128 v[166:169], v145 offset:1024
	ds_read_b128 v[170:173], v145 offset:2048
	ds_read_b128 v[174:177], v145 offset:3072
	s_add_i32 m0, s39, 0xc000
	ds_read_b128 v[178:181], v143
	ds_read_b128 v[182:185], v143 offset:1024
	ds_read_b128 v[202:205], v143 offset:2048
	ds_read_b128 v[206:209], v143 offset:3072
	ds_read_b128 v[210:213], v143 offset:4096
	ds_read_b128 v[232:235], v143 offset:5120
	ds_read_b128 v[236:239], v143 offset:6144
	ds_read_b128 v[240:243], v143 offset:7168
	global_load_lds_dwordx4 v138, s[22:23]
	s_add_i32 m0, s39, 0xe000
	s_nop 0
	global_load_lds_dwordx4 v140, s[22:23]
	s_waitcnt vmcnt(8)
	s_waitcnt lgkmcnt(0)
	s_setprio 1
	s_barrier
	v_mfma_f32_16x16x32_bf16 v[126:129], v[146:149], v[178:181], v[126:129]
	v_mfma_f32_16x16x32_bf16 v[122:125], v[154:157], v[178:181], v[122:125]
	v_mfma_f32_16x16x32_bf16 v[118:121], v[146:149], v[202:205], v[118:121]
	v_mfma_f32_16x16x32_bf16 v[114:117], v[154:157], v[202:205], v[114:117]
	v_mfma_f32_16x16x32_bf16 v[110:113], v[146:149], v[210:213], v[110:113]
	v_mfma_f32_16x16x32_bf16 v[106:109], v[154:157], v[210:213], v[106:109]
	v_mfma_f32_16x16x32_bf16 v[102:105], v[146:149], v[236:239], v[102:105]
	v_mfma_f32_16x16x32_bf16 v[98:101], v[154:157], v[236:239], v[98:101]
	v_mfma_f32_16x16x32_bf16 v[126:129], v[150:153], v[182:185], v[126:129]
	v_mfma_f32_16x16x32_bf16 v[122:125], v[158:161], v[182:185], v[122:125]
	v_mfma_f32_16x16x32_bf16 v[118:121], v[150:153], v[206:209], v[118:121]
	v_mfma_f32_16x16x32_bf16 v[114:117], v[158:161], v[206:209], v[114:117]
	v_mfma_f32_16x16x32_bf16 v[110:113], v[150:153], v[232:235], v[110:113]
	v_mfma_f32_16x16x32_bf16 v[106:109], v[158:161], v[232:235], v[106:109]
	v_mfma_f32_16x16x32_bf16 v[102:105], v[150:153], v[240:243], v[102:105]
	v_mfma_f32_16x16x32_bf16 v[98:101], v[158:161], v[240:243], v[98:101]
	s_setprio 0
	s_setprio 1
	v_mfma_f32_16x16x32_bf16 v[78:81], v[162:165], v[178:181], v[78:81]
	v_mfma_f32_16x16x32_bf16 v[70:73], v[170:173], v[178:181], v[70:73]
	v_mfma_f32_16x16x32_bf16 v[62:65], v[162:165], v[202:205], v[62:65]
	v_mfma_f32_16x16x32_bf16 v[54:57], v[170:173], v[202:205], v[54:57]
	v_mfma_f32_16x16x32_bf16 v[46:49], v[162:165], v[210:213], v[46:49]
	v_mfma_f32_16x16x32_bf16 v[42:45], v[170:173], v[210:213], v[42:45]
	v_mfma_f32_16x16x32_bf16 v[38:41], v[162:165], v[236:239], v[38:41]
	v_mfma_f32_16x16x32_bf16 v[34:37], v[170:173], v[236:239], v[34:37]
	v_mfma_f32_16x16x32_bf16 v[78:81], v[166:169], v[182:185], v[78:81]
	v_mfma_f32_16x16x32_bf16 v[70:73], v[174:177], v[182:185], v[70:73]
	v_mfma_f32_16x16x32_bf16 v[62:65], v[166:169], v[206:209], v[62:65]
	v_mfma_f32_16x16x32_bf16 v[54:57], v[174:177], v[206:209], v[54:57]
	v_mfma_f32_16x16x32_bf16 v[46:49], v[166:169], v[232:235], v[46:49]
	v_mfma_f32_16x16x32_bf16 v[42:45], v[174:177], v[232:235], v[42:45]
	v_mfma_f32_16x16x32_bf16 v[38:41], v[166:169], v[240:243], v[38:41]
	v_mfma_f32_16x16x32_bf16 v[34:37], v[174:177], v[240:243], v[34:37]
	s_setprio 0
	s_barrier
	s_add_i32 s22, s57, s38
	s_mov_b32 m0, s22
	ds_read_b128 v[178:181], v143 offset:16384
	ds_read_b128 v[182:185], v143 offset:17408
	ds_read_b128 v[202:205], v143 offset:18432
	ds_read_b128 v[206:209], v143 offset:19456
	ds_read_b128 v[210:213], v143 offset:20480
	ds_read_b128 v[232:235], v143 offset:21504
	ds_read_b128 v[236:239], v143 offset:22528
	ds_read_b128 v[240:243], v143 offset:23552
	s_add_u32 s60, s26, 0x80
	s_addc_u32 s61, s27, 0
	s_add_u32 s62, s28, 0x80
	s_addc_u32 s63, s29, 0
	global_load_lds_dwordx4 v134, s[26:27]
	s_add_i32 m0, s22, 0x2000
	s_add_u32 s22, s26, 0x20000
	s_addc_u32 s23, s27, 0
	s_add_i32 s57, s58, s38
	global_load_lds_dwordx4 v130, s[26:27]
	s_mov_b32 m0, s57
	s_nop 0
	global_load_lds_dwordx4 v134, s[22:23]
	s_add_i32 m0, s57, 0x2000
	s_nop 0
	global_load_lds_dwordx4 v130, s[22:23]
	s_mov_b32 m0, s39
	s_nop 0
	global_load_lds_dwordx4 v136, s[28:29]
	s_mov_b32 m0, s40
	s_nop 0
	global_load_lds_dwordx4 v132, s[28:29]
	s_waitcnt vmcnt(8)
	s_waitcnt lgkmcnt(0)
	s_setprio 1
	s_barrier
; #define PG8_STAGE(bufoff, gbase, voff) do { _Pragma("unroll") for (int _i = 0; _i < 2; ++_i) \
;         __builtin_amdgcn_global_load_lds((const unsigned*)((const char*)(gbase) + (voff)[_i]), (PG8_LAS unsigned*)(lds + (bufoff) + ldsw + _i * 8192), 16, 0, 0); } while (0)
; #define PG8_LDA(dst, b, h) do { _Pragma("unroll") for (int m = 0; m < 4; ++m) _Pragma("unroll") for (int k = 0; k < 2; ++k) dst[m][k] = *(const PG8_LAS bf16x8*)(lds + PG8_SA(b, h) + aoff + m * 2048 + k * 1024); } while (0)
; #define PG8_LDB(dst, b, h) do { _Pragma("unroll") for (int n = 0; n < 2; ++n) _Pragma("unroll") for (int k = 0; k < 2; ++k) dst[n][k] = *(const PG8_LAS bf16x8*)(lds + PG8_SB(b, h) + boff + n * 2048 + k * 1024); } while (0)
; #define PG8_MMA(ai, bj, At, Bt) do { __builtin_amdgcn_s_setprio(1); _Pragma("unroll") for (int m = 0; m < 4; ++m) _Pragma("unroll") for (int n = 0; n < 2; ++n) _Pragma("unroll") for (int k = 0; k < 2; ++k) \
;         acc[ai][bj][m][n] = __builtin_amdgcn_mfma_f32_16x16x32_bf16(Bt[n][k], At[m][k], acc[ai][bj][m][n], 0, 0, 0); __builtin_amdgcn_s_setprio(0); } while (0)
; #define PG8_WAIT_V(n) asm volatile("s_waitcnt vmcnt(" #n ")" ::: "memory")
; #define PG8_WAIT_L(n) asm volatile("s_waitcnt lgkmcnt(" #n ")" ::: "memory")
; #define PG8_BAR __builtin_amdgcn_s_barrier()
; #define PG8_SCHED __builtin_amdgcn_sched_barrier(0)
; template <class Epi, class Sched, bool ALIGN_EPI = false, bool SP2 = false>
; __device__ __forceinline__ void gemm_phase(PG8_LAS unsigned char* lds, const Gemm g, const Sched& S, const Epi& E) {
;     ...
;             PG8_WAIT_V(8); PG8_WAIT_L(0); PG8_BAR; PG8_MMA(1, 0, At, B0); PG8_MMA(1, 1, At, B1); PG8_BAR; PG8_SCHED;
;             PG8_LDB(B0, 1, 0); PG8_LDB(B1, 1, 1); PG8_SCHED; PG8_LDA(At, 1, 0); PG8_STAGE(PG8_SA(0, 1), a2 + hstepA, voffA);
;             PG8_WAIT_V(8); PG8_WAIT_L(0); PG8_BAR; PG8_MMA(0, 0, At, B0); PG8_MMA(0, 1, At, B1); PG8_BAR; PG8_SCHED;
	v_mfma_f32_16x16x32_bf16 v[94:97], v[146:149], v[178:181], v[94:97]
	v_mfma_f32_16x16x32_bf16 v[90:93], v[154:157], v[178:181], v[90:93]
	v_mfma_f32_16x16x32_bf16 v[86:89], v[146:149], v[202:205], v[86:89]
	v_mfma_f32_16x16x32_bf16 v[82:85], v[154:157], v[202:205], v[82:85]
	v_mfma_f32_16x16x32_bf16 v[74:77], v[146:149], v[210:213], v[74:77]
	v_mfma_f32_16x16x32_bf16 v[66:69], v[154:157], v[210:213], v[66:69]
	v_mfma_f32_16x16x32_bf16 v[58:61], v[146:149], v[236:239], v[58:61]
	v_mfma_f32_16x16x32_bf16 v[50:53], v[154:157], v[236:239], v[50:53]
	v_mfma_f32_16x16x32_bf16 v[94:97], v[150:153], v[182:185], v[94:97]
	v_mfma_f32_16x16x32_bf16 v[90:93], v[158:161], v[182:185], v[90:93]
	v_mfma_f32_16x16x32_bf16 v[86:89], v[150:153], v[206:209], v[86:89]
	v_mfma_f32_16x16x32_bf16 v[82:85], v[158:161], v[206:209], v[82:85]
	v_mfma_f32_16x16x32_bf16 v[74:77], v[150:153], v[232:235], v[74:77]
	v_mfma_f32_16x16x32_bf16 v[66:69], v[158:161], v[232:235], v[66:69]
	v_mfma_f32_16x16x32_bf16 v[58:61], v[150:153], v[240:243], v[58:61]
	v_mfma_f32_16x16x32_bf16 v[50:53], v[158:161], v[240:243], v[50:53]
	s_setprio 0
	s_setprio 1
	v_mfma_f32_16x16x32_bf16 v[30:33], v[162:165], v[178:181], v[30:33]
	v_mfma_f32_16x16x32_bf16 v[26:29], v[170:173], v[178:181], v[26:29]
	v_mfma_f32_16x16x32_bf16 v[22:25], v[162:165], v[202:205], v[22:25]
	v_mfma_f32_16x16x32_bf16 v[18:21], v[170:173], v[202:205], v[18:21]
	v_mfma_f32_16x16x32_bf16 v[14:17], v[162:165], v[210:213], v[14:17]
	v_mfma_f32_16x16x32_bf16 v[10:13], v[170:173], v[210:213], v[10:13]
	v_mfma_f32_16x16x32_bf16 v[6:9], v[162:165], v[236:239], v[6:9]
	v_mfma_f32_16x16x32_bf16 v[2:5], v[170:173], v[236:239], v[2:5]
	v_mfma_f32_16x16x32_bf16 v[30:33], v[166:169], v[182:185], v[30:33]
	v_mfma_f32_16x16x32_bf16 v[26:29], v[174:177], v[182:185], v[26:29]
	v_mfma_f32_16x16x32_bf16 v[22:25], v[166:169], v[206:209], v[22:25]
	v_mfma_f32_16x16x32_bf16 v[18:21], v[174:177], v[206:209], v[18:21]
	v_mfma_f32_16x16x32_bf16 v[14:17], v[166:169], v[232:235], v[14:17]
	v_mfma_f32_16x16x32_bf16 v[10:13], v[174:177], v[232:235], v[10:13]
	v_mfma_f32_16x16x32_bf16 v[6:9], v[166:169], v[240:243], v[6:9]
	v_mfma_f32_16x16x32_bf16 v[2:5], v[174:177], v[240:243], v[2:5]
	s_setprio 0
	s_barrier
	s_add_i32 s57, 0, 0x18000
	v_add_u32_e32 v145, s57, v142
	s_add_i32 s58, 0, 0x1c000
	ds_read_b128 v[146:149], v145
	ds_read_b128 v[150:153], v145 offset:1024
	ds_read_b128 v[154:157], v145 offset:2048
	ds_read_b128 v[158:161], v145 offset:3072
	v_add_u32_e32 v145, s58, v142
	ds_read_b128 v[162:165], v145
	ds_read_b128 v[166:169], v145 offset:1024
	ds_read_b128 v[170:173], v145 offset:2048
	ds_read_b128 v[174:177], v145 offset:3072
	s_add_u32 s22, s28, 0x30000
	s_addc_u32 s23, s29, 0
	s_mov_b32 m0, s41
	ds_read_b128 v[178:181], v143 offset:32768
	ds_read_b128 v[182:185], v143 offset:33792
	ds_read_b128 v[202:205], v143 offset:34816
	ds_read_b128 v[206:209], v143 offset:35840
	ds_read_b128 v[210:213], v143 offset:36864
	ds_read_b128 v[232:235], v143 offset:37888
	ds_read_b128 v[236:239], v143 offset:38912
	ds_read_b128 v[240:243], v143 offset:39936
	global_load_lds_dwordx4 v136, s[22:23]
	s_mov_b32 m0, s42
	s_nop 0
	global_load_lds_dwordx4 v132, s[22:23]
	s_waitcnt vmcnt(8)
	s_waitcnt lgkmcnt(0)
	s_setprio 1
	s_barrier
	v_mfma_f32_16x16x32_bf16 v[126:129], v[146:149], v[178:181], v[126:129]
	v_mfma_f32_16x16x32_bf16 v[122:125], v[154:157], v[178:181], v[122:125]
	v_mfma_f32_16x16x32_bf16 v[118:121], v[146:149], v[202:205], v[118:121]
	v_mfma_f32_16x16x32_bf16 v[114:117], v[154:157], v[202:205], v[114:117]
	v_mfma_f32_16x16x32_bf16 v[110:113], v[146:149], v[210:213], v[110:113]
	v_mfma_f32_16x16x32_bf16 v[106:109], v[154:157], v[210:213], v[106:109]
	v_mfma_f32_16x16x32_bf16 v[102:105], v[146:149], v[236:239], v[102:105]
	v_mfma_f32_16x16x32_bf16 v[98:101], v[154:157], v[236:239], v[98:101]
	v_mfma_f32_16x16x32_bf16 v[126:129], v[150:153], v[182:185], v[126:129]
	v_mfma_f32_16x16x32_bf16 v[122:125], v[158:161], v[182:185], v[122:125]
	v_mfma_f32_16x16x32_bf16 v[118:121], v[150:153], v[206:209], v[118:121]
	v_mfma_f32_16x16x32_bf16 v[114:117], v[158:161], v[206:209], v[114:117]
	v_mfma_f32_16x16x32_bf16 v[110:113], v[150:153], v[232:235], v[110:113]
	v_mfma_f32_16x16x32_bf16 v[106:109], v[158:161], v[232:235], v[106:109]
	v_mfma_f32_16x16x32_bf16 v[102:105], v[150:153], v[240:243], v[102:105]
	v_mfma_f32_16x16x32_bf16 v[98:101], v[158:161], v[240:243], v[98:101]
	s_setprio 0
	s_setprio 1
	v_mfma_f32_16x16x32_bf16 v[78:81], v[162:165], v[178:181], v[78:81]
	v_mfma_f32_16x16x32_bf16 v[70:73], v[170:173], v[178:181], v[70:73]
	v_mfma_f32_16x16x32_bf16 v[62:65], v[162:165], v[202:205], v[62:65]
	v_mfma_f32_16x16x32_bf16 v[54:57], v[170:173], v[202:205], v[54:57]
	v_mfma_f32_16x16x32_bf16 v[46:49], v[162:165], v[210:213], v[46:49]
	v_mfma_f32_16x16x32_bf16 v[42:45], v[170:173], v[210:213], v[42:45]
	v_mfma_f32_16x16x32_bf16 v[38:41], v[162:165], v[236:239], v[38:41]
	v_mfma_f32_16x16x32_bf16 v[34:37], v[170:173], v[236:239], v[34:37]
	v_mfma_f32_16x16x32_bf16 v[78:81], v[166:169], v[182:185], v[78:81]
	v_mfma_f32_16x16x32_bf16 v[70:73], v[174:177], v[182:185], v[70:73]
	v_mfma_f32_16x16x32_bf16 v[62:65], v[166:169], v[206:209], v[62:65]
	v_mfma_f32_16x16x32_bf16 v[54:57], v[174:177], v[206:209], v[54:57]
	v_mfma_f32_16x16x32_bf16 v[46:49], v[166:169], v[232:235], v[46:49]
	v_mfma_f32_16x16x32_bf16 v[42:45], v[174:177], v[232:235], v[42:45]
	v_mfma_f32_16x16x32_bf16 v[38:41], v[166:169], v[240:243], v[38:41]
	v_mfma_f32_16x16x32_bf16 v[34:37], v[174:177], v[240:243], v[34:37]
	s_setprio 0
	s_barrier
; #define PG8_STAGE(bufoff, gbase, voff) do { _Pragma("unroll") for (int _i = 0; _i < 2; ++_i) \
;         __builtin_amdgcn_global_load_lds((const unsigned*)((const char*)(gbase) + (voff)[_i]), (PG8_LAS unsigned*)(lds + (bufoff) + ldsw + _i * 8192), 16, 0, 0); } while (0)
; #define PG8_LDA(dst, b, h) do { _Pragma("unroll") for (int m = 0; m < 4; ++m) _Pragma("unroll") for (int k = 0; k < 2; ++k) dst[m][k] = *(const PG8_LAS bf16x8*)(lds + PG8_SA(b, h) + aoff + m * 2048 + k * 1024); } while (0)
; #define PG8_MMA(ai, bj, At, Bt) do { __builtin_amdgcn_s_setprio(1); _Pragma("unroll") for (int m = 0; m < 4; ++m) _Pragma("unroll") for (int n = 0; n < 2; ++n) _Pragma("unroll") for (int k = 0; k < 2; ++k) \
;         acc[ai][bj][m][n] = __builtin_amdgcn_mfma_f32_16x16x32_bf16(Bt[n][k], At[m][k], acc[ai][bj][m][n], 0, 0, 0); __builtin_amdgcn_s_setprio(0); } while (0)
; #define PG8_WAIT_V(n) asm volatile("s_waitcnt vmcnt(" #n ")" ::: "memory")
; #define PG8_WAIT_L(n) asm volatile("s_waitcnt lgkmcnt(" #n ")" ::: "memory")
; #define PG8_BAR __builtin_amdgcn_s_barrier()
; #define PG8_SCHED __builtin_amdgcn_sched_barrier(0)
; template <class Epi, class Sched, bool ALIGN_EPI = false, bool SP2 = false>
; __device__ __forceinline__ void gemm_phase(PG8_LAS unsigned char* lds, const Gemm g, const Sched& S, const Epi& E) {
;     ...
;         for (int t = 0; t < nt; t += 2) {
;             const bool last = (t == nt - 2);
;     ...
;             PG8_LDA(At, 1, 1); PG8_STAGE(PG8_SB(1, 0), b3, voffB); PG8_STAGE(PG8_SB(1, 1), b3 + hstepB, voffB); PG8_STAGE(PG8_SA(1, 0), a3, voffA);
;             PG8_WAIT_V(8); PG8_WAIT_L(0); PG8_BAR; PG8_MMA(1, 0, At, B0); PG8_MMA(1, 1, At, B1); PG8_BAR; PG8_SCHED;
	s_add_i32 s22, s57, s38
	s_mov_b32 m0, s22
	ds_read_b128 v[178:181], v143 offset:49152
	ds_read_b128 v[182:185], v143 offset:50176
	ds_read_b128 v[202:205], v143 offset:51200
	ds_read_b128 v[206:209], v143 offset:52224
	ds_read_b128 v[210:213], v143 offset:53248
	ds_read_b128 v[232:235], v143 offset:54272
	ds_read_b128 v[236:239], v143 offset:55296
	ds_read_b128 v[240:243], v143 offset:56320
	global_load_lds_dwordx4 v134, s[60:61]
	s_add_i32 m0, s22, 0x2000
	s_add_u32 s22, s26, 0x20080
	s_addc_u32 s23, s27, 0
	s_add_i32 s26, s58, s38
	global_load_lds_dwordx4 v130, s[60:61]
	s_mov_b32 m0, s26
	s_nop 0
	global_load_lds_dwordx4 v134, s[22:23]
	s_add_i32 m0, s26, 0x2000
	s_nop 0
	global_load_lds_dwordx4 v130, s[22:23]
	s_mov_b32 m0, s43
	s_nop 0
	global_load_lds_dwordx4 v136, s[62:63]
	s_mov_b32 m0, s46
	s_nop 0
	global_load_lds_dwordx4 v132, s[62:63]
	s_waitcnt vmcnt(8)
	s_waitcnt lgkmcnt(0)
	s_setprio 1
	s_barrier
	v_mfma_f32_16x16x32_bf16 v[94:97], v[146:149], v[178:181], v[94:97]
	v_mfma_f32_16x16x32_bf16 v[90:93], v[154:157], v[178:181], v[90:93]
	v_mfma_f32_16x16x32_bf16 v[86:89], v[146:149], v[202:205], v[86:89]
	v_mfma_f32_16x16x32_bf16 v[82:85], v[154:157], v[202:205], v[82:85]
	v_mfma_f32_16x16x32_bf16 v[74:77], v[146:149], v[210:213], v[74:77]
	v_mfma_f32_16x16x32_bf16 v[66:69], v[154:157], v[210:213], v[66:69]
	v_mfma_f32_16x16x32_bf16 v[58:61], v[146:149], v[236:239], v[58:61]
	v_mfma_f32_16x16x32_bf16 v[50:53], v[154:157], v[236:239], v[50:53]
	v_mfma_f32_16x16x32_bf16 v[94:97], v[150:153], v[182:185], v[94:97]
	v_mfma_f32_16x16x32_bf16 v[90:93], v[158:161], v[182:185], v[90:93]
	v_mfma_f32_16x16x32_bf16 v[86:89], v[150:153], v[206:209], v[86:89]
	v_mfma_f32_16x16x32_bf16 v[82:85], v[158:161], v[206:209], v[82:85]
	v_mfma_f32_16x16x32_bf16 v[74:77], v[150:153], v[232:235], v[74:77]
	v_mfma_f32_16x16x32_bf16 v[66:69], v[158:161], v[232:235], v[66:69]
	v_mfma_f32_16x16x32_bf16 v[58:61], v[150:153], v[240:243], v[58:61]
	v_mfma_f32_16x16x32_bf16 v[50:53], v[158:161], v[240:243], v[50:53]
	s_setprio 0
	s_setprio 1
	v_mfma_f32_16x16x32_bf16 v[30:33], v[162:165], v[178:181], v[30:33]
	v_mfma_f32_16x16x32_bf16 v[26:29], v[170:173], v[178:181], v[26:29]
	v_mfma_f32_16x16x32_bf16 v[22:25], v[162:165], v[202:205], v[22:25]
	v_mfma_f32_16x16x32_bf16 v[18:21], v[170:173], v[202:205], v[18:21]
	v_mfma_f32_16x16x32_bf16 v[14:17], v[162:165], v[210:213], v[14:17]
	v_mfma_f32_16x16x32_bf16 v[10:13], v[170:173], v[210:213], v[10:13]
	v_mfma_f32_16x16x32_bf16 v[6:9], v[162:165], v[236:239], v[6:9]
	v_mfma_f32_16x16x32_bf16 v[2:5], v[170:173], v[236:239], v[2:5]
	v_mfma_f32_16x16x32_bf16 v[30:33], v[166:169], v[182:185], v[30:33]
	v_mfma_f32_16x16x32_bf16 v[26:29], v[174:177], v[182:185], v[26:29]
	v_mfma_f32_16x16x32_bf16 v[22:25], v[166:169], v[206:209], v[22:25]
	v_mfma_f32_16x16x32_bf16 v[18:21], v[174:177], v[206:209], v[18:21]
	v_mfma_f32_16x16x32_bf16 v[14:17], v[166:169], v[232:235], v[14:17]
	v_mfma_f32_16x16x32_bf16 v[10:13], v[174:177], v[232:235], v[10:13]
	v_mfma_f32_16x16x32_bf16 v[6:9], v[166:169], v[240:243], v[6:9]
	v_mfma_f32_16x16x32_bf16 v[2:5], v[174:177], v[240:243], v[2:5]
	s_setprio 0
	s_barrier
	s_add_i32 s56, s56, 2
	s_add_u32 s54, s54, 0x100
	s_addc_u32 s55, s55, 0
	s_cmp_gt_u32 s56, 5
	s_mov_b64 s[22:23], s[24:25]
	s_cbranch_scc0 .LBB0_1160
	s_and_b64 vcc, exec, s[8:9]
	s_cbranch_vccz .LBB0_1163
	s_barrier

; #define PG8_STAGE(bufoff, gbase, voff) do { _Pragma("unroll") for (int _i = 0; _i < 2; ++_i) \
;         __builtin_amdgcn_global_load_lds((const unsigned*)((const char*)(gbase) + (voff)[_i]), (PG8_LAS unsigned*)(lds + (bufoff) + ldsw + _i * 8192), 16, 0, 0); } while (0)
; #define PG8_LDA(dst, b, h) do { _Pragma("unroll") for (int m = 0; m < 4; ++m) _Pragma("unroll") for (int k = 0; k < 2; ++k) dst[m][k] = *(const PG8_LAS bf16x8*)(lds + PG8_SA(b, h) + aoff + m * 2048 + k * 1024); } while (0)
; #define PG8_LDB(dst, b, h) do { _Pragma("unroll") for (int n = 0; n < 2; ++n) _Pragma("unroll") for (int k = 0; k < 2; ++k) dst[n][k] = *(const PG8_LAS bf16x8*)(lds + PG8_SB(b, h) + boff + n * 2048 + k * 1024); } while (0)
; #define PG8_MMA(ai, bj, At, Bt) do { __builtin_amdgcn_s_setprio(1); _Pragma("unroll") for (int m = 0; m < 4; ++m) _Pragma("unroll") for (int n = 0; n < 2; ++n) _Pragma("unroll") for (int k = 0; k < 2; ++k) \
;         acc[ai][bj][m][n] = __builtin_amdgcn_mfma_f32_16x16x32_bf16(Bt[n][k], At[m][k], acc[ai][bj][m][n], 0, 0, 0); __builtin_amdgcn_s_setprio(0); } while (0)
; #define PG8_WAIT_V(n) asm volatile("s_waitcnt vmcnt(" #n ")" ::: "memory")
; #define PG8_BAR __builtin_amdgcn_s_barrier()
; template <class Epi, class Sched, bool ALIGN_EPI = false, bool SP2 = false>
; __device__ __forceinline__ void gemm_phase(PG8_LAS unsigned char* lds, const Gemm g, const Sched& S, const Epi& E) {
;     ...
;         const bool has_next = S.next(ui + 1, nxt);
;         const char* nA = has_next ? (const char*)g.A + (size_t)nxt.pm * tstepA : cA; const char* nB = has_next ? (const char*)g.Bt + (size_t)nxt.pn * tstepB : cB;
;         for (int t = 0; t < nt; t += 2) {
;             const bool last = (t == nt - 2);
;             const char* a1 = cA + (size_t)(t + 1) * kstep;
;             const char* a2 = last ? nA : cA + (size_t)(t + 2) * kstep; const char* b2 = last ? nB : cB + (size_t)(t + 2) * kstep;
;             const char* a3 = a2 + kstep; const char* b3 = b2 + kstep;
;     ...
;             PG8_LDB(B0, 0, 0); PG8_LDB(B1, 0, 1); PG8_SCHED; PG8_LDA(At, 0, 0); PG8_STAGE(PG8_SA(1, 1), a1 + hstepA, voffA);
;             PG8_WAIT_V(8); PG8_WAIT_L(0); PG8_BAR; PG8_MMA(0, 0, At, B0); PG8_MMA(0, 1, At, B1); PG8_BAR; PG8_SCHED;
;             PG8_LDA(At, 0, 1); PG8_STAGE(PG8_SB(0, 0), b2, voffB); PG8_STAGE(PG8_SB(0, 1), b2 + hstepB, voffB); PG8_STAGE(PG8_SA(0, 0), a2, voffA);
.LBB0_1176:
	s_add_u32 s35, s26, s34
	s_addc_u32 s40, s27, 0
	s_add_u32 s38, s35, 0x100
	s_addc_u32 s39, s40, 0
	s_and_b64 s[36:37], s[30:31], exec
	s_cselect_b32 s37, s19, s39
	s_cselect_b32 s36, s18, s38
	s_add_u32 s34, s24, s34
	s_addc_u32 s38, s25, 0
	s_add_u32 s34, s34, 0x100
	s_addc_u32 s38, s38, 0
	s_add_i32 s72, 0, 0x10000
	s_and_b64 s[30:31], s[30:31], exec
	s_cselect_b32 s39, s61, s38
	s_cselect_b32 s38, s62, s34
	s_add_i32 s31, 0, 0x14000
	s_add_u32 s42, s35, 0x30080
	s_addc_u32 s43, s40, 0
	s_add_i32 s71, s72, s50
	s_add_i32 m0, s51, 0xc000
	s_add_i32 s74, s51, 0xe000
	s_add_i32 s67, s71, 0x2000
	v_add_u32_e32 v141, s72, v138
	s_add_u32 s40, s38, 0x10000
	ds_read_b128 v[142:145], v141
	ds_read_b128 v[146:149], v141 offset:1024
	ds_read_b128 v[150:153], v141 offset:2048
	ds_read_b128 v[154:157], v141 offset:3072
	v_add_u32_e32 v141, s31, v138
	s_addc_u32 s41, s39, 0
	s_add_i32 s69, s31, s50
	ds_read_b128 v[158:161], v141
	ds_read_b128 v[162:165], v141 offset:1024
	ds_read_b128 v[166:169], v141 offset:2048
	ds_read_b128 v[170:173], v141 offset:3072
	s_add_i32 s68, s69, 0x2000
	s_add_i32 s66, 0, 0x18000
	s_add_i32 s65, 0, 0x1c000
	s_add_u32 s34, s36, 0x30000
	s_addc_u32 s35, s37, 0
	s_add_i32 s64, s66, s50
	s_add_i32 s63, s64, 0x2000
	s_add_u32 s30, s38, 0x10080
	s_addc_u32 s31, s39, 0
	s_add_i32 s73, s65, s50
	s_add_i32 s72, s73, 0x2000
	v_lshl_add_u64 v[186:187], s[42:43], 0, v[136:137]
	ds_read_b128 v[174:177], v140
	ds_read_b128 v[178:181], v140 offset:1024
	ds_read_b128 v[182:185], v140 offset:2048
	ds_read_b128 v[202:205], v140 offset:3072
	ds_read_b128 v[206:209], v140 offset:4096
	ds_read_b128 v[210:213], v140 offset:5120
	ds_read_b128 v[232:235], v140 offset:6144
	ds_read_b128 v[236:239], v140 offset:7168
	global_load_lds_dwordx4 v[186:187], off
	v_lshl_add_u64 v[186:187], s[42:43], 0, v[132:133]
	s_mov_b32 m0, s74
	s_nop 0
	global_load_lds_dwordx4 v[186:187], off
	s_waitcnt vmcnt(8)
	s_waitcnt lgkmcnt(0)
	s_setprio 1
	s_barrier
	v_mfma_f32_16x16x32_bf16 v[126:129], v[142:145], v[174:177], v[126:129]
	v_mfma_f32_16x16x32_bf16 v[122:125], v[150:153], v[174:177], v[122:125]
	v_mfma_f32_16x16x32_bf16 v[118:121], v[142:145], v[182:185], v[118:121]
	v_mfma_f32_16x16x32_bf16 v[114:117], v[150:153], v[182:185], v[114:117]
	v_mfma_f32_16x16x32_bf16 v[110:113], v[142:145], v[206:209], v[110:113]
	v_mfma_f32_16x16x32_bf16 v[106:109], v[150:153], v[206:209], v[106:109]
	v_mfma_f32_16x16x32_bf16 v[102:105], v[142:145], v[232:235], v[102:105]
	v_mfma_f32_16x16x32_bf16 v[98:101], v[150:153], v[232:235], v[98:101]
	v_mfma_f32_16x16x32_bf16 v[126:129], v[146:149], v[178:181], v[126:129]
	v_mfma_f32_16x16x32_bf16 v[122:125], v[154:157], v[178:181], v[122:125]
	v_mfma_f32_16x16x32_bf16 v[118:121], v[146:149], v[202:205], v[118:121]
	v_mfma_f32_16x16x32_bf16 v[114:117], v[154:157], v[202:205], v[114:117]
	v_mfma_f32_16x16x32_bf16 v[110:113], v[146:149], v[210:213], v[110:113]
	v_mfma_f32_16x16x32_bf16 v[106:109], v[154:157], v[210:213], v[106:109]
	v_mfma_f32_16x16x32_bf16 v[102:105], v[146:149], v[236:239], v[102:105]
	v_mfma_f32_16x16x32_bf16 v[98:101], v[154:157], v[236:239], v[98:101]
	s_setprio 0
	s_setprio 1
	v_mfma_f32_16x16x32_bf16 v[78:81], v[158:161], v[174:177], v[78:81]
	v_mfma_f32_16x16x32_bf16 v[70:73], v[166:169], v[174:177], v[70:73]
	v_mfma_f32_16x16x32_bf16 v[62:65], v[158:161], v[182:185], v[62:65]
	v_mfma_f32_16x16x32_bf16 v[54:57], v[166:169], v[182:185], v[54:57]
	v_mfma_f32_16x16x32_bf16 v[46:49], v[158:161], v[206:209], v[46:49]
	v_mfma_f32_16x16x32_bf16 v[42:45], v[166:169], v[206:209], v[42:45]
	v_mfma_f32_16x16x32_bf16 v[38:41], v[158:161], v[232:235], v[38:41]
	v_mfma_f32_16x16x32_bf16 v[34:37], v[166:169], v[232:235], v[34:37]
	v_mfma_f32_16x16x32_bf16 v[78:81], v[162:165], v[178:181], v[78:81]
	v_mfma_f32_16x16x32_bf16 v[70:73], v[170:173], v[178:181], v[70:73]
	v_mfma_f32_16x16x32_bf16 v[62:65], v[162:165], v[202:205], v[62:65]
	v_mfma_f32_16x16x32_bf16 v[54:57], v[170:173], v[202:205], v[54:57]
	v_mfma_f32_16x16x32_bf16 v[46:49], v[162:165], v[210:213], v[46:49]
	v_mfma_f32_16x16x32_bf16 v[42:45], v[170:173], v[210:213], v[42:45]
	v_mfma_f32_16x16x32_bf16 v[38:41], v[162:165], v[236:239], v[38:41]
	v_mfma_f32_16x16x32_bf16 v[34:37], v[170:173], v[236:239], v[34:37]
	s_setprio 0
	s_barrier
	s_mov_b32 m0, s71
	v_lshl_add_u64 v[186:187], s[38:39], 0, v[134:135]
	ds_read_b128 v[174:177], v140 offset:16384
	ds_read_b128 v[178:181], v140 offset:17408
	ds_read_b128 v[182:185], v140 offset:18432
	ds_read_b128 v[202:205], v140 offset:19456
	ds_read_b128 v[206:209], v140 offset:20480
	ds_read_b128 v[210:213], v140 offset:21504
	ds_read_b128 v[232:235], v140 offset:22528
	ds_read_b128 v[236:239], v140 offset:23552
	global_load_lds_dwordx4 v[186:187], off
	v_lshl_add_u64 v[214:215], s[38:39], 0, v[130:131]
	s_mov_b32 m0, s67
	v_lshl_add_u64 v[240:241], s[40:41], 0, v[134:135]
	global_load_lds_dwordx4 v[214:215], off
	s_mov_b32 m0, s69
	v_lshl_add_u64 v[242:243], s[36:37], 0, v[132:133]
	global_load_lds_dwordx4 v[240:241], off
	v_lshl_add_u64 v[240:241], s[40:41], 0, v[130:131]
	s_mov_b32 m0, s68
	s_nop 0
	global_load_lds_dwordx4 v[240:241], off
	v_lshl_add_u64 v[240:241], s[36:37], 0, v[136:137]
	s_mov_b32 m0, s51
	s_nop 0
	global_load_lds_dwordx4 v[240:241], off
	s_mov_b32 m0, s52
	s_nop 0
	global_load_lds_dwordx4 v[242:243], off
	s_waitcnt vmcnt(8)
	s_waitcnt lgkmcnt(0)
	s_setprio 1
	s_barrier
; #define PG8_STAGE(bufoff, gbase, voff) do { _Pragma("unroll") for (int _i = 0; _i < 2; ++_i) \
;         __builtin_amdgcn_global_load_lds((const unsigned*)((const char*)(gbase) + (voff)[_i]), (PG8_LAS unsigned*)(lds + (bufoff) + ldsw + _i * 8192), 16, 0, 0); } while (0)
; #define PG8_LDA(dst, b, h) do { _Pragma("unroll") for (int m = 0; m < 4; ++m) _Pragma("unroll") for (int k = 0; k < 2; ++k) dst[m][k] = *(const PG8_LAS bf16x8*)(lds + PG8_SA(b, h) + aoff + m * 2048 + k * 1024); } while (0)
; #define PG8_LDB(dst, b, h) do { _Pragma("unroll") for (int n = 0; n < 2; ++n) _Pragma("unroll") for (int k = 0; k < 2; ++k) dst[n][k] = *(const PG8_LAS bf16x8*)(lds + PG8_SB(b, h) + boff + n * 2048 + k * 1024); } while (0)
; #define PG8_MMA(ai, bj, At, Bt) do { __builtin_amdgcn_s_setprio(1); _Pragma("unroll") for (int m = 0; m < 4; ++m) _Pragma("unroll") for (int n = 0; n < 2; ++n) _Pragma("unroll") for (int k = 0; k < 2; ++k) \
;         acc[ai][bj][m][n] = __builtin_amdgcn_mfma_f32_16x16x32_bf16(Bt[n][k], At[m][k], acc[ai][bj][m][n], 0, 0, 0); __builtin_amdgcn_s_setprio(0); } while (0)
; #define PG8_WAIT_V(n) asm volatile("s_waitcnt vmcnt(" #n ")" ::: "memory")
; #define PG8_WAIT_L(n) asm volatile("s_waitcnt lgkmcnt(" #n ")" ::: "memory")
; #define PG8_BAR __builtin_amdgcn_s_barrier()
; #define PG8_SCHED __builtin_amdgcn_sched_barrier(0)
; template <class Epi, class Sched, bool ALIGN_EPI = false, bool SP2 = false>
; __device__ __forceinline__ void gemm_phase(PG8_LAS unsigned char* lds, const Gemm g, const Sched& S, const Epi& E) {
;     ...
;             PG8_WAIT_V(8); PG8_WAIT_L(0); PG8_BAR; PG8_MMA(1, 0, At, B0); PG8_MMA(1, 1, At, B1); PG8_BAR; PG8_SCHED;
;             PG8_LDB(B0, 1, 0); PG8_LDB(B1, 1, 1); PG8_SCHED; PG8_LDA(At, 1, 0); PG8_STAGE(PG8_SA(0, 1), a2 + hstepA, voffA);
;             PG8_WAIT_V(8); PG8_WAIT_L(0); PG8_BAR; PG8_MMA(0, 0, At, B0); PG8_MMA(0, 1, At, B1); PG8_BAR; PG8_SCHED;
	v_mfma_f32_16x16x32_bf16 v[94:97], v[142:145], v[174:177], v[94:97]
	v_mfma_f32_16x16x32_bf16 v[90:93], v[150:153], v[174:177], v[90:93]
	v_mfma_f32_16x16x32_bf16 v[86:89], v[142:145], v[182:185], v[86:89]
	v_mfma_f32_16x16x32_bf16 v[82:85], v[150:153], v[182:185], v[82:85]
	v_mfma_f32_16x16x32_bf16 v[74:77], v[142:145], v[206:209], v[74:77]
	v_mfma_f32_16x16x32_bf16 v[66:69], v[150:153], v[206:209], v[66:69]
	v_mfma_f32_16x16x32_bf16 v[58:61], v[142:145], v[232:235], v[58:61]
	v_mfma_f32_16x16x32_bf16 v[50:53], v[150:153], v[232:235], v[50:53]
	v_mfma_f32_16x16x32_bf16 v[94:97], v[146:149], v[178:181], v[94:97]
	v_mfma_f32_16x16x32_bf16 v[90:93], v[154:157], v[178:181], v[90:93]
	v_mfma_f32_16x16x32_bf16 v[86:89], v[146:149], v[202:205], v[86:89]
	v_mfma_f32_16x16x32_bf16 v[82:85], v[154:157], v[202:205], v[82:85]
	v_mfma_f32_16x16x32_bf16 v[74:77], v[146:149], v[210:213], v[74:77]
	v_mfma_f32_16x16x32_bf16 v[66:69], v[154:157], v[210:213], v[66:69]
	v_mfma_f32_16x16x32_bf16 v[58:61], v[146:149], v[236:239], v[58:61]
	v_mfma_f32_16x16x32_bf16 v[50:53], v[154:157], v[236:239], v[50:53]
	s_setprio 0
	s_setprio 1
	v_mfma_f32_16x16x32_bf16 v[30:33], v[158:161], v[174:177], v[30:33]
	v_mfma_f32_16x16x32_bf16 v[26:29], v[166:169], v[174:177], v[26:29]
	v_mfma_f32_16x16x32_bf16 v[22:25], v[158:161], v[182:185], v[22:25]
	v_mfma_f32_16x16x32_bf16 v[18:21], v[166:169], v[182:185], v[18:21]
	v_mfma_f32_16x16x32_bf16 v[14:17], v[158:161], v[206:209], v[14:17]
	v_mfma_f32_16x16x32_bf16 v[10:13], v[166:169], v[206:209], v[10:13]
	v_mfma_f32_16x16x32_bf16 v[6:9], v[158:161], v[232:235], v[6:9]
	v_mfma_f32_16x16x32_bf16 v[2:5], v[166:169], v[232:235], v[2:5]
	v_mfma_f32_16x16x32_bf16 v[30:33], v[162:165], v[178:181], v[30:33]
	v_mfma_f32_16x16x32_bf16 v[26:29], v[170:173], v[178:181], v[26:29]
	v_mfma_f32_16x16x32_bf16 v[22:25], v[162:165], v[202:205], v[22:25]
	v_mfma_f32_16x16x32_bf16 v[18:21], v[170:173], v[202:205], v[18:21]
	v_mfma_f32_16x16x32_bf16 v[14:17], v[162:165], v[210:213], v[14:17]
	v_mfma_f32_16x16x32_bf16 v[10:13], v[170:173], v[210:213], v[10:13]
	v_mfma_f32_16x16x32_bf16 v[6:9], v[162:165], v[236:239], v[6:9]
	v_mfma_f32_16x16x32_bf16 v[2:5], v[170:173], v[236:239], v[2:5]
	s_setprio 0
	s_barrier
	v_add_u32_e32 v141, s66, v138
	ds_read_b128 v[142:145], v141
	ds_read_b128 v[146:149], v141 offset:1024
	ds_read_b128 v[150:153], v141 offset:2048
	ds_read_b128 v[154:157], v141 offset:3072
	v_add_u32_e32 v141, s65, v138
	ds_read_b128 v[158:161], v141
	ds_read_b128 v[162:165], v141 offset:1024
	ds_read_b128 v[166:169], v141 offset:2048
	ds_read_b128 v[170:173], v141 offset:3072
	s_mov_b32 m0, s53
	v_lshl_add_u64 v[244:245], s[34:35], 0, v[136:137]
	ds_read_b128 v[174:177], v140 offset:32768
	ds_read_b128 v[178:181], v140 offset:33792
	ds_read_b128 v[182:185], v140 offset:34816
	ds_read_b128 v[202:205], v140 offset:35840
	ds_read_b128 v[206:209], v140 offset:36864
	ds_read_b128 v[210:213], v140 offset:37888
	ds_read_b128 v[232:235], v140 offset:38912
	ds_read_b128 v[236:239], v140 offset:39936
	global_load_lds_dwordx4 v[244:245], off
	v_lshl_add_u64 v[244:245], s[34:35], 0, v[132:133]
	s_mov_b32 m0, s54
	s_nop 0
	global_load_lds_dwordx4 v[244:245], off
	s_waitcnt vmcnt(8)
	s_waitcnt lgkmcnt(0)
	s_setprio 1
	s_barrier
	v_mfma_f32_16x16x32_bf16 v[126:129], v[142:145], v[174:177], v[126:129]
	v_mfma_f32_16x16x32_bf16 v[122:125], v[150:153], v[174:177], v[122:125]
	v_mfma_f32_16x16x32_bf16 v[118:121], v[142:145], v[182:185], v[118:121]
	v_mfma_f32_16x16x32_bf16 v[114:117], v[150:153], v[182:185], v[114:117]
	v_mfma_f32_16x16x32_bf16 v[110:113], v[142:145], v[206:209], v[110:113]
	v_mfma_f32_16x16x32_bf16 v[106:109], v[150:153], v[206:209], v[106:109]
	v_mfma_f32_16x16x32_bf16 v[102:105], v[142:145], v[232:235], v[102:105]
	v_mfma_f32_16x16x32_bf16 v[98:101], v[150:153], v[232:235], v[98:101]
	v_mfma_f32_16x16x32_bf16 v[126:129], v[146:149], v[178:181], v[126:129]
	v_mfma_f32_16x16x32_bf16 v[122:125], v[154:157], v[178:181], v[122:125]
	v_mfma_f32_16x16x32_bf16 v[118:121], v[146:149], v[202:205], v[118:121]
	v_mfma_f32_16x16x32_bf16 v[114:117], v[154:157], v[202:205], v[114:117]
	v_mfma_f32_16x16x32_bf16 v[110:113], v[146:149], v[210:213], v[110:113]
	v_mfma_f32_16x16x32_bf16 v[106:109], v[154:157], v[210:213], v[106:109]
	v_mfma_f32_16x16x32_bf16 v[102:105], v[146:149], v[236:239], v[102:105]
	v_mfma_f32_16x16x32_bf16 v[98:101], v[154:157], v[236:239], v[98:101]
	s_setprio 0
	s_setprio 1
	v_mfma_f32_16x16x32_bf16 v[78:81], v[158:161], v[174:177], v[78:81]
	v_mfma_f32_16x16x32_bf16 v[70:73], v[166:169], v[174:177], v[70:73]
	v_mfma_f32_16x16x32_bf16 v[62:65], v[158:161], v[182:185], v[62:65]
	v_mfma_f32_16x16x32_bf16 v[54:57], v[166:169], v[182:185], v[54:57]
	v_mfma_f32_16x16x32_bf16 v[46:49], v[158:161], v[206:209], v[46:49]
	v_mfma_f32_16x16x32_bf16 v[42:45], v[166:169], v[206:209], v[42:45]
	v_mfma_f32_16x16x32_bf16 v[38:41], v[158:161], v[232:235], v[38:41]
	v_mfma_f32_16x16x32_bf16 v[34:37], v[166:169], v[232:235], v[34:37]
	v_mfma_f32_16x16x32_bf16 v[78:81], v[162:165], v[178:181], v[78:81]
	v_mfma_f32_16x16x32_bf16 v[70:73], v[170:173], v[178:181], v[70:73]
	v_mfma_f32_16x16x32_bf16 v[62:65], v[162:165], v[202:205], v[62:65]
	v_mfma_f32_16x16x32_bf16 v[54:57], v[170:173], v[202:205], v[54:57]
	v_mfma_f32_16x16x32_bf16 v[46:49], v[162:165], v[210:213], v[46:49]
	v_mfma_f32_16x16x32_bf16 v[42:45], v[170:173], v[210:213], v[42:45]
	v_mfma_f32_16x16x32_bf16 v[38:41], v[162:165], v[236:239], v[38:41]
	v_mfma_f32_16x16x32_bf16 v[34:37], v[170:173], v[236:239], v[34:37]
	s_setprio 0
	s_barrier
; #define PG8_STAGE(bufoff, gbase, voff) do { _Pragma("unroll") for (int _i = 0; _i < 2; ++_i) \
;         __builtin_amdgcn_global_load_lds((const unsigned*)((const char*)(gbase) + (voff)[_i]), (PG8_LAS unsigned*)(lds + (bufoff) + ldsw + _i * 8192), 16, 0, 0); } while (0)
; #define PG8_LDA(dst, b, h) do { _Pragma("unroll") for (int m = 0; m < 4; ++m) _Pragma("unroll") for (int k = 0; k < 2; ++k) dst[m][k] = *(const PG8_LAS bf16x8*)(lds + PG8_SA(b, h) + aoff + m * 2048 + k * 1024); } while (0)
; #define PG8_MMA(ai, bj, At, Bt) do { __builtin_amdgcn_s_setprio(1); _Pragma("unroll") for (int m = 0; m < 4; ++m) _Pragma("unroll") for (int n = 0; n < 2; ++n) _Pragma("unroll") for (int k = 0; k < 2; ++k) \
;         acc[ai][bj][m][n] = __builtin_amdgcn_mfma_f32_16x16x32_bf16(Bt[n][k], At[m][k], acc[ai][bj][m][n], 0, 0, 0); __builtin_amdgcn_s_setprio(0); } while (0)
; #define PG8_WAIT_V(n) asm volatile("s_waitcnt vmcnt(" #n ")" ::: "memory")
; #define PG8_WAIT_L(n) asm volatile("s_waitcnt lgkmcnt(" #n ")" ::: "memory")
; #define PG8_BAR __builtin_amdgcn_s_barrier()
; #define PG8_SCHED __builtin_amdgcn_sched_barrier(0)
; template <class Epi, class Sched, bool ALIGN_EPI = false, bool SP2 = false>
; __device__ __forceinline__ void gemm_phase(PG8_LAS unsigned char* lds, const Gemm g, const Sched& S, const Epi& E) {
;     ...
;         for (int t = 0; t < nt; t += 2) {
;             const bool last = (t == nt - 2);
;             const char* a1 = cA + (size_t)(t + 1) * kstep;
;             const char* a2 = last ? nA : cA + (size_t)(t + 2) * kstep; const char* b2 = last ? nB : cB + (size_t)(t + 2) * kstep;
;     ...
;             PG8_LDA(At, 1, 1); PG8_STAGE(PG8_SB(1, 0), b3, voffB); PG8_STAGE(PG8_SB(1, 1), b3 + hstepB, voffB); PG8_STAGE(PG8_SA(1, 0), a3, voffA);
;             PG8_WAIT_V(8); PG8_WAIT_L(0); PG8_BAR; PG8_MMA(1, 0, At, B0); PG8_MMA(1, 1, At, B1); PG8_BAR; PG8_SCHED;
	s_mov_b32 m0, s64
	v_lshl_add_u64 v[186:187], v[186:187], 0, s[96:97]
	ds_read_b128 v[174:177], v140 offset:49152
	ds_read_b128 v[178:181], v140 offset:50176
	ds_read_b128 v[182:185], v140 offset:51200
	ds_read_b128 v[202:205], v140 offset:52224
	ds_read_b128 v[206:209], v140 offset:53248
	ds_read_b128 v[210:213], v140 offset:54272
	ds_read_b128 v[232:235], v140 offset:55296
	ds_read_b128 v[236:239], v140 offset:56320
	global_load_lds_dwordx4 v[186:187], off
	v_lshl_add_u64 v[186:187], v[214:215], 0, s[96:97]
	s_mov_b32 m0, s63
	s_nop 0
	global_load_lds_dwordx4 v[186:187], off
	v_lshl_add_u64 v[186:187], s[30:31], 0, v[134:135]
	s_mov_b32 m0, s73
	s_nop 0
	global_load_lds_dwordx4 v[186:187], off
	v_lshl_add_u64 v[186:187], s[30:31], 0, v[130:131]
	s_mov_b32 m0, s72
	s_nop 0
	global_load_lds_dwordx4 v[186:187], off
	v_lshl_add_u64 v[186:187], v[240:241], 0, s[96:97]
	s_mov_b32 m0, s55
	s_nop 0
	global_load_lds_dwordx4 v[186:187], off
	v_lshl_add_u64 v[186:187], v[242:243], 0, s[96:97]
	s_mov_b32 m0, s56
	s_nop 0
	global_load_lds_dwordx4 v[186:187], off
	s_waitcnt vmcnt(8)
	s_waitcnt lgkmcnt(0)
	s_setprio 1
	s_barrier
	v_mfma_f32_16x16x32_bf16 v[94:97], v[142:145], v[174:177], v[94:97]
	v_mfma_f32_16x16x32_bf16 v[90:93], v[150:153], v[174:177], v[90:93]
	v_mfma_f32_16x16x32_bf16 v[86:89], v[142:145], v[182:185], v[86:89]
	v_mfma_f32_16x16x32_bf16 v[82:85], v[150:153], v[182:185], v[82:85]
	v_mfma_f32_16x16x32_bf16 v[74:77], v[142:145], v[206:209], v[74:77]
	v_mfma_f32_16x16x32_bf16 v[66:69], v[150:153], v[206:209], v[66:69]
	v_mfma_f32_16x16x32_bf16 v[58:61], v[142:145], v[232:235], v[58:61]
	v_mfma_f32_16x16x32_bf16 v[50:53], v[150:153], v[232:235], v[50:53]
	v_mfma_f32_16x16x32_bf16 v[94:97], v[146:149], v[178:181], v[94:97]
	v_mfma_f32_16x16x32_bf16 v[90:93], v[154:157], v[178:181], v[90:93]
	v_mfma_f32_16x16x32_bf16 v[86:89], v[146:149], v[202:205], v[86:89]
	v_mfma_f32_16x16x32_bf16 v[82:85], v[154:157], v[202:205], v[82:85]
	v_mfma_f32_16x16x32_bf16 v[74:77], v[146:149], v[210:213], v[74:77]
	v_mfma_f32_16x16x32_bf16 v[66:69], v[154:157], v[210:213], v[66:69]
	v_mfma_f32_16x16x32_bf16 v[58:61], v[146:149], v[236:239], v[58:61]
	v_mfma_f32_16x16x32_bf16 v[50:53], v[154:157], v[236:239], v[50:53]
	s_setprio 0
	s_setprio 1
	v_mfma_f32_16x16x32_bf16 v[30:33], v[158:161], v[174:177], v[30:33]
	v_mfma_f32_16x16x32_bf16 v[26:29], v[166:169], v[174:177], v[26:29]
	v_mfma_f32_16x16x32_bf16 v[22:25], v[158:161], v[182:185], v[22:25]
	v_mfma_f32_16x16x32_bf16 v[18:21], v[166:169], v[182:185], v[18:21]
	v_mfma_f32_16x16x32_bf16 v[14:17], v[158:161], v[206:209], v[14:17]
	v_mfma_f32_16x16x32_bf16 v[10:13], v[166:169], v[206:209], v[10:13]
	v_mfma_f32_16x16x32_bf16 v[6:9], v[158:161], v[232:235], v[6:9]
	v_mfma_f32_16x16x32_bf16 v[2:5], v[166:169], v[232:235], v[2:5]
	v_mfma_f32_16x16x32_bf16 v[30:33], v[162:165], v[178:181], v[30:33]
	v_mfma_f32_16x16x32_bf16 v[26:29], v[170:173], v[178:181], v[26:29]
	v_mfma_f32_16x16x32_bf16 v[22:25], v[162:165], v[202:205], v[22:25]
	v_mfma_f32_16x16x32_bf16 v[18:21], v[170:173], v[202:205], v[18:21]
	v_mfma_f32_16x16x32_bf16 v[14:17], v[162:165], v[210:213], v[14:17]
	v_mfma_f32_16x16x32_bf16 v[10:13], v[170:173], v[210:213], v[10:13]
	v_mfma_f32_16x16x32_bf16 v[6:9], v[162:165], v[236:239], v[6:9]
	v_mfma_f32_16x16x32_bf16 v[2:5], v[170:173], v[236:239], v[2:5]
	s_setprio 0
	s_barrier
	s_movk_i32 s34, 0x100
	s_andn2_b64 vcc, exec, s[28:29]
	s_mov_b64 s[30:31], -1
	s_mov_b64 s[28:29], 0
	s_cbranch_vccz .LBB0_1176
	s_and_b64 vcc, exec, s[16:17]
	s_cbranch_vccz .LBB0_1179
	s_barrier

; #define PG8_STAGE(bufoff, gbase, voff) do { _Pragma("unroll") for (int _i = 0; _i < 2; ++_i) \
;         __builtin_amdgcn_global_load_lds((const unsigned*)((const char*)(gbase) + (voff)[_i]), (PG8_LAS unsigned*)(lds + (bufoff) + ldsw + _i * 8192), 16, 0, 0); } while (0)
; #define PG8_LDA(dst, b, h) do { _Pragma("unroll") for (int m = 0; m < 4; ++m) _Pragma("unroll") for (int k = 0; k < 2; ++k) dst[m][k] = *(const PG8_LAS bf16x8*)(lds + PG8_SA(b, h) + aoff + m * 2048 + k * 1024); } while (0)
; #define PG8_LDB(dst, b, h) do { _Pragma("unroll") for (int n = 0; n < 2; ++n) _Pragma("unroll") for (int k = 0; k < 2; ++k) dst[n][k] = *(const PG8_LAS bf16x8*)(lds + PG8_SB(b, h) + boff + n * 2048 + k * 1024); } while (0)
; #define PG8_MMA(ai, bj, At, Bt) do { __builtin_amdgcn_s_setprio(1); _Pragma("unroll") for (int m = 0; m < 4; ++m) _Pragma("unroll") for (int n = 0; n < 2; ++n) _Pragma("unroll") for (int k = 0; k < 2; ++k) \
;         acc[ai][bj][m][n] = __builtin_amdgcn_mfma_f32_16x16x32_bf16(Bt[n][k], At[m][k], acc[ai][bj][m][n], 0, 0, 0); __builtin_amdgcn_s_setprio(0); } while (0)
; #define PG8_WAIT_V(n) asm volatile("s_waitcnt vmcnt(" #n ")" ::: "memory")
; #define PG8_WAIT_L(n) asm volatile("s_waitcnt lgkmcnt(" #n ")" ::: "memory")
; #define PG8_BAR __builtin_amdgcn_s_barrier()
; #define PG8_SCHED __builtin_amdgcn_sched_barrier(0)
; template <class Epi, class Sched, bool ALIGN_EPI = false, bool SP2 = false>
; __device__ __forceinline__ void gemm_phase(PG8_LAS unsigned char* lds, const Gemm g, const Sched& S, const Epi& E) {
;     ...
;             PG8_LDB(B0, 0, 0); PG8_LDB(B1, 0, 1); PG8_SCHED; PG8_LDA(At, 0, 0); PG8_STAGE(PG8_SA(1, 1), a1 + hstepA, voffA);
;             PG8_WAIT_V(8); PG8_WAIT_L(0); PG8_BAR; PG8_MMA(0, 0, At, B0); PG8_MMA(0, 1, At, B1); PG8_BAR; PG8_SCHED;
;             PG8_LDA(At, 0, 1); PG8_STAGE(PG8_SB(0, 0), b2, voffB); PG8_STAGE(PG8_SB(0, 1), b2 + hstepB, voffB); PG8_STAGE(PG8_SA(0, 0), a2, voffA);
.LBB0_1190:
	s_add_u32 s24, s22, 0xfffc0080
	s_addc_u32 s25, s23, -1
	s_add_i32 s51, 0, 0x10000
	s_cmp_eq_u32 s50, 12
	s_cselect_b32 s27, s44, s25
	s_cselect_b32 s26, s45, s24
	s_cselect_b32 s25, s46, s49
	s_cselect_b32 s24, s47, s48
	s_add_i32 s54, 0, 0x14000
	v_add_u32_e32 v142, s51, v168
	v_add_u32_e32 v166, s54, v168
	ds_read_b128 v[130:133], v142
	ds_read_b128 v[134:137], v142 offset:1024
	ds_read_b128 v[138:141], v142 offset:2048
	ds_read_b128 v[142:145], v142 offset:3072
	ds_read_b128 v[158:161], v166
	ds_read_b128 v[162:165], v166 offset:1024
	ds_read_b128 v[172:175], v166 offset:2048
	ds_read_b128 v[176:179], v166 offset:3072
	s_add_i32 m0, s7, 0xc000
	ds_read_b128 v[180:183], v171
	ds_read_b128 v[184:187], v171 offset:1024
	ds_read_b128 v[202:205], v171 offset:2048
	ds_read_b128 v[206:209], v171 offset:3072
	ds_read_b128 v[210:213], v171 offset:4096
	ds_read_b128 v[232:235], v171 offset:5120
	ds_read_b128 v[236:239], v171 offset:6144
	ds_read_b128 v[240:243], v171 offset:7168
	global_load_lds_dwordx4 v154, s[22:23]
	s_add_i32 m0, s7, 0xe000
	s_nop 0
	global_load_lds_dwordx4 v156, s[22:23]
	s_waitcnt vmcnt(8)
	s_waitcnt lgkmcnt(0)
	s_setprio 1
	s_barrier
	v_mfma_f32_16x16x32_bf16 v[126:129], v[130:133], v[180:183], v[126:129]
	v_mfma_f32_16x16x32_bf16 v[118:121], v[138:141], v[180:183], v[118:121]
	v_mfma_f32_16x16x32_bf16 v[110:113], v[130:133], v[202:205], v[110:113]
	v_mfma_f32_16x16x32_bf16 v[102:105], v[138:141], v[202:205], v[102:105]
	v_mfma_f32_16x16x32_bf16 v[94:97], v[130:133], v[210:213], v[94:97]
	v_mfma_f32_16x16x32_bf16 v[86:89], v[138:141], v[210:213], v[86:89]
	v_mfma_f32_16x16x32_bf16 v[78:81], v[130:133], v[236:239], v[78:81]
	v_mfma_f32_16x16x32_bf16 v[70:73], v[138:141], v[236:239], v[70:73]
	v_mfma_f32_16x16x32_bf16 v[126:129], v[134:137], v[184:187], v[126:129]
	v_mfma_f32_16x16x32_bf16 v[118:121], v[142:145], v[184:187], v[118:121]
	v_mfma_f32_16x16x32_bf16 v[110:113], v[134:137], v[206:209], v[110:113]
	v_mfma_f32_16x16x32_bf16 v[102:105], v[142:145], v[206:209], v[102:105]
	v_mfma_f32_16x16x32_bf16 v[94:97], v[134:137], v[232:235], v[94:97]
	v_mfma_f32_16x16x32_bf16 v[86:89], v[142:145], v[232:235], v[86:89]
	v_mfma_f32_16x16x32_bf16 v[78:81], v[134:137], v[240:243], v[78:81]
	v_mfma_f32_16x16x32_bf16 v[70:73], v[142:145], v[240:243], v[70:73]
	s_setprio 0
	s_setprio 1
	v_mfma_f32_16x16x32_bf16 v[122:125], v[158:161], v[180:183], v[122:125]
	v_mfma_f32_16x16x32_bf16 v[114:117], v[172:175], v[180:183], v[114:117]
	v_mfma_f32_16x16x32_bf16 v[106:109], v[158:161], v[202:205], v[106:109]
	v_mfma_f32_16x16x32_bf16 v[98:101], v[172:175], v[202:205], v[98:101]
	v_mfma_f32_16x16x32_bf16 v[90:93], v[158:161], v[210:213], v[90:93]
	v_mfma_f32_16x16x32_bf16 v[82:85], v[172:175], v[210:213], v[82:85]
	v_mfma_f32_16x16x32_bf16 v[74:77], v[158:161], v[236:239], v[74:77]
	v_mfma_f32_16x16x32_bf16 v[66:69], v[172:175], v[236:239], v[66:69]
	v_mfma_f32_16x16x32_bf16 v[122:125], v[162:165], v[184:187], v[122:125]
	v_mfma_f32_16x16x32_bf16 v[114:117], v[176:179], v[184:187], v[114:117]
	v_mfma_f32_16x16x32_bf16 v[106:109], v[162:165], v[206:209], v[106:109]
	v_mfma_f32_16x16x32_bf16 v[98:101], v[176:179], v[206:209], v[98:101]
	v_mfma_f32_16x16x32_bf16 v[90:93], v[162:165], v[232:235], v[90:93]
	v_mfma_f32_16x16x32_bf16 v[82:85], v[176:179], v[232:235], v[82:85]
	v_mfma_f32_16x16x32_bf16 v[74:77], v[162:165], v[240:243], v[74:77]
	v_mfma_f32_16x16x32_bf16 v[66:69], v[176:179], v[240:243], v[66:69]
	s_setprio 0
	s_barrier
	s_add_i32 s51, s51, s30
	s_mov_b32 m0, s51
	ds_read_b128 v[180:183], v171 offset:16384
	ds_read_b128 v[184:187], v171 offset:17408
	ds_read_b128 v[202:205], v171 offset:18432
	ds_read_b128 v[206:209], v171 offset:19456
	ds_read_b128 v[210:213], v171 offset:20480
	ds_read_b128 v[232:235], v171 offset:21504
	ds_read_b128 v[236:239], v171 offset:22528
	ds_read_b128 v[240:243], v171 offset:23552
	s_add_u32 s60, s24, 0x80
	s_addc_u32 s61, s25, 0
	s_add_u32 s62, s26, 0x80
	s_addc_u32 s63, s27, 0
	global_load_lds_dwordx4 v150, s[24:25]
	s_add_i32 m0, s51, 0x2000
	s_add_u32 s52, s24, 0x40000
	s_addc_u32 s53, s25, 0
	s_add_i32 s51, s54, s30
	global_load_lds_dwordx4 v146, s[24:25]
	s_mov_b32 m0, s51
	s_nop 0
	global_load_lds_dwordx4 v150, s[52:53]
	s_add_i32 m0, s51, 0x2000
	s_nop 0
	global_load_lds_dwordx4 v146, s[52:53]
	s_mov_b32 m0, s7
	s_nop 0
	global_load_lds_dwordx4 v152, s[26:27]
	s_mov_b32 m0, s36
	s_nop 0
	global_load_lds_dwordx4 v148, s[26:27]
	s_waitcnt vmcnt(8)
	s_waitcnt lgkmcnt(0)
	s_setprio 1
	s_barrier
; #define PG8_STAGE(bufoff, gbase, voff) do { _Pragma("unroll") for (int _i = 0; _i < 2; ++_i) \
;         __builtin_amdgcn_global_load_lds((const unsigned*)((const char*)(gbase) + (voff)[_i]), (PG8_LAS unsigned*)(lds + (bufoff) + ldsw + _i * 8192), 16, 0, 0); } while (0)
; #define PG8_LDA(dst, b, h) do { _Pragma("unroll") for (int m = 0; m < 4; ++m) _Pragma("unroll") for (int k = 0; k < 2; ++k) dst[m][k] = *(const PG8_LAS bf16x8*)(lds + PG8_SA(b, h) + aoff + m * 2048 + k * 1024); } while (0)
; #define PG8_LDB(dst, b, h) do { _Pragma("unroll") for (int n = 0; n < 2; ++n) _Pragma("unroll") for (int k = 0; k < 2; ++k) dst[n][k] = *(const PG8_LAS bf16x8*)(lds + PG8_SB(b, h) + boff + n * 2048 + k * 1024); } while (0)
; #define PG8_MMA(ai, bj, At, Bt) do { __builtin_amdgcn_s_setprio(1); _Pragma("unroll") for (int m = 0; m < 4; ++m) _Pragma("unroll") for (int n = 0; n < 2; ++n) _Pragma("unroll") for (int k = 0; k < 2; ++k) \
;         acc[ai][bj][m][n] = __builtin_amdgcn_mfma_f32_16x16x32_bf16(Bt[n][k], At[m][k], acc[ai][bj][m][n], 0, 0, 0); __builtin_amdgcn_s_setprio(0); } while (0)
; #define PG8_WAIT_V(n) asm volatile("s_waitcnt vmcnt(" #n ")" ::: "memory")
; #define PG8_WAIT_L(n) asm volatile("s_waitcnt lgkmcnt(" #n ")" ::: "memory")
; #define PG8_BAR __builtin_amdgcn_s_barrier()
; #define PG8_SCHED __builtin_amdgcn_sched_barrier(0)
; template <class Epi, class Sched, bool ALIGN_EPI = false, bool SP2 = false>
; __device__ __forceinline__ void gemm_phase(PG8_LAS unsigned char* lds, const Gemm g, const Sched& S, const Epi& E) {
;     ...
;             PG8_WAIT_V(8); PG8_WAIT_L(0); PG8_BAR; PG8_MMA(1, 0, At, B0); PG8_MMA(1, 1, At, B1); PG8_BAR; PG8_SCHED;
;             PG8_LDB(B0, 1, 0); PG8_LDB(B1, 1, 1); PG8_SCHED; PG8_LDA(At, 1, 0); PG8_STAGE(PG8_SA(0, 1), a2 + hstepA, voffA);
;             PG8_WAIT_V(8); PG8_WAIT_L(0); PG8_BAR; PG8_MMA(0, 0, At, B0); PG8_MMA(0, 1, At, B1); PG8_BAR; PG8_SCHED;
	v_mfma_f32_16x16x32_bf16 v[62:65], v[130:133], v[180:183], v[62:65]
	v_mfma_f32_16x16x32_bf16 v[54:57], v[138:141], v[180:183], v[54:57]
	v_mfma_f32_16x16x32_bf16 v[46:49], v[130:133], v[202:205], v[46:49]
	v_mfma_f32_16x16x32_bf16 v[38:41], v[138:141], v[202:205], v[38:41]
	v_mfma_f32_16x16x32_bf16 v[30:33], v[130:133], v[210:213], v[30:33]
	v_mfma_f32_16x16x32_bf16 v[22:25], v[138:141], v[210:213], v[22:25]
	v_mfma_f32_16x16x32_bf16 v[14:17], v[130:133], v[236:239], v[14:17]
	v_mfma_f32_16x16x32_bf16 v[6:9], v[138:141], v[236:239], v[6:9]
	v_mfma_f32_16x16x32_bf16 v[62:65], v[134:137], v[184:187], v[62:65]
	v_mfma_f32_16x16x32_bf16 v[54:57], v[142:145], v[184:187], v[54:57]
	v_mfma_f32_16x16x32_bf16 v[46:49], v[134:137], v[206:209], v[46:49]
	v_mfma_f32_16x16x32_bf16 v[38:41], v[142:145], v[206:209], v[38:41]
	v_mfma_f32_16x16x32_bf16 v[30:33], v[134:137], v[232:235], v[30:33]
	v_mfma_f32_16x16x32_bf16 v[22:25], v[142:145], v[232:235], v[22:25]
	v_mfma_f32_16x16x32_bf16 v[14:17], v[134:137], v[240:243], v[14:17]
	v_mfma_f32_16x16x32_bf16 v[6:9], v[142:145], v[240:243], v[6:9]
	s_setprio 0
	s_setprio 1
	v_mfma_f32_16x16x32_bf16 v[58:61], v[158:161], v[180:183], v[58:61]
	v_mfma_f32_16x16x32_bf16 v[50:53], v[172:175], v[180:183], v[50:53]
	v_mfma_f32_16x16x32_bf16 v[42:45], v[158:161], v[202:205], v[42:45]
	v_mfma_f32_16x16x32_bf16 v[34:37], v[172:175], v[202:205], v[34:37]
	v_mfma_f32_16x16x32_bf16 v[26:29], v[158:161], v[210:213], v[26:29]
	v_mfma_f32_16x16x32_bf16 v[18:21], v[172:175], v[210:213], v[18:21]
	v_mfma_f32_16x16x32_bf16 v[10:13], v[158:161], v[236:239], v[10:13]
	v_mfma_f32_16x16x32_bf16 v[2:5], v[172:175], v[236:239], v[2:5]
	v_mfma_f32_16x16x32_bf16 v[58:61], v[162:165], v[184:187], v[58:61]
	v_mfma_f32_16x16x32_bf16 v[50:53], v[176:179], v[184:187], v[50:53]
	v_mfma_f32_16x16x32_bf16 v[42:45], v[162:165], v[206:209], v[42:45]
	v_mfma_f32_16x16x32_bf16 v[34:37], v[176:179], v[206:209], v[34:37]
	v_mfma_f32_16x16x32_bf16 v[26:29], v[162:165], v[232:235], v[26:29]
	v_mfma_f32_16x16x32_bf16 v[18:21], v[176:179], v[232:235], v[18:21]
	v_mfma_f32_16x16x32_bf16 v[10:13], v[162:165], v[240:243], v[10:13]
	v_mfma_f32_16x16x32_bf16 v[2:5], v[176:179], v[240:243], v[2:5]
	s_setprio 0
	s_barrier
	s_add_i32 s51, 0, 0x18000
	s_add_i32 s52, 0, 0x1c000
	v_add_u32_e32 v142, s51, v168
	v_add_u32_e32 v176, s52, v168
	ds_read_b128 v[130:133], v142
	ds_read_b128 v[134:137], v142 offset:1024
	ds_read_b128 v[138:141], v142 offset:2048
	ds_read_b128 v[142:145], v142 offset:3072
	ds_read_b128 v[158:161], v176
	ds_read_b128 v[162:165], v176 offset:1024
	ds_read_b128 v[172:175], v176 offset:2048
	ds_read_b128 v[176:179], v176 offset:3072
	s_add_u32 s26, s26, 0x40000
	s_addc_u32 s27, s27, 0
	s_mov_b32 m0, s37
	ds_read_b128 v[180:183], v171 offset:32768
	ds_read_b128 v[184:187], v171 offset:33792
	ds_read_b128 v[202:205], v171 offset:34816
	ds_read_b128 v[206:209], v171 offset:35840
	ds_read_b128 v[210:213], v171 offset:36864
	ds_read_b128 v[232:235], v171 offset:37888
	ds_read_b128 v[236:239], v171 offset:38912
	ds_read_b128 v[240:243], v171 offset:39936
	global_load_lds_dwordx4 v152, s[26:27]
	s_mov_b32 m0, s38
	s_nop 0
	global_load_lds_dwordx4 v148, s[26:27]
	s_waitcnt vmcnt(8)
	s_waitcnt lgkmcnt(0)
	s_setprio 1
	s_barrier
	v_mfma_f32_16x16x32_bf16 v[126:129], v[130:133], v[180:183], v[126:129]
	v_mfma_f32_16x16x32_bf16 v[118:121], v[138:141], v[180:183], v[118:121]
	v_mfma_f32_16x16x32_bf16 v[110:113], v[130:133], v[202:205], v[110:113]
	v_mfma_f32_16x16x32_bf16 v[102:105], v[138:141], v[202:205], v[102:105]
	v_mfma_f32_16x16x32_bf16 v[94:97], v[130:133], v[210:213], v[94:97]
	v_mfma_f32_16x16x32_bf16 v[86:89], v[138:141], v[210:213], v[86:89]
	v_mfma_f32_16x16x32_bf16 v[78:81], v[130:133], v[236:239], v[78:81]
	v_mfma_f32_16x16x32_bf16 v[70:73], v[138:141], v[236:239], v[70:73]
	v_mfma_f32_16x16x32_bf16 v[126:129], v[134:137], v[184:187], v[126:129]
	v_mfma_f32_16x16x32_bf16 v[118:121], v[142:145], v[184:187], v[118:121]
	v_mfma_f32_16x16x32_bf16 v[110:113], v[134:137], v[206:209], v[110:113]
	v_mfma_f32_16x16x32_bf16 v[102:105], v[142:145], v[206:209], v[102:105]
	v_mfma_f32_16x16x32_bf16 v[94:97], v[134:137], v[232:235], v[94:97]
	v_mfma_f32_16x16x32_bf16 v[86:89], v[142:145], v[232:235], v[86:89]
	v_mfma_f32_16x16x32_bf16 v[78:81], v[134:137], v[240:243], v[78:81]
	v_mfma_f32_16x16x32_bf16 v[70:73], v[142:145], v[240:243], v[70:73]
	s_setprio 0
	s_setprio 1
	v_mfma_f32_16x16x32_bf16 v[122:125], v[158:161], v[180:183], v[122:125]
	v_mfma_f32_16x16x32_bf16 v[114:117], v[172:175], v[180:183], v[114:117]
	v_mfma_f32_16x16x32_bf16 v[106:109], v[158:161], v[202:205], v[106:109]
	v_mfma_f32_16x16x32_bf16 v[98:101], v[172:175], v[202:205], v[98:101]
	v_mfma_f32_16x16x32_bf16 v[90:93], v[158:161], v[210:213], v[90:93]
	v_mfma_f32_16x16x32_bf16 v[82:85], v[172:175], v[210:213], v[82:85]
	v_mfma_f32_16x16x32_bf16 v[74:77], v[158:161], v[236:239], v[74:77]
	v_mfma_f32_16x16x32_bf16 v[66:69], v[172:175], v[236:239], v[66:69]
	v_mfma_f32_16x16x32_bf16 v[122:125], v[162:165], v[184:187], v[122:125]
	v_mfma_f32_16x16x32_bf16 v[114:117], v[176:179], v[184:187], v[114:117]
	v_mfma_f32_16x16x32_bf16 v[106:109], v[162:165], v[206:209], v[106:109]
	v_mfma_f32_16x16x32_bf16 v[98:101], v[176:179], v[206:209], v[98:101]
	v_mfma_f32_16x16x32_bf16 v[90:93], v[162:165], v[232:235], v[90:93]
	v_mfma_f32_16x16x32_bf16 v[82:85], v[176:179], v[232:235], v[82:85]
	v_mfma_f32_16x16x32_bf16 v[74:77], v[162:165], v[240:243], v[74:77]
	v_mfma_f32_16x16x32_bf16 v[66:69], v[176:179], v[240:243], v[66:69]
	s_setprio 0
	s_barrier
; #define PG8_STAGE(bufoff, gbase, voff) do { _Pragma("unroll") for (int _i = 0; _i < 2; ++_i) \
;         __builtin_amdgcn_global_load_lds((const unsigned*)((const char*)(gbase) + (voff)[_i]), (PG8_LAS unsigned*)(lds + (bufoff) + ldsw + _i * 8192), 16, 0, 0); } while (0)
; #define PG8_LDA(dst, b, h) do { _Pragma("unroll") for (int m = 0; m < 4; ++m) _Pragma("unroll") for (int k = 0; k < 2; ++k) dst[m][k] = *(const PG8_LAS bf16x8*)(lds + PG8_SA(b, h) + aoff + m * 2048 + k * 1024); } while (0)
; #define PG8_MMA(ai, bj, At, Bt) do { __builtin_amdgcn_s_setprio(1); _Pragma("unroll") for (int m = 0; m < 4; ++m) _Pragma("unroll") for (int n = 0; n < 2; ++n) _Pragma("unroll") for (int k = 0; k < 2; ++k) \
;         acc[ai][bj][m][n] = __builtin_amdgcn_mfma_f32_16x16x32_bf16(Bt[n][k], At[m][k], acc[ai][bj][m][n], 0, 0, 0); __builtin_amdgcn_s_setprio(0); } while (0)
; #define PG8_WAIT_V(n) asm volatile("s_waitcnt vmcnt(" #n ")" ::: "memory")
; #define PG8_WAIT_L(n) asm volatile("s_waitcnt lgkmcnt(" #n ")" ::: "memory")
; #define PG8_BAR __builtin_amdgcn_s_barrier()
; #define PG8_SCHED __builtin_amdgcn_sched_barrier(0)
; template <class Epi, class Sched, bool ALIGN_EPI = false, bool SP2 = false>
; __device__ __forceinline__ void gemm_phase(PG8_LAS unsigned char* lds, const Gemm g, const Sched& S, const Epi& E) {
;     ...
;         for (int t = 0; t < nt; t += 2) {
;     ...
;             PG8_LDA(At, 1, 1); PG8_STAGE(PG8_SB(1, 0), b3, voffB); PG8_STAGE(PG8_SB(1, 1), b3 + hstepB, voffB); PG8_STAGE(PG8_SA(1, 0), a3, voffA);
;             PG8_WAIT_V(8); PG8_WAIT_L(0); PG8_BAR; PG8_MMA(1, 0, At, B0); PG8_MMA(1, 1, At, B1); PG8_BAR; PG8_SCHED;
	s_add_i32 s26, s51, s30
	s_mov_b32 m0, s26
	ds_read_b128 v[180:183], v171 offset:49152
	ds_read_b128 v[184:187], v171 offset:50176
	ds_read_b128 v[202:205], v171 offset:51200
	ds_read_b128 v[206:209], v171 offset:52224
	ds_read_b128 v[210:213], v171 offset:53248
	ds_read_b128 v[232:235], v171 offset:54272
	ds_read_b128 v[236:239], v171 offset:55296
	ds_read_b128 v[240:243], v171 offset:56320
	global_load_lds_dwordx4 v150, s[60:61]
	s_add_i32 m0, s26, 0x2000
	s_add_u32 s24, s24, 0x40080
	s_addc_u32 s25, s25, 0
	s_add_i32 s26, s52, s30
	global_load_lds_dwordx4 v146, s[60:61]
	s_mov_b32 m0, s26
	s_nop 0
	global_load_lds_dwordx4 v150, s[24:25]
	s_add_i32 m0, s26, 0x2000
	s_nop 0
	global_load_lds_dwordx4 v146, s[24:25]
	s_mov_b32 m0, s39
	s_nop 0
	global_load_lds_dwordx4 v152, s[62:63]
	s_mov_b32 m0, s40
	s_nop 0
	global_load_lds_dwordx4 v148, s[62:63]
	s_waitcnt vmcnt(8)
	s_waitcnt lgkmcnt(0)
	s_setprio 1
	s_barrier
	v_mfma_f32_16x16x32_bf16 v[62:65], v[130:133], v[180:183], v[62:65]
	v_mfma_f32_16x16x32_bf16 v[54:57], v[138:141], v[180:183], v[54:57]
	v_mfma_f32_16x16x32_bf16 v[46:49], v[130:133], v[202:205], v[46:49]
	v_mfma_f32_16x16x32_bf16 v[38:41], v[138:141], v[202:205], v[38:41]
	v_mfma_f32_16x16x32_bf16 v[30:33], v[130:133], v[210:213], v[30:33]
	v_mfma_f32_16x16x32_bf16 v[22:25], v[138:141], v[210:213], v[22:25]
	v_mfma_f32_16x16x32_bf16 v[14:17], v[130:133], v[236:239], v[14:17]
	v_mfma_f32_16x16x32_bf16 v[6:9], v[138:141], v[236:239], v[6:9]
	v_mfma_f32_16x16x32_bf16 v[62:65], v[134:137], v[184:187], v[62:65]
	v_mfma_f32_16x16x32_bf16 v[54:57], v[142:145], v[184:187], v[54:57]
	v_mfma_f32_16x16x32_bf16 v[46:49], v[134:137], v[206:209], v[46:49]
	v_mfma_f32_16x16x32_bf16 v[38:41], v[142:145], v[206:209], v[38:41]
	v_mfma_f32_16x16x32_bf16 v[30:33], v[134:137], v[232:235], v[30:33]
	v_mfma_f32_16x16x32_bf16 v[22:25], v[142:145], v[232:235], v[22:25]
	v_mfma_f32_16x16x32_bf16 v[14:17], v[134:137], v[240:243], v[14:17]
	v_mfma_f32_16x16x32_bf16 v[6:9], v[142:145], v[240:243], v[6:9]
	s_setprio 0
	s_setprio 1
	v_mfma_f32_16x16x32_bf16 v[58:61], v[158:161], v[180:183], v[58:61]
	v_mfma_f32_16x16x32_bf16 v[50:53], v[172:175], v[180:183], v[50:53]
	v_mfma_f32_16x16x32_bf16 v[42:45], v[158:161], v[202:205], v[42:45]
	v_mfma_f32_16x16x32_bf16 v[34:37], v[172:175], v[202:205], v[34:37]
	v_mfma_f32_16x16x32_bf16 v[26:29], v[158:161], v[210:213], v[26:29]
	v_mfma_f32_16x16x32_bf16 v[18:21], v[172:175], v[210:213], v[18:21]
	v_mfma_f32_16x16x32_bf16 v[10:13], v[158:161], v[236:239], v[10:13]
	v_mfma_f32_16x16x32_bf16 v[2:5], v[172:175], v[236:239], v[2:5]
	v_mfma_f32_16x16x32_bf16 v[58:61], v[162:165], v[184:187], v[58:61]
	v_mfma_f32_16x16x32_bf16 v[50:53], v[176:179], v[184:187], v[50:53]
	v_mfma_f32_16x16x32_bf16 v[42:45], v[162:165], v[206:209], v[42:45]
	v_mfma_f32_16x16x32_bf16 v[34:37], v[176:179], v[206:209], v[34:37]
	v_mfma_f32_16x16x32_bf16 v[26:29], v[162:165], v[232:235], v[26:29]
	v_mfma_f32_16x16x32_bf16 v[18:21], v[176:179], v[232:235], v[18:21]
	v_mfma_f32_16x16x32_bf16 v[10:13], v[162:165], v[240:243], v[10:13]
	v_mfma_f32_16x16x32_bf16 v[2:5], v[176:179], v[240:243], v[2:5]
	s_setprio 0
	s_barrier
	s_add_i32 s50, s50, 2
	s_add_u32 s22, s22, 0x100
	s_addc_u32 s23, s23, 0
	s_add_u32 s48, s48, 0x100
	s_addc_u32 s49, s49, 0
	s_cmp_gt_u32 s50, 13
	s_cbranch_scc0 .LBB0_1190
	s_and_b64 vcc, exec, s[18:19]
	s_cbranch_vccz .LBB0_1193
	s_barrier

; #define PG8_STAGE(bufoff, gbase, voff) do { _Pragma("unroll") for (int _i = 0; _i < 2; ++_i) \
;         __builtin_amdgcn_global_load_lds((const unsigned*)((const char*)(gbase) + (voff)[_i]), (PG8_LAS unsigned*)(lds + (bufoff) + ldsw + _i * 8192), 16, 0, 0); } while (0)
; #define PG8_LDA(dst, b, h) do { _Pragma("unroll") for (int m = 0; m < 4; ++m) _Pragma("unroll") for (int k = 0; k < 2; ++k) dst[m][k] = *(const PG8_LAS bf16x8*)(lds + PG8_SA(b, h) + aoff + m * 2048 + k * 1024); } while (0)
; #define PG8_LDB(dst, b, h) do { _Pragma("unroll") for (int n = 0; n < 2; ++n) _Pragma("unroll") for (int k = 0; k < 2; ++k) dst[n][k] = *(const PG8_LAS bf16x8*)(lds + PG8_SB(b, h) + boff + n * 2048 + k * 1024); } while (0)
; #define PG8_MMA(ai, bj, At, Bt) do { __builtin_amdgcn_s_setprio(1); _Pragma("unroll") for (int m = 0; m < 4; ++m) _Pragma("unroll") for (int n = 0; n < 2; ++n) _Pragma("unroll") for (int k = 0; k < 2; ++k) \
;         acc[ai][bj][m][n] = __builtin_amdgcn_mfma_f32_16x16x32_bf16(Bt[n][k], At[m][k], acc[ai][bj][m][n], 0, 0, 0); __builtin_amdgcn_s_setprio(0); } while (0)
; #define PG8_WAIT_V(n) asm volatile("s_waitcnt vmcnt(" #n ")" ::: "memory")
; #define PG8_WAIT_L(n) asm volatile("s_waitcnt lgkmcnt(" #n ")" ::: "memory")
; #define PG8_BAR __builtin_amdgcn_s_barrier()
; #define PG8_SCHED __builtin_amdgcn_sched_barrier(0)
; template <class Epi, class Sched, bool ALIGN_EPI = false, bool SP2 = false>
; __device__ __forceinline__ void gemm_phase(PG8_LAS unsigned char* lds, const Gemm g, const Sched& S, const Epi& E) {
;     ...
;             PG8_LDB(B0, 0, 0); PG8_LDB(B1, 0, 1); PG8_SCHED; PG8_LDA(At, 0, 0); PG8_STAGE(PG8_SA(1, 1), a1 + hstepA, voffA);
;             PG8_WAIT_V(8); PG8_WAIT_L(0); PG8_BAR; PG8_MMA(0, 0, At, B0); PG8_MMA(0, 1, At, B1); PG8_BAR; PG8_SCHED;
;             PG8_LDA(At, 0, 1); PG8_STAGE(PG8_SB(0, 0), b2, voffB); PG8_STAGE(PG8_SB(0, 1), b2 + hstepB, voffB); PG8_STAGE(PG8_SA(0, 0), a2, voffA);
.LBB0_1270:
	s_add_u32 s28, s26, 0xfffc0080
	s_addc_u32 s29, s27, -1
	s_add_i32 s52, 0, 0x10000
	s_cmp_eq_u32 s51, 12
	s_cselect_b32 s31, s17, s29
	s_cselect_b32 s30, s23, s28
	s_cselect_b32 s29, s15, s50
	s_cselect_b32 s28, s25, s49
	s_add_i32 s54, 0, 0x14000
	v_add_u32_e32 v142, s52, v186
	v_add_u32_e32 v172, s54, v186
	ds_read_b128 v[130:133], v142
	ds_read_b128 v[134:137], v142 offset:1024
	ds_read_b128 v[138:141], v142 offset:2048
	ds_read_b128 v[142:145], v142 offset:3072
	ds_read_b128 v[146:149], v172
	ds_read_b128 v[150:153], v172 offset:1024
	ds_read_b128 v[168:171], v172 offset:2048
	ds_read_b128 v[172:175], v172 offset:3072
	s_add_i32 m0, s39, 0xc000
	ds_read_b128 v[176:179], v200
	ds_read_b128 v[180:183], v200 offset:1024
	ds_read_b128 v[202:205], v200 offset:2048
	ds_read_b128 v[206:209], v200 offset:3072
	ds_read_b128 v[210:213], v200 offset:4096
	ds_read_b128 v[232:235], v200 offset:5120
	ds_read_b128 v[236:239], v200 offset:6144
	ds_read_b128 v[240:243], v200 offset:7168
	global_load_lds_dwordx4 v164, s[26:27]
	s_add_i32 m0, s39, 0xe000
	s_nop 0
	global_load_lds_dwordx4 v166, s[26:27]
	s_waitcnt vmcnt(8)
	s_waitcnt lgkmcnt(0)
	s_setprio 1
	s_barrier
	v_mfma_f32_16x16x32_bf16 v[126:129], v[130:133], v[176:179], v[126:129]
	v_mfma_f32_16x16x32_bf16 v[122:125], v[138:141], v[176:179], v[122:125]
	v_mfma_f32_16x16x32_bf16 v[110:113], v[130:133], v[202:205], v[110:113]
	v_mfma_f32_16x16x32_bf16 v[106:109], v[138:141], v[202:205], v[106:109]
	v_mfma_f32_16x16x32_bf16 v[94:97], v[130:133], v[210:213], v[94:97]
	v_mfma_f32_16x16x32_bf16 v[90:93], v[138:141], v[210:213], v[90:93]
	v_mfma_f32_16x16x32_bf16 v[78:81], v[130:133], v[236:239], v[78:81]
	v_mfma_f32_16x16x32_bf16 v[74:77], v[138:141], v[236:239], v[74:77]
	v_mfma_f32_16x16x32_bf16 v[126:129], v[134:137], v[180:183], v[126:129]
	v_mfma_f32_16x16x32_bf16 v[122:125], v[142:145], v[180:183], v[122:125]
	v_mfma_f32_16x16x32_bf16 v[110:113], v[134:137], v[206:209], v[110:113]
	v_mfma_f32_16x16x32_bf16 v[106:109], v[142:145], v[206:209], v[106:109]
	v_mfma_f32_16x16x32_bf16 v[94:97], v[134:137], v[232:235], v[94:97]
	v_mfma_f32_16x16x32_bf16 v[90:93], v[142:145], v[232:235], v[90:93]
	v_mfma_f32_16x16x32_bf16 v[78:81], v[134:137], v[240:243], v[78:81]
	v_mfma_f32_16x16x32_bf16 v[74:77], v[142:145], v[240:243], v[74:77]
	s_setprio 0
	s_setprio 1
	v_mfma_f32_16x16x32_bf16 v[118:121], v[146:149], v[176:179], v[118:121]
	v_mfma_f32_16x16x32_bf16 v[114:117], v[168:171], v[176:179], v[114:117]
	v_mfma_f32_16x16x32_bf16 v[102:105], v[146:149], v[202:205], v[102:105]
	v_mfma_f32_16x16x32_bf16 v[98:101], v[168:171], v[202:205], v[98:101]
	v_mfma_f32_16x16x32_bf16 v[86:89], v[146:149], v[210:213], v[86:89]
	v_mfma_f32_16x16x32_bf16 v[82:85], v[168:171], v[210:213], v[82:85]
	v_mfma_f32_16x16x32_bf16 v[70:73], v[146:149], v[236:239], v[70:73]
	v_mfma_f32_16x16x32_bf16 v[66:69], v[168:171], v[236:239], v[66:69]
	v_mfma_f32_16x16x32_bf16 v[118:121], v[150:153], v[180:183], v[118:121]
	v_mfma_f32_16x16x32_bf16 v[114:117], v[172:175], v[180:183], v[114:117]
	v_mfma_f32_16x16x32_bf16 v[102:105], v[150:153], v[206:209], v[102:105]
	v_mfma_f32_16x16x32_bf16 v[98:101], v[172:175], v[206:209], v[98:101]
	v_mfma_f32_16x16x32_bf16 v[86:89], v[150:153], v[232:235], v[86:89]
	v_mfma_f32_16x16x32_bf16 v[82:85], v[172:175], v[232:235], v[82:85]
	v_mfma_f32_16x16x32_bf16 v[70:73], v[150:153], v[240:243], v[70:73]
	v_mfma_f32_16x16x32_bf16 v[66:69], v[172:175], v[240:243], v[66:69]
	s_setprio 0
	s_barrier
	s_add_i32 s52, s52, s38
	s_mov_b32 m0, s52
	ds_read_b128 v[176:179], v200 offset:16384
	ds_read_b128 v[180:183], v200 offset:17408
	ds_read_b128 v[202:205], v200 offset:18432
	ds_read_b128 v[206:209], v200 offset:19456
	ds_read_b128 v[210:213], v200 offset:20480
	ds_read_b128 v[232:235], v200 offset:21504
	ds_read_b128 v[236:239], v200 offset:22528
	ds_read_b128 v[240:243], v200 offset:23552
	s_add_u32 s60, s28, 0x80
	s_addc_u32 s61, s29, 0
	s_add_u32 s62, s30, 0x80
	s_addc_u32 s63, s31, 0
	global_load_lds_dwordx4 v156, s[28:29]
	s_add_i32 m0, s52, 0x2000
	s_add_u32 s52, s28, 0x40000
	s_addc_u32 s53, s29, 0
	s_add_i32 s54, s54, s38
	global_load_lds_dwordx4 v160, s[28:29]
	s_mov_b32 m0, s54
	s_nop 0
	global_load_lds_dwordx4 v156, s[52:53]
	s_add_i32 m0, s54, 0x2000
	s_nop 0
	global_load_lds_dwordx4 v160, s[52:53]
	s_mov_b32 m0, s39
	s_nop 0
	global_load_lds_dwordx4 v154, s[30:31]
	s_mov_b32 m0, s40
	s_nop 0
	global_load_lds_dwordx4 v158, s[30:31]
	s_waitcnt vmcnt(8)
	s_waitcnt lgkmcnt(0)
	s_setprio 1
	s_barrier
; #define PG8_STAGE(bufoff, gbase, voff) do { _Pragma("unroll") for (int _i = 0; _i < 2; ++_i) \
;         __builtin_amdgcn_global_load_lds((const unsigned*)((const char*)(gbase) + (voff)[_i]), (PG8_LAS unsigned*)(lds + (bufoff) + ldsw + _i * 8192), 16, 0, 0); } while (0)
; #define PG8_LDA(dst, b, h) do { _Pragma("unroll") for (int m = 0; m < 4; ++m) _Pragma("unroll") for (int k = 0; k < 2; ++k) dst[m][k] = *(const PG8_LAS bf16x8*)(lds + PG8_SA(b, h) + aoff + m * 2048 + k * 1024); } while (0)
; #define PG8_LDB(dst, b, h) do { _Pragma("unroll") for (int n = 0; n < 2; ++n) _Pragma("unroll") for (int k = 0; k < 2; ++k) dst[n][k] = *(const PG8_LAS bf16x8*)(lds + PG8_SB(b, h) + boff + n * 2048 + k * 1024); } while (0)
; #define PG8_MMA(ai, bj, At, Bt) do { __builtin_amdgcn_s_setprio(1); _Pragma("unroll") for (int m = 0; m < 4; ++m) _Pragma("unroll") for (int n = 0; n < 2; ++n) _Pragma("unroll") for (int k = 0; k < 2; ++k) \
;         acc[ai][bj][m][n] = __builtin_amdgcn_mfma_f32_16x16x32_bf16(Bt[n][k], At[m][k], acc[ai][bj][m][n], 0, 0, 0); __builtin_amdgcn_s_setprio(0); } while (0)
; #define PG8_WAIT_V(n) asm volatile("s_waitcnt vmcnt(" #n ")" ::: "memory")
; #define PG8_WAIT_L(n) asm volatile("s_waitcnt lgkmcnt(" #n ")" ::: "memory")
; #define PG8_BAR __builtin_amdgcn_s_barrier()
; #define PG8_SCHED __builtin_amdgcn_sched_barrier(0)
; template <class Epi, class Sched, bool ALIGN_EPI = false, bool SP2 = false>
; __device__ __forceinline__ void gemm_phase(PG8_LAS unsigned char* lds, const Gemm g, const Sched& S, const Epi& E) {
;     ...
;             PG8_WAIT_V(8); PG8_WAIT_L(0); PG8_BAR; PG8_MMA(1, 0, At, B0); PG8_MMA(1, 1, At, B1); PG8_BAR; PG8_SCHED;
;             PG8_LDB(B0, 1, 0); PG8_LDB(B1, 1, 1); PG8_SCHED; PG8_LDA(At, 1, 0); PG8_STAGE(PG8_SA(0, 1), a2 + hstepA, voffA);
;             PG8_WAIT_V(8); PG8_WAIT_L(0); PG8_BAR; PG8_MMA(0, 0, At, B0); PG8_MMA(0, 1, At, B1); PG8_BAR; PG8_SCHED;
	v_mfma_f32_16x16x32_bf16 v[62:65], v[130:133], v[176:179], v[62:65]
	v_mfma_f32_16x16x32_bf16 v[58:61], v[138:141], v[176:179], v[58:61]
	v_mfma_f32_16x16x32_bf16 v[46:49], v[130:133], v[202:205], v[46:49]
	v_mfma_f32_16x16x32_bf16 v[42:45], v[138:141], v[202:205], v[42:45]
	v_mfma_f32_16x16x32_bf16 v[30:33], v[130:133], v[210:213], v[30:33]
	v_mfma_f32_16x16x32_bf16 v[26:29], v[138:141], v[210:213], v[26:29]
	v_mfma_f32_16x16x32_bf16 v[14:17], v[130:133], v[236:239], v[14:17]
	v_mfma_f32_16x16x32_bf16 v[10:13], v[138:141], v[236:239], v[10:13]
	v_mfma_f32_16x16x32_bf16 v[62:65], v[134:137], v[180:183], v[62:65]
	v_mfma_f32_16x16x32_bf16 v[58:61], v[142:145], v[180:183], v[58:61]
	v_mfma_f32_16x16x32_bf16 v[46:49], v[134:137], v[206:209], v[46:49]
	v_mfma_f32_16x16x32_bf16 v[42:45], v[142:145], v[206:209], v[42:45]
	v_mfma_f32_16x16x32_bf16 v[30:33], v[134:137], v[232:235], v[30:33]
	v_mfma_f32_16x16x32_bf16 v[26:29], v[142:145], v[232:235], v[26:29]
	v_mfma_f32_16x16x32_bf16 v[14:17], v[134:137], v[240:243], v[14:17]
	v_mfma_f32_16x16x32_bf16 v[10:13], v[142:145], v[240:243], v[10:13]
	s_setprio 0
	s_setprio 1
	v_mfma_f32_16x16x32_bf16 v[54:57], v[146:149], v[176:179], v[54:57]
	v_mfma_f32_16x16x32_bf16 v[50:53], v[168:171], v[176:179], v[50:53]
	v_mfma_f32_16x16x32_bf16 v[38:41], v[146:149], v[202:205], v[38:41]
	v_mfma_f32_16x16x32_bf16 v[34:37], v[168:171], v[202:205], v[34:37]
	v_mfma_f32_16x16x32_bf16 v[22:25], v[146:149], v[210:213], v[22:25]
	v_mfma_f32_16x16x32_bf16 v[18:21], v[168:171], v[210:213], v[18:21]
	v_mfma_f32_16x16x32_bf16 v[6:9], v[146:149], v[236:239], v[6:9]
	v_mfma_f32_16x16x32_bf16 v[2:5], v[168:171], v[236:239], v[2:5]
	v_mfma_f32_16x16x32_bf16 v[54:57], v[150:153], v[180:183], v[54:57]
	v_mfma_f32_16x16x32_bf16 v[50:53], v[172:175], v[180:183], v[50:53]
	v_mfma_f32_16x16x32_bf16 v[38:41], v[150:153], v[206:209], v[38:41]
	v_mfma_f32_16x16x32_bf16 v[34:37], v[172:175], v[206:209], v[34:37]
	v_mfma_f32_16x16x32_bf16 v[22:25], v[150:153], v[232:235], v[22:25]
	v_mfma_f32_16x16x32_bf16 v[18:21], v[172:175], v[232:235], v[18:21]
	v_mfma_f32_16x16x32_bf16 v[6:9], v[150:153], v[240:243], v[6:9]
	v_mfma_f32_16x16x32_bf16 v[2:5], v[172:175], v[240:243], v[2:5]
	s_setprio 0
	s_barrier
	s_add_i32 s52, 0, 0x18000
	s_add_i32 s53, 0, 0x1c000
	v_add_u32_e32 v142, s52, v186
	v_add_u32_e32 v172, s53, v186
	ds_read_b128 v[130:133], v142
	ds_read_b128 v[134:137], v142 offset:1024
	ds_read_b128 v[138:141], v142 offset:2048
	ds_read_b128 v[142:145], v142 offset:3072
	ds_read_b128 v[146:149], v172
	ds_read_b128 v[150:153], v172 offset:1024
	ds_read_b128 v[168:171], v172 offset:2048
	ds_read_b128 v[172:175], v172 offset:3072
	s_add_u32 s30, s30, 0x40000
	s_addc_u32 s31, s31, 0
	s_mov_b32 m0, s41
	ds_read_b128 v[176:179], v200 offset:32768
	ds_read_b128 v[180:183], v200 offset:33792
	ds_read_b128 v[202:205], v200 offset:34816
	ds_read_b128 v[206:209], v200 offset:35840
	ds_read_b128 v[210:213], v200 offset:36864
	ds_read_b128 v[232:235], v200 offset:37888
	ds_read_b128 v[236:239], v200 offset:38912
	ds_read_b128 v[240:243], v200 offset:39936
	global_load_lds_dwordx4 v154, s[30:31]
	s_mov_b32 m0, s42
	s_nop 0
	global_load_lds_dwordx4 v158, s[30:31]
	s_waitcnt vmcnt(8)
	s_waitcnt lgkmcnt(0)
	s_setprio 1
	s_barrier
	v_mfma_f32_16x16x32_bf16 v[126:129], v[130:133], v[176:179], v[126:129]
	v_mfma_f32_16x16x32_bf16 v[122:125], v[138:141], v[176:179], v[122:125]
	v_mfma_f32_16x16x32_bf16 v[110:113], v[130:133], v[202:205], v[110:113]
	v_mfma_f32_16x16x32_bf16 v[106:109], v[138:141], v[202:205], v[106:109]
	v_mfma_f32_16x16x32_bf16 v[94:97], v[130:133], v[210:213], v[94:97]
	v_mfma_f32_16x16x32_bf16 v[90:93], v[138:141], v[210:213], v[90:93]
	v_mfma_f32_16x16x32_bf16 v[78:81], v[130:133], v[236:239], v[78:81]
	v_mfma_f32_16x16x32_bf16 v[74:77], v[138:141], v[236:239], v[74:77]
	v_mfma_f32_16x16x32_bf16 v[126:129], v[134:137], v[180:183], v[126:129]
	v_mfma_f32_16x16x32_bf16 v[122:125], v[142:145], v[180:183], v[122:125]
	v_mfma_f32_16x16x32_bf16 v[110:113], v[134:137], v[206:209], v[110:113]
	v_mfma_f32_16x16x32_bf16 v[106:109], v[142:145], v[206:209], v[106:109]
	v_mfma_f32_16x16x32_bf16 v[94:97], v[134:137], v[232:235], v[94:97]
	v_mfma_f32_16x16x32_bf16 v[90:93], v[142:145], v[232:235], v[90:93]
	v_mfma_f32_16x16x32_bf16 v[78:81], v[134:137], v[240:243], v[78:81]
	v_mfma_f32_16x16x32_bf16 v[74:77], v[142:145], v[240:243], v[74:77]
	s_setprio 0
	s_setprio 1
	v_mfma_f32_16x16x32_bf16 v[118:121], v[146:149], v[176:179], v[118:121]
	v_mfma_f32_16x16x32_bf16 v[114:117], v[168:171], v[176:179], v[114:117]
	v_mfma_f32_16x16x32_bf16 v[102:105], v[146:149], v[202:205], v[102:105]
	v_mfma_f32_16x16x32_bf16 v[98:101], v[168:171], v[202:205], v[98:101]
	v_mfma_f32_16x16x32_bf16 v[86:89], v[146:149], v[210:213], v[86:89]
	v_mfma_f32_16x16x32_bf16 v[82:85], v[168:171], v[210:213], v[82:85]
	v_mfma_f32_16x16x32_bf16 v[70:73], v[146:149], v[236:239], v[70:73]
	v_mfma_f32_16x16x32_bf16 v[66:69], v[168:171], v[236:239], v[66:69]
	v_mfma_f32_16x16x32_bf16 v[118:121], v[150:153], v[180:183], v[118:121]
	v_mfma_f32_16x16x32_bf16 v[114:117], v[172:175], v[180:183], v[114:117]
	v_mfma_f32_16x16x32_bf16 v[102:105], v[150:153], v[206:209], v[102:105]
	v_mfma_f32_16x16x32_bf16 v[98:101], v[172:175], v[206:209], v[98:101]
	v_mfma_f32_16x16x32_bf16 v[86:89], v[150:153], v[232:235], v[86:89]
	v_mfma_f32_16x16x32_bf16 v[82:85], v[172:175], v[232:235], v[82:85]
	v_mfma_f32_16x16x32_bf16 v[70:73], v[150:153], v[240:243], v[70:73]
	v_mfma_f32_16x16x32_bf16 v[66:69], v[172:175], v[240:243], v[66:69]
	s_setprio 0
	s_barrier
; #define PG8_STAGE(bufoff, gbase, voff) do { _Pragma("unroll") for (int _i = 0; _i < 2; ++_i) \
;         __builtin_amdgcn_global_load_lds((const unsigned*)((const char*)(gbase) + (voff)[_i]), (PG8_LAS unsigned*)(lds + (bufoff) + ldsw + _i * 8192), 16, 0, 0); } while (0)
; #define PG8_LDA(dst, b, h) do { _Pragma("unroll") for (int m = 0; m < 4; ++m) _Pragma("unroll") for (int k = 0; k < 2; ++k) dst[m][k] = *(const PG8_LAS bf16x8*)(lds + PG8_SA(b, h) + aoff + m * 2048 + k * 1024); } while (0)
; #define PG8_MMA(ai, bj, At, Bt) do { __builtin_amdgcn_s_setprio(1); _Pragma("unroll") for (int m = 0; m < 4; ++m) _Pragma("unroll") for (int n = 0; n < 2; ++n) _Pragma("unroll") for (int k = 0; k < 2; ++k) \
;         acc[ai][bj][m][n] = __builtin_amdgcn_mfma_f32_16x16x32_bf16(Bt[n][k], At[m][k], acc[ai][bj][m][n], 0, 0, 0); __builtin_amdgcn_s_setprio(0); } while (0)
; #define PG8_WAIT_V(n) asm volatile("s_waitcnt vmcnt(" #n ")" ::: "memory")
; #define PG8_WAIT_L(n) asm volatile("s_waitcnt lgkmcnt(" #n ")" ::: "memory")
; #define PG8_BAR __builtin_amdgcn_s_barrier()
; #define PG8_SCHED __builtin_amdgcn_sched_barrier(0)
; template <class Epi, class Sched, bool ALIGN_EPI = false, bool SP2 = false>
; __device__ __forceinline__ void gemm_phase(PG8_LAS unsigned char* lds, const Gemm g, const Sched& S, const Epi& E) {
;     ...
;             PG8_LDA(At, 1, 1); PG8_STAGE(PG8_SB(1, 0), b3, voffB); PG8_STAGE(PG8_SB(1, 1), b3 + hstepB, voffB); PG8_STAGE(PG8_SA(1, 0), a3, voffA);
;             PG8_WAIT_V(8); PG8_WAIT_L(0); PG8_BAR; PG8_MMA(1, 0, At, B0); PG8_MMA(1, 1, At, B1); PG8_BAR; PG8_SCHED;
	s_add_i32 s30, s52, s38
	s_mov_b32 m0, s30
	ds_read_b128 v[176:179], v200 offset:49152
	ds_read_b128 v[180:183], v200 offset:50176
	ds_read_b128 v[202:205], v200 offset:51200
	ds_read_b128 v[206:209], v200 offset:52224
	ds_read_b128 v[210:213], v200 offset:53248
	ds_read_b128 v[232:235], v200 offset:54272
	ds_read_b128 v[236:239], v200 offset:55296
	ds_read_b128 v[240:243], v200 offset:56320
	global_load_lds_dwordx4 v156, s[60:61]
	s_add_i32 m0, s30, 0x2000
	s_add_u32 s28, s28, 0x40080
	s_addc_u32 s29, s29, 0
	s_add_i32 s30, s53, s38
	global_load_lds_dwordx4 v160, s[60:61]
	s_mov_b32 m0, s30
	s_nop 0
	global_load_lds_dwordx4 v156, s[28:29]
	s_add_i32 m0, s30, 0x2000
	s_nop 0
	global_load_lds_dwordx4 v160, s[28:29]
	s_mov_b32 m0, s44
	s_nop 0
	global_load_lds_dwordx4 v154, s[62:63]
	s_mov_b32 m0, s45
	s_nop 0
	global_load_lds_dwordx4 v158, s[62:63]
	s_waitcnt vmcnt(8)
	s_waitcnt lgkmcnt(0)
	s_setprio 1
	s_barrier
	v_mfma_f32_16x16x32_bf16 v[62:65], v[130:133], v[176:179], v[62:65]
	v_mfma_f32_16x16x32_bf16 v[58:61], v[138:141], v[176:179], v[58:61]
	v_mfma_f32_16x16x32_bf16 v[46:49], v[130:133], v[202:205], v[46:49]
	v_mfma_f32_16x16x32_bf16 v[42:45], v[138:141], v[202:205], v[42:45]
	v_mfma_f32_16x16x32_bf16 v[30:33], v[130:133], v[210:213], v[30:33]
	v_mfma_f32_16x16x32_bf16 v[26:29], v[138:141], v[210:213], v[26:29]
	v_mfma_f32_16x16x32_bf16 v[14:17], v[130:133], v[236:239], v[14:17]
	v_mfma_f32_16x16x32_bf16 v[10:13], v[138:141], v[236:239], v[10:13]
	v_mfma_f32_16x16x32_bf16 v[62:65], v[134:137], v[180:183], v[62:65]
	v_mfma_f32_16x16x32_bf16 v[58:61], v[142:145], v[180:183], v[58:61]
	v_mfma_f32_16x16x32_bf16 v[46:49], v[134:137], v[206:209], v[46:49]
	v_mfma_f32_16x16x32_bf16 v[42:45], v[142:145], v[206:209], v[42:45]
	v_mfma_f32_16x16x32_bf16 v[30:33], v[134:137], v[232:235], v[30:33]
	v_mfma_f32_16x16x32_bf16 v[26:29], v[142:145], v[232:235], v[26:29]
	v_mfma_f32_16x16x32_bf16 v[14:17], v[134:137], v[240:243], v[14:17]
	v_mfma_f32_16x16x32_bf16 v[10:13], v[142:145], v[240:243], v[10:13]
	s_setprio 0
	s_setprio 1
	v_mfma_f32_16x16x32_bf16 v[54:57], v[146:149], v[176:179], v[54:57]
	v_mfma_f32_16x16x32_bf16 v[50:53], v[168:171], v[176:179], v[50:53]
	v_mfma_f32_16x16x32_bf16 v[38:41], v[146:149], v[202:205], v[38:41]
	v_mfma_f32_16x16x32_bf16 v[34:37], v[168:171], v[202:205], v[34:37]
	v_mfma_f32_16x16x32_bf16 v[22:25], v[146:149], v[210:213], v[22:25]
	v_mfma_f32_16x16x32_bf16 v[18:21], v[168:171], v[210:213], v[18:21]
	v_mfma_f32_16x16x32_bf16 v[6:9], v[146:149], v[236:239], v[6:9]
	v_mfma_f32_16x16x32_bf16 v[2:5], v[168:171], v[236:239], v[2:5]
	v_mfma_f32_16x16x32_bf16 v[54:57], v[150:153], v[180:183], v[54:57]
	v_mfma_f32_16x16x32_bf16 v[50:53], v[172:175], v[180:183], v[50:53]
	v_mfma_f32_16x16x32_bf16 v[38:41], v[150:153], v[206:209], v[38:41]
	v_mfma_f32_16x16x32_bf16 v[34:37], v[172:175], v[206:209], v[34:37]
	v_mfma_f32_16x16x32_bf16 v[22:25], v[150:153], v[232:235], v[22:25]
	v_mfma_f32_16x16x32_bf16 v[18:21], v[172:175], v[232:235], v[18:21]
	v_mfma_f32_16x16x32_bf16 v[6:9], v[150:153], v[240:243], v[6:9]
	v_mfma_f32_16x16x32_bf16 v[2:5], v[172:175], v[240:243], v[2:5]
	s_setprio 0
	s_barrier
	s_add_i32 s51, s51, 2
	s_add_u32 s26, s26, 0x100
	s_addc_u32 s27, s27, 0
	s_add_u32 s49, s49, 0x100
	s_addc_u32 s50, s50, 0
	s_cmp_gt_u32 s51, 13
	s_cbranch_scc0 .LBB0_1270
	s_and_b64 vcc, exec, s[12:13]
	s_cbranch_vccz .LBB0_1273
	s_barrier

; #define PG8_STAGE(bufoff, gbase, voff) do { _Pragma("unroll") for (int _i = 0; _i < 2; ++_i) \
;         __builtin_amdgcn_global_load_lds((const unsigned*)((const char*)(gbase) + (voff)[_i]), (PG8_LAS unsigned*)(lds + (bufoff) + ldsw + _i * 8192), 16, 0, 0); } while (0)
; #define PG8_LDA(dst, b, h) do { _Pragma("unroll") for (int m = 0; m < 4; ++m) _Pragma("unroll") for (int k = 0; k < 2; ++k) dst[m][k] = *(const PG8_LAS bf16x8*)(lds + PG8_SA(b, h) + aoff + m * 2048 + k * 1024); } while (0)
; #define PG8_LDB(dst, b, h) do { _Pragma("unroll") for (int n = 0; n < 2; ++n) _Pragma("unroll") for (int k = 0; k < 2; ++k) dst[n][k] = *(const PG8_LAS bf16x8*)(lds + PG8_SB(b, h) + boff + n * 2048 + k * 1024); } while (0)
; #define PG8_BAR __builtin_amdgcn_s_barrier()
; template <class Epi, class Sched, bool ALIGN_EPI = false, bool SP2 = false>
; __device__ __forceinline__ void gemm_phase(PG8_LAS unsigned char* lds, const Gemm g, const Sched& S, const Epi& E) {
;     ...
;             const bool last = (t == nt - 2);
;             const char* a1 = cA + (size_t)(t + 1) * kstep;
;             const char* a2 = last ? nA : cA + (size_t)(t + 2) * kstep; const char* b2 = last ? nB : cB + (size_t)(t + 2) * kstep;
;             const char* a3 = a2 + kstep; const char* b3 = b2 + kstep;
;             if (last && has_next) S.a_ready(nxt);
;             if constexpr (SP2) {
;             PG8_LDB(B0, 0, 0); PG8_LDB(B1, 0, 1); PG8_SCHED; PG8_LDA(At, 0, 0); PG8_STAGE(PG8_SA(1, 1), a1 + hstepA, voffA);
;             PG8_WAIT_V(8); PG8_WAIT_L(0); PG8_BAR; PG8_MMA(0, 0, At, B0); PG8_MMA(0, 1, At, B1); PG8_BAR; PG8_SCHED;
;             PG8_LDA(At, 0, 1); PG8_STAGE(PG8_SB(0, 0), b2, voffB); PG8_STAGE(PG8_SB(0, 1), b2 + hstepB, voffB); PG8_STAGE(PG8_SA(0, 0), a2, voffA);
;             PG8_WAIT_V(8); PG8_WAIT_L(0); PG8_BAR; PG8_MMA(1, 0, At, B0); PG8_MMA(1, 1, At, B1); PG8_BAR; PG8_SCHED;
;             PG8_LDB(B0, 1, 0); PG8_LDB(B1, 1, 1); PG8_SCHED; PG8_LDA(At, 1, 0); PG8_STAGE(PG8_SA(0, 1), a2 + hstepA, voffA);
;             PG8_WAIT_V(8); PG8_WAIT_L(0); PG8_BAR; PG8_MMA(0, 0, At, B0); PG8_MMA(0, 1, At, B1); PG8_BAR; PG8_SCHED;
;             PG8_LDA(At, 1, 1); PG8_STAGE(PG8_SB(1, 0), b3, voffB); PG8_STAGE(PG8_SB(1, 1), b3 + hstepB, voffB); PG8_STAGE(PG8_SA(1, 0), a3, voffA);
;             PG8_WAIT_V(8); PG8_WAIT_L(0); PG8_BAR; PG8_MMA(1, 0, At, B0); PG8_MMA(1, 1, At, B1); PG8_BAR; PG8_SCHED;
.LBB0_1354:
	s_add_u32 s24, s22, 0xfffc0080
	s_addc_u32 s25, s23, -1
	s_add_i32 s49, 0, 0x10000
	s_cmp_eq_u32 s48, 12
	s_cselect_b32 s27, s15, s25
	s_cselect_b32 s26, s21, s24
	v_add_u32_e32 v142, s49, v145
	s_cselect_b32 s25, s13, s47
	s_cselect_b32 s24, s45, s46
	s_add_i32 s52, 0, 0x14000
	ds_read_b128 v[150:153], v142
	ds_read_b128 v[154:157], v142 offset:1024
	ds_read_b128 v[158:161], v142 offset:2048
	ds_read_b128 v[162:165], v142 offset:3072
	v_add_u32_e32 v142, s52, v145
	ds_read_b128 v[166:169], v142
	ds_read_b128 v[170:173], v142 offset:1024
	ds_read_b128 v[174:177], v142 offset:2048
	ds_read_b128 v[178:181], v142 offset:3072
	s_add_i32 m0, s36, 0xc000
	ds_read_b128 v[182:185], v148
	ds_read_b128 v[202:205], v148 offset:1024
	ds_read_b128 v[206:209], v148 offset:2048
	ds_read_b128 v[210:213], v148 offset:3072
	ds_read_b128 v[232:235], v148 offset:4096
	ds_read_b128 v[236:239], v148 offset:5120
	ds_read_b128 v[240:243], v148 offset:6144
	ds_read_b128 v[244:247], v148 offset:7168
	global_load_lds_dwordx4 v138, s[22:23]
	s_add_i32 m0, s36, 0xe000
	s_nop 0
	global_load_lds_dwordx4 v140, s[22:23]
	s_waitcnt vmcnt(8)
	s_waitcnt lgkmcnt(0)
	s_setprio 1
	s_barrier
	v_mfma_f32_16x16x32_bf16 v[126:129], v[150:153], v[182:185], v[126:129]
	v_mfma_f32_16x16x32_bf16 v[122:125], v[158:161], v[182:185], v[122:125]
	v_mfma_f32_16x16x32_bf16 v[114:117], v[150:153], v[206:209], v[114:117]
	v_mfma_f32_16x16x32_bf16 v[106:109], v[158:161], v[206:209], v[106:109]
	v_mfma_f32_16x16x32_bf16 v[98:101], v[150:153], v[232:235], v[98:101]
	v_mfma_f32_16x16x32_bf16 v[90:93], v[158:161], v[232:235], v[90:93]
	v_mfma_f32_16x16x32_bf16 v[78:81], v[150:153], v[240:243], v[78:81]
	v_mfma_f32_16x16x32_bf16 v[74:77], v[158:161], v[240:243], v[74:77]
	v_mfma_f32_16x16x32_bf16 v[126:129], v[154:157], v[202:205], v[126:129]
	v_mfma_f32_16x16x32_bf16 v[122:125], v[162:165], v[202:205], v[122:125]
	v_mfma_f32_16x16x32_bf16 v[114:117], v[154:157], v[210:213], v[114:117]
	v_mfma_f32_16x16x32_bf16 v[106:109], v[162:165], v[210:213], v[106:109]
	v_mfma_f32_16x16x32_bf16 v[98:101], v[154:157], v[236:239], v[98:101]
	v_mfma_f32_16x16x32_bf16 v[90:93], v[162:165], v[236:239], v[90:93]
	v_mfma_f32_16x16x32_bf16 v[78:81], v[154:157], v[244:247], v[78:81]
	v_mfma_f32_16x16x32_bf16 v[74:77], v[162:165], v[244:247], v[74:77]
	s_setprio 0
	s_setprio 1
	v_mfma_f32_16x16x32_bf16 v[118:121], v[166:169], v[182:185], v[118:121]
	v_mfma_f32_16x16x32_bf16 v[110:113], v[174:177], v[182:185], v[110:113]
	v_mfma_f32_16x16x32_bf16 v[102:105], v[166:169], v[206:209], v[102:105]
	v_mfma_f32_16x16x32_bf16 v[94:97], v[174:177], v[206:209], v[94:97]
	v_mfma_f32_16x16x32_bf16 v[86:89], v[166:169], v[232:235], v[86:89]
	v_mfma_f32_16x16x32_bf16 v[82:85], v[174:177], v[232:235], v[82:85]
	v_mfma_f32_16x16x32_bf16 v[70:73], v[166:169], v[240:243], v[70:73]
	v_mfma_f32_16x16x32_bf16 v[66:69], v[174:177], v[240:243], v[66:69]
	v_mfma_f32_16x16x32_bf16 v[118:121], v[170:173], v[202:205], v[118:121]
	v_mfma_f32_16x16x32_bf16 v[110:113], v[178:181], v[202:205], v[110:113]
	v_mfma_f32_16x16x32_bf16 v[102:105], v[170:173], v[210:213], v[102:105]
	v_mfma_f32_16x16x32_bf16 v[94:97], v[178:181], v[210:213], v[94:97]
	v_mfma_f32_16x16x32_bf16 v[86:89], v[170:173], v[236:239], v[86:89]
	v_mfma_f32_16x16x32_bf16 v[82:85], v[178:181], v[236:239], v[82:85]
	v_mfma_f32_16x16x32_bf16 v[70:73], v[170:173], v[244:247], v[70:73]
	v_mfma_f32_16x16x32_bf16 v[66:69], v[178:181], v[244:247], v[66:69]
	s_setprio 0
	s_barrier
	s_add_i32 s49, s49, s34
	s_mov_b32 m0, s49
	ds_read_b128 v[182:185], v148 offset:16384
	ds_read_b128 v[202:205], v148 offset:17408
	ds_read_b128 v[206:209], v148 offset:18432
	ds_read_b128 v[210:213], v148 offset:19456
	ds_read_b128 v[232:235], v148 offset:20480
	ds_read_b128 v[236:239], v148 offset:21504
	ds_read_b128 v[240:243], v148 offset:22528
	ds_read_b128 v[244:247], v148 offset:23552
	s_add_u32 s60, s24, 0x80
	s_addc_u32 s61, s25, 0
	s_add_u32 s62, s26, 0x80
	s_addc_u32 s63, s27, 0
	global_load_lds_dwordx4 v134, s[24:25]
	s_add_i32 m0, s49, 0x2000
	s_add_u32 s50, s24, 0x40000
	s_addc_u32 s51, s25, 0
	s_add_i32 s49, s52, s34
	global_load_lds_dwordx4 v130, s[24:25]
	s_mov_b32 m0, s49
	s_nop 0
	global_load_lds_dwordx4 v134, s[50:51]
	s_add_i32 m0, s49, 0x2000
	s_nop 0
	global_load_lds_dwordx4 v130, s[50:51]
	s_mov_b32 m0, s36
	s_nop 0
	global_load_lds_dwordx4 v136, s[26:27]
	s_mov_b32 m0, s37
	s_nop 0
	global_load_lds_dwordx4 v132, s[26:27]
	s_waitcnt vmcnt(8)
	s_waitcnt lgkmcnt(0)
	s_setprio 1
	s_barrier
; #define PG8_STAGE(bufoff, gbase, voff) do { _Pragma("unroll") for (int _i = 0; _i < 2; ++_i) \
;         __builtin_amdgcn_global_load_lds((const unsigned*)((const char*)(gbase) + (voff)[_i]), (PG8_LAS unsigned*)(lds + (bufoff) + ldsw + _i * 8192), 16, 0, 0); } while (0)
; #define PG8_LDA(dst, b, h) do { _Pragma("unroll") for (int m = 0; m < 4; ++m) _Pragma("unroll") for (int k = 0; k < 2; ++k) dst[m][k] = *(const PG8_LAS bf16x8*)(lds + PG8_SA(b, h) + aoff + m * 2048 + k * 1024); } while (0)
; #define PG8_LDB(dst, b, h) do { _Pragma("unroll") for (int n = 0; n < 2; ++n) _Pragma("unroll") for (int k = 0; k < 2; ++k) dst[n][k] = *(const PG8_LAS bf16x8*)(lds + PG8_SB(b, h) + boff + n * 2048 + k * 1024); } while (0)
; #define PG8_MMA(ai, bj, At, Bt) do { __builtin_amdgcn_s_setprio(1); _Pragma("unroll") for (int m = 0; m < 4; ++m) _Pragma("unroll") for (int n = 0; n < 2; ++n) _Pragma("unroll") for (int k = 0; k < 2; ++k) \
;         acc[ai][bj][m][n] = __builtin_amdgcn_mfma_f32_16x16x32_bf16(Bt[n][k], At[m][k], acc[ai][bj][m][n], 0, 0, 0); __builtin_amdgcn_s_setprio(0); } while (0)
; #define PG8_WAIT_V(n) asm volatile("s_waitcnt vmcnt(" #n ")" ::: "memory")
; template <class Epi, class Sched, bool ALIGN_EPI = false, bool SP2 = false>
; __device__ __forceinline__ void gemm_phase(PG8_LAS unsigned char* lds, const Gemm g, const Sched& S, const Epi& E) {
;     ...
;             PG8_LDB(B0, 0, 0); PG8_LDB(B1, 0, 1); PG8_SCHED; PG8_LDA(At, 0, 0); PG8_STAGE(PG8_SA(1, 1), a1 + hstepA, voffA);
;             PG8_WAIT_V(8); PG8_WAIT_L(0); PG8_BAR; PG8_MMA(0, 0, At, B0); PG8_MMA(0, 1, At, B1); PG8_BAR; PG8_SCHED;
;             PG8_LDA(At, 0, 1); PG8_STAGE(PG8_SB(0, 0), b2, voffB); PG8_STAGE(PG8_SB(0, 1), b2 + hstepB, voffB); PG8_STAGE(PG8_SA(0, 0), a2, voffA);
;             PG8_WAIT_V(8); PG8_WAIT_L(0); PG8_BAR; PG8_MMA(1, 0, At, B0); PG8_MMA(1, 1, At, B1); PG8_BAR; PG8_SCHED;
;             PG8_LDB(B0, 1, 0); PG8_LDB(B1, 1, 1); PG8_SCHED; PG8_LDA(At, 1, 0); PG8_STAGE(PG8_SA(0, 1), a2 + hstepA, voffA);
;             PG8_WAIT_V(8); PG8_WAIT_L(0); PG8_BAR; PG8_MMA(0, 0, At, B0); PG8_MMA(0, 1, At, B1); PG8_BAR; PG8_SCHED;
;             PG8_LDA(At, 1, 1); PG8_STAGE(PG8_SB(1, 0), b3, voffB); PG8_STAGE(PG8_SB(1, 1), b3 + hstepB, voffB); PG8_STAGE(PG8_SA(1, 0), a3, voffA);
;             PG8_WAIT_V(8); PG8_WAIT_L(0); PG8_BAR; PG8_MMA(1, 0, At, B0); PG8_MMA(1, 1, At, B1); PG8_BAR; PG8_SCHED;
	v_mfma_f32_16x16x32_bf16 v[62:65], v[150:153], v[182:185], v[62:65]
	v_mfma_f32_16x16x32_bf16 v[58:61], v[158:161], v[182:185], v[58:61]
	v_mfma_f32_16x16x32_bf16 v[46:49], v[150:153], v[206:209], v[46:49]
	v_mfma_f32_16x16x32_bf16 v[42:45], v[158:161], v[206:209], v[42:45]
	v_mfma_f32_16x16x32_bf16 v[30:33], v[150:153], v[232:235], v[30:33]
	v_mfma_f32_16x16x32_bf16 v[26:29], v[158:161], v[232:235], v[26:29]
	v_mfma_f32_16x16x32_bf16 v[14:17], v[150:153], v[240:243], v[14:17]
	v_mfma_f32_16x16x32_bf16 v[10:13], v[158:161], v[240:243], v[10:13]
	v_mfma_f32_16x16x32_bf16 v[62:65], v[154:157], v[202:205], v[62:65]
	v_mfma_f32_16x16x32_bf16 v[58:61], v[162:165], v[202:205], v[58:61]
	v_mfma_f32_16x16x32_bf16 v[46:49], v[154:157], v[210:213], v[46:49]
	v_mfma_f32_16x16x32_bf16 v[42:45], v[162:165], v[210:213], v[42:45]
	v_mfma_f32_16x16x32_bf16 v[30:33], v[154:157], v[236:239], v[30:33]
	v_mfma_f32_16x16x32_bf16 v[26:29], v[162:165], v[236:239], v[26:29]
	v_mfma_f32_16x16x32_bf16 v[14:17], v[154:157], v[244:247], v[14:17]
	v_mfma_f32_16x16x32_bf16 v[10:13], v[162:165], v[244:247], v[10:13]
	s_setprio 0
	s_setprio 1
	v_mfma_f32_16x16x32_bf16 v[54:57], v[166:169], v[182:185], v[54:57]
	v_mfma_f32_16x16x32_bf16 v[50:53], v[174:177], v[182:185], v[50:53]
	v_mfma_f32_16x16x32_bf16 v[38:41], v[166:169], v[206:209], v[38:41]
	v_mfma_f32_16x16x32_bf16 v[34:37], v[174:177], v[206:209], v[34:37]
	v_mfma_f32_16x16x32_bf16 v[22:25], v[166:169], v[232:235], v[22:25]
	v_mfma_f32_16x16x32_bf16 v[18:21], v[174:177], v[232:235], v[18:21]
	v_mfma_f32_16x16x32_bf16 v[6:9], v[166:169], v[240:243], v[6:9]
	v_mfma_f32_16x16x32_bf16 v[2:5], v[174:177], v[240:243], v[2:5]
	v_mfma_f32_16x16x32_bf16 v[54:57], v[170:173], v[202:205], v[54:57]
	v_mfma_f32_16x16x32_bf16 v[50:53], v[178:181], v[202:205], v[50:53]
	v_mfma_f32_16x16x32_bf16 v[38:41], v[170:173], v[210:213], v[38:41]
	v_mfma_f32_16x16x32_bf16 v[34:37], v[178:181], v[210:213], v[34:37]
	v_mfma_f32_16x16x32_bf16 v[22:25], v[170:173], v[236:239], v[22:25]
	v_mfma_f32_16x16x32_bf16 v[18:21], v[178:181], v[236:239], v[18:21]
	v_mfma_f32_16x16x32_bf16 v[6:9], v[170:173], v[244:247], v[6:9]
	v_mfma_f32_16x16x32_bf16 v[2:5], v[178:181], v[244:247], v[2:5]
	s_setprio 0
	s_barrier
	s_add_i32 s49, 0, 0x18000
	v_add_u32_e32 v144, s49, v145
	s_add_i32 s50, 0, 0x1c000
	ds_read_b128 v[150:153], v144
	ds_read_b128 v[154:157], v144 offset:1024
	ds_read_b128 v[158:161], v144 offset:2048
	ds_read_b128 v[162:165], v144 offset:3072
	v_add_u32_e32 v144, s50, v145
	ds_read_b128 v[166:169], v144
	ds_read_b128 v[170:173], v144 offset:1024
	ds_read_b128 v[174:177], v144 offset:2048
	ds_read_b128 v[178:181], v144 offset:3072
	s_add_u32 s26, s26, 0x40000
	s_addc_u32 s27, s27, 0
	s_mov_b32 m0, s38
	ds_read_b128 v[182:185], v148 offset:32768
	ds_read_b128 v[202:205], v148 offset:33792
	ds_read_b128 v[206:209], v148 offset:34816
	ds_read_b128 v[210:213], v148 offset:35840
	ds_read_b128 v[232:235], v148 offset:36864
	ds_read_b128 v[236:239], v148 offset:37888
	ds_read_b128 v[240:243], v148 offset:38912
	ds_read_b128 v[244:247], v148 offset:39936
	global_load_lds_dwordx4 v136, s[26:27]
	s_mov_b32 m0, s39
	s_nop 0
	global_load_lds_dwordx4 v132, s[26:27]
	s_waitcnt vmcnt(8)
	s_waitcnt lgkmcnt(0)
	s_setprio 1
	s_barrier
	v_mfma_f32_16x16x32_bf16 v[126:129], v[150:153], v[182:185], v[126:129]
	v_mfma_f32_16x16x32_bf16 v[122:125], v[158:161], v[182:185], v[122:125]
	v_mfma_f32_16x16x32_bf16 v[114:117], v[150:153], v[206:209], v[114:117]
	v_mfma_f32_16x16x32_bf16 v[106:109], v[158:161], v[206:209], v[106:109]
	v_mfma_f32_16x16x32_bf16 v[98:101], v[150:153], v[232:235], v[98:101]
	v_mfma_f32_16x16x32_bf16 v[90:93], v[158:161], v[232:235], v[90:93]
	v_mfma_f32_16x16x32_bf16 v[78:81], v[150:153], v[240:243], v[78:81]
	v_mfma_f32_16x16x32_bf16 v[74:77], v[158:161], v[240:243], v[74:77]
	v_mfma_f32_16x16x32_bf16 v[126:129], v[154:157], v[202:205], v[126:129]
	v_mfma_f32_16x16x32_bf16 v[122:125], v[162:165], v[202:205], v[122:125]
	v_mfma_f32_16x16x32_bf16 v[114:117], v[154:157], v[210:213], v[114:117]
	v_mfma_f32_16x16x32_bf16 v[106:109], v[162:165], v[210:213], v[106:109]
	v_mfma_f32_16x16x32_bf16 v[98:101], v[154:157], v[236:239], v[98:101]
	v_mfma_f32_16x16x32_bf16 v[90:93], v[162:165], v[236:239], v[90:93]
	v_mfma_f32_16x16x32_bf16 v[78:81], v[154:157], v[244:247], v[78:81]
	v_mfma_f32_16x16x32_bf16 v[74:77], v[162:165], v[244:247], v[74:77]
	s_setprio 0
	s_setprio 1
	v_mfma_f32_16x16x32_bf16 v[118:121], v[166:169], v[182:185], v[118:121]
	v_mfma_f32_16x16x32_bf16 v[110:113], v[174:177], v[182:185], v[110:113]
	v_mfma_f32_16x16x32_bf16 v[102:105], v[166:169], v[206:209], v[102:105]
	v_mfma_f32_16x16x32_bf16 v[94:97], v[174:177], v[206:209], v[94:97]
	v_mfma_f32_16x16x32_bf16 v[86:89], v[166:169], v[232:235], v[86:89]
	v_mfma_f32_16x16x32_bf16 v[82:85], v[174:177], v[232:235], v[82:85]
	v_mfma_f32_16x16x32_bf16 v[70:73], v[166:169], v[240:243], v[70:73]
	v_mfma_f32_16x16x32_bf16 v[66:69], v[174:177], v[240:243], v[66:69]
	v_mfma_f32_16x16x32_bf16 v[118:121], v[170:173], v[202:205], v[118:121]
	v_mfma_f32_16x16x32_bf16 v[110:113], v[178:181], v[202:205], v[110:113]
	v_mfma_f32_16x16x32_bf16 v[102:105], v[170:173], v[210:213], v[102:105]
	v_mfma_f32_16x16x32_bf16 v[94:97], v[178:181], v[210:213], v[94:97]
	v_mfma_f32_16x16x32_bf16 v[86:89], v[170:173], v[236:239], v[86:89]
	v_mfma_f32_16x16x32_bf16 v[82:85], v[178:181], v[236:239], v[82:85]
	v_mfma_f32_16x16x32_bf16 v[70:73], v[170:173], v[244:247], v[70:73]
	v_mfma_f32_16x16x32_bf16 v[66:69], v[178:181], v[244:247], v[66:69]
	s_setprio 0
	s_barrier
; #define PG8_STAGE(bufoff, gbase, voff) do { _Pragma("unroll") for (int _i = 0; _i < 2; ++_i) \
;         __builtin_amdgcn_global_load_lds((const unsigned*)((const char*)(gbase) + (voff)[_i]), (PG8_LAS unsigned*)(lds + (bufoff) + ldsw + _i * 8192), 16, 0, 0); } while (0)
; #define PG8_LDA(dst, b, h) do { _Pragma("unroll") for (int m = 0; m < 4; ++m) _Pragma("unroll") for (int k = 0; k < 2; ++k) dst[m][k] = *(const PG8_LAS bf16x8*)(lds + PG8_SA(b, h) + aoff + m * 2048 + k * 1024); } while (0)
; #define PG8_LDB(dst, b, h) do { _Pragma("unroll") for (int n = 0; n < 2; ++n) _Pragma("unroll") for (int k = 0; k < 2; ++k) dst[n][k] = *(const PG8_LAS bf16x8*)(lds + PG8_SB(b, h) + boff + n * 2048 + k * 1024); } while (0)
; #define PG8_MMA(ai, bj, At, Bt) do { __builtin_amdgcn_s_setprio(1); _Pragma("unroll") for (int m = 0; m < 4; ++m) _Pragma("unroll") for (int n = 0; n < 2; ++n) _Pragma("unroll") for (int k = 0; k < 2; ++k) \
;         acc[ai][bj][m][n] = __builtin_amdgcn_mfma_f32_16x16x32_bf16(Bt[n][k], At[m][k], acc[ai][bj][m][n], 0, 0, 0); __builtin_amdgcn_s_setprio(0); } while (0)
; template <class Epi, class Sched, bool ALIGN_EPI = false, bool SP2 = false>
; __device__ __forceinline__ void gemm_phase(PG8_LAS unsigned char* lds, const Gemm g, const Sched& S, const Epi& E) {
;     ...
;         for (int t = 0; t < nt; t += 2) {
;     ...
;             PG8_LDB(B0, 0, 0); PG8_LDB(B1, 0, 1); PG8_SCHED; PG8_LDA(At, 0, 0); PG8_STAGE(PG8_SA(1, 1), a1 + hstepA, voffA);
;             PG8_WAIT_V(8); PG8_WAIT_L(0); PG8_BAR; PG8_MMA(0, 0, At, B0); PG8_MMA(0, 1, At, B1); PG8_BAR; PG8_SCHED;
;             PG8_LDA(At, 0, 1); PG8_STAGE(PG8_SB(0, 0), b2, voffB); PG8_STAGE(PG8_SB(0, 1), b2 + hstepB, voffB); PG8_STAGE(PG8_SA(0, 0), a2, voffA);
;             PG8_WAIT_V(8); PG8_WAIT_L(0); PG8_BAR; PG8_MMA(1, 0, At, B0); PG8_MMA(1, 1, At, B1); PG8_BAR; PG8_SCHED;
;             PG8_LDB(B0, 1, 0); PG8_LDB(B1, 1, 1); PG8_SCHED; PG8_LDA(At, 1, 0); PG8_STAGE(PG8_SA(0, 1), a2 + hstepA, voffA);
;             PG8_WAIT_V(8); PG8_WAIT_L(0); PG8_BAR; PG8_MMA(0, 0, At, B0); PG8_MMA(0, 1, At, B1); PG8_BAR; PG8_SCHED;
;             PG8_LDA(At, 1, 1); PG8_STAGE(PG8_SB(1, 0), b3, voffB); PG8_STAGE(PG8_SB(1, 1), b3 + hstepB, voffB); PG8_STAGE(PG8_SA(1, 0), a3, voffA);
;             PG8_WAIT_V(8); PG8_WAIT_L(0); PG8_BAR; PG8_MMA(1, 0, At, B0); PG8_MMA(1, 1, At, B1); PG8_BAR; PG8_SCHED;
	s_add_i32 s26, s49, s34
	s_mov_b32 m0, s26
	ds_read_b128 v[182:185], v148 offset:49152
	ds_read_b128 v[202:205], v148 offset:50176
	ds_read_b128 v[206:209], v148 offset:51200
	ds_read_b128 v[210:213], v148 offset:52224
	ds_read_b128 v[232:235], v148 offset:53248
	ds_read_b128 v[236:239], v148 offset:54272
	ds_read_b128 v[240:243], v148 offset:55296
	ds_read_b128 v[244:247], v148 offset:56320
	global_load_lds_dwordx4 v134, s[60:61]
	s_add_i32 m0, s26, 0x2000
	s_add_u32 s24, s24, 0x40080
	s_addc_u32 s25, s25, 0
	s_add_i32 s26, s50, s34
	global_load_lds_dwordx4 v130, s[60:61]
	s_mov_b32 m0, s26
	s_nop 0
	global_load_lds_dwordx4 v134, s[24:25]
	s_add_i32 m0, s26, 0x2000
	s_nop 0
	global_load_lds_dwordx4 v130, s[24:25]
	s_mov_b32 m0, s40
	s_nop 0
	global_load_lds_dwordx4 v136, s[62:63]
	s_mov_b32 m0, s41
	s_nop 0
	global_load_lds_dwordx4 v132, s[62:63]
	s_waitcnt vmcnt(8)
	s_waitcnt lgkmcnt(0)
	s_setprio 1
	s_barrier
	v_mfma_f32_16x16x32_bf16 v[62:65], v[150:153], v[182:185], v[62:65]
	v_mfma_f32_16x16x32_bf16 v[58:61], v[158:161], v[182:185], v[58:61]
	v_mfma_f32_16x16x32_bf16 v[46:49], v[150:153], v[206:209], v[46:49]
	v_mfma_f32_16x16x32_bf16 v[42:45], v[158:161], v[206:209], v[42:45]
	v_mfma_f32_16x16x32_bf16 v[30:33], v[150:153], v[232:235], v[30:33]
	v_mfma_f32_16x16x32_bf16 v[26:29], v[158:161], v[232:235], v[26:29]
	v_mfma_f32_16x16x32_bf16 v[14:17], v[150:153], v[240:243], v[14:17]
	v_mfma_f32_16x16x32_bf16 v[10:13], v[158:161], v[240:243], v[10:13]
	v_mfma_f32_16x16x32_bf16 v[62:65], v[154:157], v[202:205], v[62:65]
	v_mfma_f32_16x16x32_bf16 v[58:61], v[162:165], v[202:205], v[58:61]
	v_mfma_f32_16x16x32_bf16 v[46:49], v[154:157], v[210:213], v[46:49]
	v_mfma_f32_16x16x32_bf16 v[42:45], v[162:165], v[210:213], v[42:45]
	v_mfma_f32_16x16x32_bf16 v[30:33], v[154:157], v[236:239], v[30:33]
	v_mfma_f32_16x16x32_bf16 v[26:29], v[162:165], v[236:239], v[26:29]
	v_mfma_f32_16x16x32_bf16 v[14:17], v[154:157], v[244:247], v[14:17]
	v_mfma_f32_16x16x32_bf16 v[10:13], v[162:165], v[244:247], v[10:13]
	s_setprio 0
	s_setprio 1
	v_mfma_f32_16x16x32_bf16 v[54:57], v[166:169], v[182:185], v[54:57]
	v_mfma_f32_16x16x32_bf16 v[50:53], v[174:177], v[182:185], v[50:53]
	v_mfma_f32_16x16x32_bf16 v[38:41], v[166:169], v[206:209], v[38:41]
	v_mfma_f32_16x16x32_bf16 v[34:37], v[174:177], v[206:209], v[34:37]
	v_mfma_f32_16x16x32_bf16 v[22:25], v[166:169], v[232:235], v[22:25]
	v_mfma_f32_16x16x32_bf16 v[18:21], v[174:177], v[232:235], v[18:21]
	v_mfma_f32_16x16x32_bf16 v[6:9], v[166:169], v[240:243], v[6:9]
	v_mfma_f32_16x16x32_bf16 v[2:5], v[174:177], v[240:243], v[2:5]
	v_mfma_f32_16x16x32_bf16 v[54:57], v[170:173], v[202:205], v[54:57]
	v_mfma_f32_16x16x32_bf16 v[50:53], v[178:181], v[202:205], v[50:53]
	v_mfma_f32_16x16x32_bf16 v[38:41], v[170:173], v[210:213], v[38:41]
	v_mfma_f32_16x16x32_bf16 v[34:37], v[178:181], v[210:213], v[34:37]
	v_mfma_f32_16x16x32_bf16 v[22:25], v[170:173], v[236:239], v[22:25]
	v_mfma_f32_16x16x32_bf16 v[18:21], v[178:181], v[236:239], v[18:21]
	v_mfma_f32_16x16x32_bf16 v[6:9], v[170:173], v[244:247], v[6:9]
	v_mfma_f32_16x16x32_bf16 v[2:5], v[178:181], v[244:247], v[2:5]
	s_setprio 0
	s_barrier
	s_add_i32 s48, s48, 2
	s_add_u32 s22, s22, 0x100
	s_addc_u32 s23, s23, 0
	s_add_u32 s46, s46, 0x100
	s_addc_u32 s47, s47, 0
	s_cmp_gt_u32 s48, 13
	s_cbranch_scc0 .LBB0_1354
	s_and_b64 vcc, exec, s[10:11]
	s_cbranch_vccz .LBB0_1357
	s_barrier

; #define PG8_STAGE(bufoff, gbase, voff) do { _Pragma("unroll") for (int _i = 0; _i < 2; ++_i) \
;         __builtin_amdgcn_global_load_lds((const unsigned*)((const char*)(gbase) + (voff)[_i]), (PG8_LAS unsigned*)(lds + (bufoff) + ldsw + _i * 8192), 16, 0, 0); } while (0)
; #define PG8_LDA(dst, b, h) do { _Pragma("unroll") for (int m = 0; m < 4; ++m) _Pragma("unroll") for (int k = 0; k < 2; ++k) dst[m][k] = *(const PG8_LAS bf16x8*)(lds + PG8_SA(b, h) + aoff + m * 2048 + k * 1024); } while (0)
; #define PG8_LDB(dst, b, h) do { _Pragma("unroll") for (int n = 0; n < 2; ++n) _Pragma("unroll") for (int k = 0; k < 2; ++k) dst[n][k] = *(const PG8_LAS bf16x8*)(lds + PG8_SB(b, h) + boff + n * 2048 + k * 1024); } while (0)
; #define PG8_BAR __builtin_amdgcn_s_barrier()
; template <class Epi, class Sched, bool ALIGN_EPI = false, bool SP2 = false>
; __device__ __forceinline__ void gemm_phase(PG8_LAS unsigned char* lds, const Gemm g, const Sched& S, const Epi& E) {
;     ...
;             const bool last = (t == nt - 2);
;             const char* a1 = cA + (size_t)(t + 1) * kstep;
;             const char* a2 = last ? nA : cA + (size_t)(t + 2) * kstep; const char* b2 = last ? nB : cB + (size_t)(t + 2) * kstep;
;             const char* a3 = a2 + kstep; const char* b3 = b2 + kstep;
;             if (last && has_next) S.a_ready(nxt);
;             if constexpr (SP2) {
;             PG8_LDB(B0, 0, 0); PG8_LDB(B1, 0, 1); PG8_SCHED; PG8_LDA(At, 0, 0); PG8_STAGE(PG8_SA(1, 1), a1 + hstepA, voffA);
;             PG8_WAIT_V(8); PG8_WAIT_L(0); PG8_BAR; PG8_MMA(0, 0, At, B0); PG8_MMA(0, 1, At, B1); PG8_BAR; PG8_SCHED;
;             PG8_LDA(At, 0, 1); PG8_STAGE(PG8_SB(0, 0), b2, voffB); PG8_STAGE(PG8_SB(0, 1), b2 + hstepB, voffB); PG8_STAGE(PG8_SA(0, 0), a2, voffA);
;             PG8_WAIT_V(8); PG8_WAIT_L(0); PG8_BAR; PG8_MMA(1, 0, At, B0); PG8_MMA(1, 1, At, B1); PG8_BAR; PG8_SCHED;
;             PG8_LDB(B0, 1, 0); PG8_LDB(B1, 1, 1); PG8_SCHED; PG8_LDA(At, 1, 0); PG8_STAGE(PG8_SA(0, 1), a2 + hstepA, voffA);
;             PG8_WAIT_V(8); PG8_WAIT_L(0); PG8_BAR; PG8_MMA(0, 0, At, B0); PG8_MMA(0, 1, At, B1); PG8_BAR; PG8_SCHED;
;             PG8_LDA(At, 1, 1); PG8_STAGE(PG8_SB(1, 0), b3, voffB); PG8_STAGE(PG8_SB(1, 1), b3 + hstepB, voffB); PG8_STAGE(PG8_SA(1, 0), a3, voffA);
;             PG8_WAIT_V(8); PG8_WAIT_L(0); PG8_BAR; PG8_MMA(1, 0, At, B0); PG8_MMA(1, 1, At, B1); PG8_BAR; PG8_SCHED;
.LBB0_1438:
	s_add_u32 s20, s18, 0x100
	s_addc_u32 s21, s19, 0
	s_add_i32 s50, 0, 0x10000
	s_cmp_eq_u32 s49, 40
	s_cselect_b32 s25, s9, s21
	s_cselect_b32 s24, s8, s20
	s_cselect_b32 s23, s17, s48
	s_cselect_b32 s22, s16, s47
	s_add_i32 s51, 0, 0x14000
	v_add_u32_e32 v142, s50, v186
	v_add_u32_e32 v172, s51, v186
	ds_read_b128 v[130:133], v142
	ds_read_b128 v[134:137], v142 offset:1024
	ds_read_b128 v[138:141], v142 offset:2048
	ds_read_b128 v[142:145], v142 offset:3072
	ds_read_b128 v[146:149], v172
	ds_read_b128 v[150:153], v172 offset:1024
	ds_read_b128 v[168:171], v172 offset:2048
	ds_read_b128 v[172:175], v172 offset:3072
	s_add_i32 m0, s31, 0xc000
	ds_read_b128 v[176:179], v200
	ds_read_b128 v[180:183], v200 offset:1024
	ds_read_b128 v[202:205], v200 offset:2048
	ds_read_b128 v[206:209], v200 offset:3072
	ds_read_b128 v[210:213], v200 offset:4096
	ds_read_b128 v[232:235], v200 offset:5120
	ds_read_b128 v[236:239], v200 offset:6144
	ds_read_b128 v[240:243], v200 offset:7168
	global_load_lds_dwordx4 v164, s[18:19]
	s_add_i32 m0, s31, 0xe000
	s_nop 0
	global_load_lds_dwordx4 v166, s[18:19]
	s_waitcnt vmcnt(8)
	s_waitcnt lgkmcnt(0)
	s_setprio 1
	s_barrier
	v_mfma_f32_16x16x32_bf16 v[126:129], v[130:133], v[176:179], v[126:129]
	v_mfma_f32_16x16x32_bf16 v[122:125], v[138:141], v[176:179], v[122:125]
	v_mfma_f32_16x16x32_bf16 v[110:113], v[130:133], v[202:205], v[110:113]
	v_mfma_f32_16x16x32_bf16 v[106:109], v[138:141], v[202:205], v[106:109]
	v_mfma_f32_16x16x32_bf16 v[94:97], v[130:133], v[210:213], v[94:97]
	v_mfma_f32_16x16x32_bf16 v[90:93], v[138:141], v[210:213], v[90:93]
	v_mfma_f32_16x16x32_bf16 v[78:81], v[130:133], v[236:239], v[78:81]
	v_mfma_f32_16x16x32_bf16 v[74:77], v[138:141], v[236:239], v[74:77]
	v_mfma_f32_16x16x32_bf16 v[126:129], v[134:137], v[180:183], v[126:129]
	v_mfma_f32_16x16x32_bf16 v[122:125], v[142:145], v[180:183], v[122:125]
	v_mfma_f32_16x16x32_bf16 v[110:113], v[134:137], v[206:209], v[110:113]
	v_mfma_f32_16x16x32_bf16 v[106:109], v[142:145], v[206:209], v[106:109]
	v_mfma_f32_16x16x32_bf16 v[94:97], v[134:137], v[232:235], v[94:97]
	v_mfma_f32_16x16x32_bf16 v[90:93], v[142:145], v[232:235], v[90:93]
	v_mfma_f32_16x16x32_bf16 v[78:81], v[134:137], v[240:243], v[78:81]
	v_mfma_f32_16x16x32_bf16 v[74:77], v[142:145], v[240:243], v[74:77]
	s_setprio 0
	s_setprio 1
	v_mfma_f32_16x16x32_bf16 v[118:121], v[146:149], v[176:179], v[118:121]
	v_mfma_f32_16x16x32_bf16 v[114:117], v[168:171], v[176:179], v[114:117]
	v_mfma_f32_16x16x32_bf16 v[102:105], v[146:149], v[202:205], v[102:105]
	v_mfma_f32_16x16x32_bf16 v[98:101], v[168:171], v[202:205], v[98:101]
	v_mfma_f32_16x16x32_bf16 v[86:89], v[146:149], v[210:213], v[86:89]
	v_mfma_f32_16x16x32_bf16 v[82:85], v[168:171], v[210:213], v[82:85]
	v_mfma_f32_16x16x32_bf16 v[70:73], v[146:149], v[236:239], v[70:73]
	v_mfma_f32_16x16x32_bf16 v[66:69], v[168:171], v[236:239], v[66:69]
	v_mfma_f32_16x16x32_bf16 v[118:121], v[150:153], v[180:183], v[118:121]
	v_mfma_f32_16x16x32_bf16 v[114:117], v[172:175], v[180:183], v[114:117]
	v_mfma_f32_16x16x32_bf16 v[102:105], v[150:153], v[206:209], v[102:105]
	v_mfma_f32_16x16x32_bf16 v[98:101], v[172:175], v[206:209], v[98:101]
	v_mfma_f32_16x16x32_bf16 v[86:89], v[150:153], v[232:235], v[86:89]
	v_mfma_f32_16x16x32_bf16 v[82:85], v[172:175], v[232:235], v[82:85]
	v_mfma_f32_16x16x32_bf16 v[70:73], v[150:153], v[240:243], v[70:73]
	v_mfma_f32_16x16x32_bf16 v[66:69], v[172:175], v[240:243], v[66:69]
	s_setprio 0
	s_barrier
	s_add_i32 s18, s50, s30
	s_mov_b32 m0, s18
	ds_read_b128 v[176:179], v200 offset:16384
	ds_read_b128 v[180:183], v200 offset:17408
	ds_read_b128 v[202:205], v200 offset:18432
	ds_read_b128 v[206:209], v200 offset:19456
	ds_read_b128 v[210:213], v200 offset:20480
	ds_read_b128 v[232:235], v200 offset:21504
	ds_read_b128 v[236:239], v200 offset:22528
	ds_read_b128 v[240:243], v200 offset:23552
	s_add_u32 s60, s22, 0x80
	s_addc_u32 s61, s23, 0
	s_add_u32 s62, s24, 0x80
	s_addc_u32 s63, s25, 0
	global_load_lds_dwordx4 v156, s[22:23]
	s_add_i32 m0, s18, 0x2000
	s_add_u32 s18, s22, 0xb0000
	s_addc_u32 s19, s23, 0
	s_add_i32 s50, s51, s30
	global_load_lds_dwordx4 v160, s[22:23]
	s_mov_b32 m0, s50
	s_nop 0
	global_load_lds_dwordx4 v156, s[18:19]
	s_add_i32 m0, s50, 0x2000
	s_nop 0
	global_load_lds_dwordx4 v160, s[18:19]
	s_mov_b32 m0, s31
	s_nop 0
	global_load_lds_dwordx4 v154, s[24:25]
	s_mov_b32 m0, s34
	s_nop 0
	global_load_lds_dwordx4 v158, s[24:25]
	s_waitcnt vmcnt(8)
	s_waitcnt lgkmcnt(0)
	s_setprio 1
	s_barrier
; #define PG8_STAGE(bufoff, gbase, voff) do { _Pragma("unroll") for (int _i = 0; _i < 2; ++_i) \
;         __builtin_amdgcn_global_load_lds((const unsigned*)((const char*)(gbase) + (voff)[_i]), (PG8_LAS unsigned*)(lds + (bufoff) + ldsw + _i * 8192), 16, 0, 0); } while (0)
; #define PG8_LDA(dst, b, h) do { _Pragma("unroll") for (int m = 0; m < 4; ++m) _Pragma("unroll") for (int k = 0; k < 2; ++k) dst[m][k] = *(const PG8_LAS bf16x8*)(lds + PG8_SA(b, h) + aoff + m * 2048 + k * 1024); } while (0)
; #define PG8_LDB(dst, b, h) do { _Pragma("unroll") for (int n = 0; n < 2; ++n) _Pragma("unroll") for (int k = 0; k < 2; ++k) dst[n][k] = *(const PG8_LAS bf16x8*)(lds + PG8_SB(b, h) + boff + n * 2048 + k * 1024); } while (0)
; #define PG8_MMA(ai, bj, At, Bt) do { __builtin_amdgcn_s_setprio(1); _Pragma("unroll") for (int m = 0; m < 4; ++m) _Pragma("unroll") for (int n = 0; n < 2; ++n) _Pragma("unroll") for (int k = 0; k < 2; ++k) \
;         acc[ai][bj][m][n] = __builtin_amdgcn_mfma_f32_16x16x32_bf16(Bt[n][k], At[m][k], acc[ai][bj][m][n], 0, 0, 0); __builtin_amdgcn_s_setprio(0); } while (0)
; #define PG8_WAIT_V(n) asm volatile("s_waitcnt vmcnt(" #n ")" ::: "memory")
; template <class Epi, class Sched, bool ALIGN_EPI = false, bool SP2 = false>
; __device__ __forceinline__ void gemm_phase(PG8_LAS unsigned char* lds, const Gemm g, const Sched& S, const Epi& E) {
;     ...
;             PG8_LDB(B0, 0, 0); PG8_LDB(B1, 0, 1); PG8_SCHED; PG8_LDA(At, 0, 0); PG8_STAGE(PG8_SA(1, 1), a1 + hstepA, voffA);
;             PG8_WAIT_V(8); PG8_WAIT_L(0); PG8_BAR; PG8_MMA(0, 0, At, B0); PG8_MMA(0, 1, At, B1); PG8_BAR; PG8_SCHED;
;             PG8_LDA(At, 0, 1); PG8_STAGE(PG8_SB(0, 0), b2, voffB); PG8_STAGE(PG8_SB(0, 1), b2 + hstepB, voffB); PG8_STAGE(PG8_SA(0, 0), a2, voffA);
;             PG8_WAIT_V(8); PG8_WAIT_L(0); PG8_BAR; PG8_MMA(1, 0, At, B0); PG8_MMA(1, 1, At, B1); PG8_BAR; PG8_SCHED;
;             PG8_LDB(B0, 1, 0); PG8_LDB(B1, 1, 1); PG8_SCHED; PG8_LDA(At, 1, 0); PG8_STAGE(PG8_SA(0, 1), a2 + hstepA, voffA);
;             PG8_WAIT_V(8); PG8_WAIT_L(0); PG8_BAR; PG8_MMA(0, 0, At, B0); PG8_MMA(0, 1, At, B1); PG8_BAR; PG8_SCHED;
;             PG8_LDA(At, 1, 1); PG8_STAGE(PG8_SB(1, 0), b3, voffB); PG8_STAGE(PG8_SB(1, 1), b3 + hstepB, voffB); PG8_STAGE(PG8_SA(1, 0), a3, voffA);
;             PG8_WAIT_V(8); PG8_WAIT_L(0); PG8_BAR; PG8_MMA(1, 0, At, B0); PG8_MMA(1, 1, At, B1); PG8_BAR; PG8_SCHED;
	v_mfma_f32_16x16x32_bf16 v[62:65], v[130:133], v[176:179], v[62:65]
	v_mfma_f32_16x16x32_bf16 v[58:61], v[138:141], v[176:179], v[58:61]
	v_mfma_f32_16x16x32_bf16 v[46:49], v[130:133], v[202:205], v[46:49]
	v_mfma_f32_16x16x32_bf16 v[42:45], v[138:141], v[202:205], v[42:45]
	v_mfma_f32_16x16x32_bf16 v[30:33], v[130:133], v[210:213], v[30:33]
	v_mfma_f32_16x16x32_bf16 v[26:29], v[138:141], v[210:213], v[26:29]
	v_mfma_f32_16x16x32_bf16 v[14:17], v[130:133], v[236:239], v[14:17]
	v_mfma_f32_16x16x32_bf16 v[10:13], v[138:141], v[236:239], v[10:13]
	v_mfma_f32_16x16x32_bf16 v[62:65], v[134:137], v[180:183], v[62:65]
	v_mfma_f32_16x16x32_bf16 v[58:61], v[142:145], v[180:183], v[58:61]
	v_mfma_f32_16x16x32_bf16 v[46:49], v[134:137], v[206:209], v[46:49]
	v_mfma_f32_16x16x32_bf16 v[42:45], v[142:145], v[206:209], v[42:45]
	v_mfma_f32_16x16x32_bf16 v[30:33], v[134:137], v[232:235], v[30:33]
	v_mfma_f32_16x16x32_bf16 v[26:29], v[142:145], v[232:235], v[26:29]
	v_mfma_f32_16x16x32_bf16 v[14:17], v[134:137], v[240:243], v[14:17]
	v_mfma_f32_16x16x32_bf16 v[10:13], v[142:145], v[240:243], v[10:13]
	s_setprio 0
	s_setprio 1
	v_mfma_f32_16x16x32_bf16 v[54:57], v[146:149], v[176:179], v[54:57]
	v_mfma_f32_16x16x32_bf16 v[50:53], v[168:171], v[176:179], v[50:53]
	v_mfma_f32_16x16x32_bf16 v[38:41], v[146:149], v[202:205], v[38:41]
	v_mfma_f32_16x16x32_bf16 v[34:37], v[168:171], v[202:205], v[34:37]
	v_mfma_f32_16x16x32_bf16 v[22:25], v[146:149], v[210:213], v[22:25]
	v_mfma_f32_16x16x32_bf16 v[18:21], v[168:171], v[210:213], v[18:21]
	v_mfma_f32_16x16x32_bf16 v[6:9], v[146:149], v[236:239], v[6:9]
	v_mfma_f32_16x16x32_bf16 v[2:5], v[168:171], v[236:239], v[2:5]
	v_mfma_f32_16x16x32_bf16 v[54:57], v[150:153], v[180:183], v[54:57]
	v_mfma_f32_16x16x32_bf16 v[50:53], v[172:175], v[180:183], v[50:53]
	v_mfma_f32_16x16x32_bf16 v[38:41], v[150:153], v[206:209], v[38:41]
	v_mfma_f32_16x16x32_bf16 v[34:37], v[172:175], v[206:209], v[34:37]
	v_mfma_f32_16x16x32_bf16 v[22:25], v[150:153], v[232:235], v[22:25]
	v_mfma_f32_16x16x32_bf16 v[18:21], v[172:175], v[232:235], v[18:21]
	v_mfma_f32_16x16x32_bf16 v[6:9], v[150:153], v[240:243], v[6:9]
	v_mfma_f32_16x16x32_bf16 v[2:5], v[172:175], v[240:243], v[2:5]
	s_setprio 0
	s_barrier
	s_add_i32 s50, 0, 0x18000
	s_add_i32 s51, 0, 0x1c000
	v_add_u32_e32 v142, s50, v186
	v_add_u32_e32 v172, s51, v186
	ds_read_b128 v[130:133], v142
	ds_read_b128 v[134:137], v142 offset:1024
	ds_read_b128 v[138:141], v142 offset:2048
	ds_read_b128 v[142:145], v142 offset:3072
	ds_read_b128 v[146:149], v172
	ds_read_b128 v[150:153], v172 offset:1024
	ds_read_b128 v[168:171], v172 offset:2048
	ds_read_b128 v[172:175], v172 offset:3072
	s_add_u32 s18, s24, 0xb0000
	s_addc_u32 s19, s25, 0
	s_mov_b32 m0, s35
	ds_read_b128 v[176:179], v200 offset:32768
	ds_read_b128 v[180:183], v200 offset:33792
	ds_read_b128 v[202:205], v200 offset:34816
	ds_read_b128 v[206:209], v200 offset:35840
	ds_read_b128 v[210:213], v200 offset:36864
	ds_read_b128 v[232:235], v200 offset:37888
	ds_read_b128 v[236:239], v200 offset:38912
	ds_read_b128 v[240:243], v200 offset:39936
	global_load_lds_dwordx4 v154, s[18:19]
	s_mov_b32 m0, s36
	s_nop 0
	global_load_lds_dwordx4 v158, s[18:19]
	s_waitcnt vmcnt(8)
	s_waitcnt lgkmcnt(0)
	s_setprio 1
	s_barrier
	v_mfma_f32_16x16x32_bf16 v[126:129], v[130:133], v[176:179], v[126:129]
	v_mfma_f32_16x16x32_bf16 v[122:125], v[138:141], v[176:179], v[122:125]
	v_mfma_f32_16x16x32_bf16 v[110:113], v[130:133], v[202:205], v[110:113]
	v_mfma_f32_16x16x32_bf16 v[106:109], v[138:141], v[202:205], v[106:109]
	v_mfma_f32_16x16x32_bf16 v[94:97], v[130:133], v[210:213], v[94:97]
	v_mfma_f32_16x16x32_bf16 v[90:93], v[138:141], v[210:213], v[90:93]
	v_mfma_f32_16x16x32_bf16 v[78:81], v[130:133], v[236:239], v[78:81]
	v_mfma_f32_16x16x32_bf16 v[74:77], v[138:141], v[236:239], v[74:77]
	v_mfma_f32_16x16x32_bf16 v[126:129], v[134:137], v[180:183], v[126:129]
	v_mfma_f32_16x16x32_bf16 v[122:125], v[142:145], v[180:183], v[122:125]
	v_mfma_f32_16x16x32_bf16 v[110:113], v[134:137], v[206:209], v[110:113]
	v_mfma_f32_16x16x32_bf16 v[106:109], v[142:145], v[206:209], v[106:109]
	v_mfma_f32_16x16x32_bf16 v[94:97], v[134:137], v[232:235], v[94:97]
	v_mfma_f32_16x16x32_bf16 v[90:93], v[142:145], v[232:235], v[90:93]
	v_mfma_f32_16x16x32_bf16 v[78:81], v[134:137], v[240:243], v[78:81]
	v_mfma_f32_16x16x32_bf16 v[74:77], v[142:145], v[240:243], v[74:77]
	s_setprio 0
	s_setprio 1
	v_mfma_f32_16x16x32_bf16 v[118:121], v[146:149], v[176:179], v[118:121]
	v_mfma_f32_16x16x32_bf16 v[114:117], v[168:171], v[176:179], v[114:117]
	v_mfma_f32_16x16x32_bf16 v[102:105], v[146:149], v[202:205], v[102:105]
	v_mfma_f32_16x16x32_bf16 v[98:101], v[168:171], v[202:205], v[98:101]
	v_mfma_f32_16x16x32_bf16 v[86:89], v[146:149], v[210:213], v[86:89]
	v_mfma_f32_16x16x32_bf16 v[82:85], v[168:171], v[210:213], v[82:85]
	v_mfma_f32_16x16x32_bf16 v[70:73], v[146:149], v[236:239], v[70:73]
	v_mfma_f32_16x16x32_bf16 v[66:69], v[168:171], v[236:239], v[66:69]
	v_mfma_f32_16x16x32_bf16 v[118:121], v[150:153], v[180:183], v[118:121]
	v_mfma_f32_16x16x32_bf16 v[114:117], v[172:175], v[180:183], v[114:117]
	v_mfma_f32_16x16x32_bf16 v[102:105], v[150:153], v[206:209], v[102:105]
	v_mfma_f32_16x16x32_bf16 v[98:101], v[172:175], v[206:209], v[98:101]
	v_mfma_f32_16x16x32_bf16 v[86:89], v[150:153], v[232:235], v[86:89]
	v_mfma_f32_16x16x32_bf16 v[82:85], v[172:175], v[232:235], v[82:85]
	v_mfma_f32_16x16x32_bf16 v[70:73], v[150:153], v[240:243], v[70:73]
	v_mfma_f32_16x16x32_bf16 v[66:69], v[172:175], v[240:243], v[66:69]
	s_setprio 0
	s_barrier
; #define PG8_STAGE(bufoff, gbase, voff) do { _Pragma("unroll") for (int _i = 0; _i < 2; ++_i) \
;         __builtin_amdgcn_global_load_lds((const unsigned*)((const char*)(gbase) + (voff)[_i]), (PG8_LAS unsigned*)(lds + (bufoff) + ldsw + _i * 8192), 16, 0, 0); } while (0)
; #define PG8_LDA(dst, b, h) do { _Pragma("unroll") for (int m = 0; m < 4; ++m) _Pragma("unroll") for (int k = 0; k < 2; ++k) dst[m][k] = *(const PG8_LAS bf16x8*)(lds + PG8_SA(b, h) + aoff + m * 2048 + k * 1024); } while (0)
; #define PG8_LDB(dst, b, h) do { _Pragma("unroll") for (int n = 0; n < 2; ++n) _Pragma("unroll") for (int k = 0; k < 2; ++k) dst[n][k] = *(const PG8_LAS bf16x8*)(lds + PG8_SB(b, h) + boff + n * 2048 + k * 1024); } while (0)
; #define PG8_MMA(ai, bj, At, Bt) do { __builtin_amdgcn_s_setprio(1); _Pragma("unroll") for (int m = 0; m < 4; ++m) _Pragma("unroll") for (int n = 0; n < 2; ++n) _Pragma("unroll") for (int k = 0; k < 2; ++k) \
;         acc[ai][bj][m][n] = __builtin_amdgcn_mfma_f32_16x16x32_bf16(Bt[n][k], At[m][k], acc[ai][bj][m][n], 0, 0, 0); __builtin_amdgcn_s_setprio(0); } while (0)
; template <class Epi, class Sched, bool ALIGN_EPI = false, bool SP2 = false>
; __device__ __forceinline__ void gemm_phase(PG8_LAS unsigned char* lds, const Gemm g, const Sched& S, const Epi& E) {
;     ...
;         for (int t = 0; t < nt; t += 2) {
;     ...
;             PG8_LDB(B0, 0, 0); PG8_LDB(B1, 0, 1); PG8_SCHED; PG8_LDA(At, 0, 0); PG8_STAGE(PG8_SA(1, 1), a1 + hstepA, voffA);
;             PG8_WAIT_V(8); PG8_WAIT_L(0); PG8_BAR; PG8_MMA(0, 0, At, B0); PG8_MMA(0, 1, At, B1); PG8_BAR; PG8_SCHED;
;             PG8_LDA(At, 0, 1); PG8_STAGE(PG8_SB(0, 0), b2, voffB); PG8_STAGE(PG8_SB(0, 1), b2 + hstepB, voffB); PG8_STAGE(PG8_SA(0, 0), a2, voffA);
;             PG8_WAIT_V(8); PG8_WAIT_L(0); PG8_BAR; PG8_MMA(1, 0, At, B0); PG8_MMA(1, 1, At, B1); PG8_BAR; PG8_SCHED;
;             PG8_LDB(B0, 1, 0); PG8_LDB(B1, 1, 1); PG8_SCHED; PG8_LDA(At, 1, 0); PG8_STAGE(PG8_SA(0, 1), a2 + hstepA, voffA);
;             PG8_WAIT_V(8); PG8_WAIT_L(0); PG8_BAR; PG8_MMA(0, 0, At, B0); PG8_MMA(0, 1, At, B1); PG8_BAR; PG8_SCHED;
;             PG8_LDA(At, 1, 1); PG8_STAGE(PG8_SB(1, 0), b3, voffB); PG8_STAGE(PG8_SB(1, 1), b3 + hstepB, voffB); PG8_STAGE(PG8_SA(1, 0), a3, voffA);
;             PG8_WAIT_V(8); PG8_WAIT_L(0); PG8_BAR; PG8_MMA(1, 0, At, B0); PG8_MMA(1, 1, At, B1); PG8_BAR; PG8_SCHED;
	s_add_i32 s18, s50, s30
	s_mov_b32 m0, s18
	ds_read_b128 v[176:179], v200 offset:49152
	ds_read_b128 v[180:183], v200 offset:50176
	ds_read_b128 v[202:205], v200 offset:51200
	ds_read_b128 v[206:209], v200 offset:52224
	ds_read_b128 v[210:213], v200 offset:53248
	ds_read_b128 v[232:235], v200 offset:54272
	ds_read_b128 v[236:239], v200 offset:55296
	ds_read_b128 v[240:243], v200 offset:56320
	global_load_lds_dwordx4 v156, s[60:61]
	s_add_i32 m0, s18, 0x2000
	s_add_u32 s18, s22, 0xb0080
	s_addc_u32 s19, s23, 0
	s_add_i32 s22, s51, s30
	global_load_lds_dwordx4 v160, s[60:61]
	s_mov_b32 m0, s22
	s_nop 0
	global_load_lds_dwordx4 v156, s[18:19]
	s_add_i32 m0, s22, 0x2000
	s_nop 0
	global_load_lds_dwordx4 v160, s[18:19]
	s_mov_b32 m0, s38
	s_nop 0
	global_load_lds_dwordx4 v154, s[62:63]
	s_mov_b32 m0, s39
	s_nop 0
	global_load_lds_dwordx4 v158, s[62:63]
	s_waitcnt vmcnt(8)
	s_waitcnt lgkmcnt(0)
	s_setprio 1
	s_barrier
	v_mfma_f32_16x16x32_bf16 v[62:65], v[130:133], v[176:179], v[62:65]
	v_mfma_f32_16x16x32_bf16 v[58:61], v[138:141], v[176:179], v[58:61]
	v_mfma_f32_16x16x32_bf16 v[46:49], v[130:133], v[202:205], v[46:49]
	v_mfma_f32_16x16x32_bf16 v[42:45], v[138:141], v[202:205], v[42:45]
	v_mfma_f32_16x16x32_bf16 v[30:33], v[130:133], v[210:213], v[30:33]
	v_mfma_f32_16x16x32_bf16 v[26:29], v[138:141], v[210:213], v[26:29]
	v_mfma_f32_16x16x32_bf16 v[14:17], v[130:133], v[236:239], v[14:17]
	v_mfma_f32_16x16x32_bf16 v[10:13], v[138:141], v[236:239], v[10:13]
	v_mfma_f32_16x16x32_bf16 v[62:65], v[134:137], v[180:183], v[62:65]
	v_mfma_f32_16x16x32_bf16 v[58:61], v[142:145], v[180:183], v[58:61]
	v_mfma_f32_16x16x32_bf16 v[46:49], v[134:137], v[206:209], v[46:49]
	v_mfma_f32_16x16x32_bf16 v[42:45], v[142:145], v[206:209], v[42:45]
	v_mfma_f32_16x16x32_bf16 v[30:33], v[134:137], v[232:235], v[30:33]
	v_mfma_f32_16x16x32_bf16 v[26:29], v[142:145], v[232:235], v[26:29]
	v_mfma_f32_16x16x32_bf16 v[14:17], v[134:137], v[240:243], v[14:17]
	v_mfma_f32_16x16x32_bf16 v[10:13], v[142:145], v[240:243], v[10:13]
	s_setprio 0
	s_setprio 1
	v_mfma_f32_16x16x32_bf16 v[54:57], v[146:149], v[176:179], v[54:57]
	v_mfma_f32_16x16x32_bf16 v[50:53], v[168:171], v[176:179], v[50:53]
	v_mfma_f32_16x16x32_bf16 v[38:41], v[146:149], v[202:205], v[38:41]
	v_mfma_f32_16x16x32_bf16 v[34:37], v[168:171], v[202:205], v[34:37]
	v_mfma_f32_16x16x32_bf16 v[22:25], v[146:149], v[210:213], v[22:25]
	v_mfma_f32_16x16x32_bf16 v[18:21], v[168:171], v[210:213], v[18:21]
	v_mfma_f32_16x16x32_bf16 v[6:9], v[146:149], v[236:239], v[6:9]
	v_mfma_f32_16x16x32_bf16 v[2:5], v[168:171], v[236:239], v[2:5]
	v_mfma_f32_16x16x32_bf16 v[54:57], v[150:153], v[180:183], v[54:57]
	v_mfma_f32_16x16x32_bf16 v[50:53], v[172:175], v[180:183], v[50:53]
	v_mfma_f32_16x16x32_bf16 v[38:41], v[150:153], v[206:209], v[38:41]
	v_mfma_f32_16x16x32_bf16 v[34:37], v[172:175], v[206:209], v[34:37]
	v_mfma_f32_16x16x32_bf16 v[22:25], v[150:153], v[232:235], v[22:25]
	v_mfma_f32_16x16x32_bf16 v[18:21], v[172:175], v[232:235], v[18:21]
	v_mfma_f32_16x16x32_bf16 v[6:9], v[150:153], v[240:243], v[6:9]
	v_mfma_f32_16x16x32_bf16 v[2:5], v[172:175], v[240:243], v[2:5]
	s_setprio 0
	s_barrier
	s_add_i32 s49, s49, 2
	s_add_u32 s47, s47, 0x100
	s_addc_u32 s48, s48, 0
	s_cmp_gt_u32 s49, 41
	s_mov_b64 s[18:19], s[20:21]
	s_cbranch_scc0 .LBB0_1438
	s_and_b64 vcc, exec, s[14:15]
	s_cbranch_vccz .LBB0_1441
	s_barrier
